# speedup vs baseline: 1.0349x; 1.0036x over previous
.LBB0_108:
	s_lshl_b32 s24, s24, 5
	v_and_b32_e32 v19, 15, v17
	s_and_b32 s24, s24, 0x60
	v_lshlrev_b32_e32 v20, 7, v19
	v_or_b32_e32 v19, s24, v19
	s_add_i32 s24, s1, 0x18000
	s_mov_b64 s[28:29], 0x80
	v_lshl_or_b32 v20, s25, 13, v20
	v_lshl_add_u64 v[6:7], v[6:7], 0, s[28:29]
	s_mov_b32 m0, s24
	s_add_i32 s25, s1, 0x1a000
	s_waitcnt vmcnt(4)
	s_barrier
	global_load_lds_dwordx4 v[6:7], off
	v_lshl_add_u64 v[6:7], v[8:9], 0, s[28:29]
	s_mov_b32 m0, s25
	s_add_i32 s26, s1, 0x8000
	global_load_lds_dwordx4 v[6:7], off
	v_lshl_add_u64 v[6:7], v[12:13], 0, s[28:29]
	s_mov_b32 m0, s26
	s_add_i32 s27, s1, 0xa000
	global_load_lds_dwordx4 v[6:7], off
	v_lshl_add_u64 v[6:7], v[10:11], 0, s[28:29]
	s_mov_b32 m0, s27
	v_lshl_add_u64 v[4:5], v[4:5], 0, s[50:51]
	s_add_i32 s28, s1, 0x1c000
	global_load_lds_dwordx4 v[6:7], off
	v_lshl_add_u64 v[6:7], v[0:1], 1, v[4:5]
	s_mov_b32 m0, s28
	s_add_i32 s29, s1, 0x1e000
	global_load_lds_dwordx4 v[6:7], off
	v_lshl_add_u64 v[2:3], v[2:3], 1, v[4:5]
	s_mov_b32 m0, s29
	v_and_b32_e32 v21, 3, v18
	global_load_lds_dwordx4 v[2:3], off
	v_bfe_u32 v17, v17, 1, 3
	v_add_u32_e32 v0, v16, v14
	v_bitop3_b32 v18, v18, v17, 3 bitop3:0x6c
	v_bitop3_b32 v17, v21, v17, 4 bitop3:0x36
	s_waitcnt vmcnt(6)
	v_lshlrev_b64 v[2:3], 1, v[0:1]
	v_add_u32_e32 v0, v15, v14
	v_lshlrev_b32_e32 v18, 4, v18
	v_lshlrev_b32_e32 v17, 4, v17
	v_lshlrev_b32_e32 v19, 7, v19
	v_lshl_add_u64 v[140:141], s[4:5], 0, v[2:3]
	v_lshlrev_b64 v[4:5], 1, v[0:1]
	v_lshl_add_u64 v[144:145], v[2:3], 0, s[90:91]
	v_mov_b32_e32 v2, 0
	v_or_b32_e32 v148, v18, v20
	v_or_b32_e32 v150, v19, v18
	v_or_b32_e32 v149, v17, v20
	v_or_b32_e32 v151, v19, v17
	v_lshl_add_u64 v[142:143], s[4:5], 0, v[4:5]
	v_lshl_add_u64 v[146:147], v[4:5], 0, s[90:91]
	s_mov_b32 s4, -2
	v_mov_b32_e32 v3, v2
	v_mov_b32_e32 v4, v2
	v_mov_b32_e32 v5, v2
	v_mov_b32_e32 v6, v2
	v_mov_b32_e32 v7, v2
	v_mov_b32_e32 v8, v2
	v_mov_b32_e32 v9, v2
	v_mov_b32_e32 v10, v2
	v_mov_b32_e32 v11, v2
	v_mov_b32_e32 v12, v2
	v_mov_b32_e32 v13, v2
	v_mov_b32_e32 v14, v2
	v_mov_b32_e32 v15, v2
	v_mov_b32_e32 v16, v2
	v_mov_b32_e32 v17, v2
	v_mov_b32_e32 v18, v2
	v_mov_b32_e32 v19, v2
	v_mov_b32_e32 v20, v2
	v_mov_b32_e32 v21, v2
	v_mov_b32_e32 v22, v2
	v_mov_b32_e32 v23, v2
	v_mov_b32_e32 v24, v2
	v_mov_b32_e32 v25, v2
	v_mov_b32_e32 v26, v2
	v_mov_b32_e32 v27, v2
	v_mov_b32_e32 v28, v2
	v_mov_b32_e32 v29, v2
	v_mov_b32_e32 v30, v2
	v_mov_b32_e32 v31, v2
	v_mov_b32_e32 v32, v2
	v_mov_b32_e32 v33, v2
	v_mov_b32_e32 v34, v2
	v_mov_b32_e32 v35, v2
	v_mov_b32_e32 v36, v2
	v_mov_b32_e32 v37, v2
	v_mov_b32_e32 v38, v2
	v_mov_b32_e32 v39, v2
	v_mov_b32_e32 v40, v2
	v_mov_b32_e32 v41, v2
	v_mov_b32_e32 v42, v2
	v_mov_b32_e32 v43, v2
	v_mov_b32_e32 v44, v2
	v_mov_b32_e32 v45, v2
	v_mov_b32_e32 v46, v2
	v_mov_b32_e32 v47, v2
	v_mov_b32_e32 v48, v2
	v_mov_b32_e32 v49, v2
	v_mov_b32_e32 v50, v2
	v_mov_b32_e32 v51, v2
	v_mov_b32_e32 v52, v2
	v_mov_b32_e32 v53, v2
	v_mov_b32_e32 v54, v2
	v_mov_b32_e32 v55, v2
	v_mov_b32_e32 v56, v2
	v_mov_b32_e32 v57, v2
	v_mov_b32_e32 v58, v2
	v_mov_b32_e32 v59, v2
	v_mov_b32_e32 v60, v2
	v_mov_b32_e32 v61, v2
	v_mov_b32_e32 v62, v2
	v_mov_b32_e32 v63, v2
	v_mov_b32_e32 v64, v2
	v_mov_b32_e32 v65, v2
	v_mov_b32_e32 v66, v2
	v_mov_b32_e32 v67, v2
	v_mov_b32_e32 v68, v2
	v_mov_b32_e32 v69, v2
	v_mov_b32_e32 v70, v2
	v_mov_b32_e32 v71, v2
	v_mov_b32_e32 v72, v2
	v_mov_b32_e32 v73, v2
	v_mov_b32_e32 v74, v2
	v_mov_b32_e32 v75, v2
	v_mov_b32_e32 v76, v2
	v_mov_b32_e32 v77, v2
	v_mov_b32_e32 v78, v2
	v_mov_b32_e32 v79, v2
	v_mov_b32_e32 v80, v2
	v_mov_b32_e32 v81, v2
	v_mov_b32_e32 v82, v2
	v_mov_b32_e32 v83, v2
	v_mov_b32_e32 v84, v2
	v_mov_b32_e32 v85, v2
	v_mov_b32_e32 v86, v2
	v_mov_b32_e32 v87, v2
	v_mov_b32_e32 v88, v2
	v_mov_b32_e32 v89, v2
	v_mov_b32_e32 v90, v2
	v_mov_b32_e32 v91, v2
	v_mov_b32_e32 v92, v2
	v_mov_b32_e32 v93, v2
	v_mov_b32_e32 v94, v2
	v_mov_b32_e32 v95, v2
	v_mov_b32_e32 v96, v2
	v_mov_b32_e32 v97, v2
	v_mov_b32_e32 v98, v2
	v_mov_b32_e32 v99, v2
	v_mov_b32_e32 v100, v2
	v_mov_b32_e32 v101, v2
	v_mov_b32_e32 v102, v2
	v_mov_b32_e32 v103, v2
	v_mov_b32_e32 v104, v2
	v_mov_b32_e32 v105, v2
	v_mov_b32_e32 v106, v2
	v_mov_b32_e32 v107, v2
	v_mov_b32_e32 v108, v2
	v_mov_b32_e32 v109, v2
	v_mov_b32_e32 v110, v2
	v_mov_b32_e32 v111, v2
	v_mov_b32_e32 v112, v2
	v_mov_b32_e32 v113, v2
	v_mov_b32_e32 v114, v2
	v_mov_b32_e32 v115, v2
	v_mov_b32_e32 v116, v2
	v_mov_b32_e32 v117, v2
	v_mov_b32_e32 v118, v2
	v_mov_b32_e32 v119, v2
	v_mov_b32_e32 v120, v2
	v_mov_b32_e32 v121, v2
	v_mov_b32_e32 v122, v2
	v_mov_b32_e32 v123, v2
	v_mov_b32_e32 v124, v2
	v_mov_b32_e32 v125, v2
	v_mov_b32_e32 v126, v2
	v_mov_b32_e32 v127, v2
	v_mov_b32_e32 v128, v2
	v_mov_b32_e32 v129, v2
	s_mov_b64 s[34:35], 0x82d4900
	s_mov_b64 s[36:37], 0x8254980
	s_mov_b64 s[38:39], 0x82d4980
	s_waitcnt lgkmcnt(0)
	s_sub_u32 s100, s100, 0x40000000
	s_subb_u32 s101, s101, 0
	s_mov_b64 vcc, s[100:101]
	v_lshl_add_u64 v[210:211], v[132:133], 0, v[142:143]
	v_subrev_u32_e32 v210, vcc_lo, v210
	v_lshl_add_u64 v[214:215], v[132:133], 0, v[140:141]
	v_subrev_u32_e32 v214, vcc_lo, v214
	v_lshl_add_u64 v[242:243], v[132:133], 0, v[146:147]
	v_subrev_u32_e32 v242, vcc_lo, v242
	v_lshl_add_u64 v[244:245], v[132:133], 0, v[144:145]
	v_subrev_u32_e32 v244, vcc_lo, v244
	v_add_u32_e32 v211, 0x10000, v150
	v_add_u32_e32 v215, 0x10000, v151
	v_add_u32_e32 v0, s50, v210
	v_add_u32_e32 v152, s54, v210
	v_add_u32_e32 v153, s58, v210
	v_add_u32_e32 v210, s62, v210
	v_add_u32_e32 v154, s50, v214
	v_add_u32_e32 v155, s54, v214
	v_add_u32_e32 v156, s58, v214
	v_add_u32_e32 v214, s62, v214
	v_add_u32_e32 v157, s70, v242
	v_add_u32_e32 v158, s34, v242
	v_add_u32_e32 v159, s36, v242
	v_add_u32_e32 v242, s38, v242
	v_add_u32_e32 v243, s70, v244
	v_add_u32_e32 v245, s34, v244
	v_add_u32_e32 v246, s36, v244
	v_add_u32_e32 v244, s38, v244
	s_add_i32 s30, s1, 0xc000
	s_add_i32 s5, s1, 0xe000
	s_barrier
.LBB0_109:
	ds_read_b128 v[160:163], v211
	ds_read_b128 v[164:167], v215
	ds_read_b128 v[168:171], v211 offset:2048
	ds_read_b128 v[172:175], v215 offset:2048
	ds_read_b128 v[176:179], v148
	ds_read_b128 v[180:183], v148 offset:2048
	ds_read_b128 v[184:187], v149
	ds_read_b128 v[188:191], v149 offset:2048
	ds_read_b128 v[192:195], v148 offset:4096
	ds_read_b128 v[196:199], v148 offset:6144
	s_mov_b32 m0, s30
	ds_read_b128 v[200:203], v149 offset:4096
	global_load_lds_dwordx4 v0, vcc
	s_mov_b32 m0, s5
	ds_read_b128 v[206:209], v149 offset:6144
	global_load_lds_dwordx4 v154, vcc
	s_waitcnt vmcnt(10) lgkmcnt(8)
	s_barrier
	s_waitcnt lgkmcnt(0)
	v_mfma_f32_16x16x32_bf16 v[126:129], v[160:163], v[176:179], v[126:129]
	v_mfma_f32_16x16x32_bf16 v[122:125], v[168:171], v[176:179], v[122:125]
	v_mfma_f32_16x16x32_bf16 v[118:121], v[160:163], v[180:183], v[118:121]
	v_mfma_f32_16x16x32_bf16 v[114:117], v[168:171], v[180:183], v[114:117]
	v_mfma_f32_16x16x32_bf16 v[110:113], v[160:163], v[192:195], v[110:113]
	v_mfma_f32_16x16x32_bf16 v[106:109], v[168:171], v[192:195], v[106:109]
	v_mfma_f32_16x16x32_bf16 v[102:105], v[160:163], v[196:199], v[102:105]
	v_mfma_f32_16x16x32_bf16 v[98:101], v[168:171], v[196:199], v[98:101]
	v_mfma_f32_16x16x32_bf16 v[126:129], v[164:167], v[184:187], v[126:129]
	v_mfma_f32_16x16x32_bf16 v[122:125], v[172:175], v[184:187], v[122:125]
	v_mfma_f32_16x16x32_bf16 v[118:121], v[164:167], v[188:191], v[118:121]
	v_mfma_f32_16x16x32_bf16 v[114:117], v[172:175], v[188:191], v[114:117]
	v_mfma_f32_16x16x32_bf16 v[110:113], v[164:167], v[200:203], v[110:113]
	v_mfma_f32_16x16x32_bf16 v[106:109], v[172:175], v[200:203], v[106:109]
	v_mfma_f32_16x16x32_bf16 v[102:105], v[164:167], v[206:209], v[102:105]
	v_mfma_f32_16x16x32_bf16 v[98:101], v[172:175], v[206:209], v[98:101]
	s_barrier
	ds_read_b128 v[218:221], v211 offset:16384
	ds_read_b128 v[222:225], v215 offset:16384
	s_mov_b32 m0, s2
	ds_read_b128 v[226:229], v211 offset:18432
	global_load_lds_dwordx4 v157, vcc
	s_mov_b32 m0, s3
	ds_read_b128 v[230:233], v215 offset:18432
	global_load_lds_dwordx4 v243, vcc
	s_waitcnt vmcnt(10) lgkmcnt(0)
	s_barrier
	v_mfma_f32_16x16x32_bf16 v[94:97], v[218:221], v[176:179], v[94:97]
	v_mfma_f32_16x16x32_bf16 v[90:93], v[226:229], v[176:179], v[90:93]
	v_mfma_f32_16x16x32_bf16 v[86:89], v[218:221], v[180:183], v[86:89]
	v_mfma_f32_16x16x32_bf16 v[82:85], v[226:229], v[180:183], v[82:85]
	v_mfma_f32_16x16x32_bf16 v[78:81], v[218:221], v[192:195], v[78:81]
	v_mfma_f32_16x16x32_bf16 v[74:77], v[226:229], v[192:195], v[74:77]
	v_mfma_f32_16x16x32_bf16 v[70:73], v[218:221], v[196:199], v[70:73]
	v_mfma_f32_16x16x32_bf16 v[66:69], v[226:229], v[196:199], v[66:69]
	v_mfma_f32_16x16x32_bf16 v[94:97], v[222:225], v[184:187], v[94:97]
	v_mfma_f32_16x16x32_bf16 v[90:93], v[230:233], v[184:187], v[90:93]
	v_mfma_f32_16x16x32_bf16 v[86:89], v[222:225], v[188:191], v[86:89]
	v_mfma_f32_16x16x32_bf16 v[82:85], v[230:233], v[188:191], v[82:85]
	v_mfma_f32_16x16x32_bf16 v[78:81], v[222:225], v[200:203], v[78:81]
	v_mfma_f32_16x16x32_bf16 v[74:77], v[230:233], v[200:203], v[74:77]
	v_mfma_f32_16x16x32_bf16 v[70:73], v[222:225], v[206:209], v[70:73]
	v_mfma_f32_16x16x32_bf16 v[66:69], v[230:233], v[206:209], v[66:69]
	s_barrier
	ds_read_b128 v[176:179], v148 offset:16384
	ds_read_b128 v[180:183], v148 offset:18432
	ds_read_b128 v[184:187], v149 offset:16384
	ds_read_b128 v[188:191], v149 offset:18432
	s_mov_b32 m0, s1
	ds_read_b128 v[192:195], v148 offset:20480
	global_load_lds_dwordx4 v152, vcc
	s_mov_b32 m0, s9
	ds_read_b128 v[196:199], v148 offset:22528
	global_load_lds_dwordx4 v155, vcc
	s_mov_b32 m0, s11
	ds_read_b128 v[200:203], v149 offset:20480
	global_load_lds_dwordx4 v158, vcc
	s_mov_b32 m0, s12
	ds_read_b128 v[206:209], v149 offset:22528
	global_load_lds_dwordx4 v245, vcc
	s_waitcnt vmcnt(10) lgkmcnt(0)
	s_barrier
	v_mfma_f32_16x16x32_bf16 v[62:65], v[160:163], v[176:179], v[62:65]
	v_mfma_f32_16x16x32_bf16 v[58:61], v[168:171], v[176:179], v[58:61]
	v_mfma_f32_16x16x32_bf16 v[54:57], v[160:163], v[180:183], v[54:57]
	v_mfma_f32_16x16x32_bf16 v[50:53], v[168:171], v[180:183], v[50:53]
	v_mfma_f32_16x16x32_bf16 v[46:49], v[160:163], v[192:195], v[46:49]
	v_mfma_f32_16x16x32_bf16 v[42:45], v[168:171], v[192:195], v[42:45]
	v_mfma_f32_16x16x32_bf16 v[38:41], v[160:163], v[196:199], v[38:41]
	v_mfma_f32_16x16x32_bf16 v[34:37], v[168:171], v[196:199], v[34:37]
	v_mfma_f32_16x16x32_bf16 v[62:65], v[164:167], v[184:187], v[62:65]
	v_mfma_f32_16x16x32_bf16 v[58:61], v[172:175], v[184:187], v[58:61]
	v_mfma_f32_16x16x32_bf16 v[54:57], v[164:167], v[188:191], v[54:57]
	v_mfma_f32_16x16x32_bf16 v[50:53], v[172:175], v[188:191], v[50:53]
	v_mfma_f32_16x16x32_bf16 v[46:49], v[164:167], v[200:203], v[46:49]
	v_mfma_f32_16x16x32_bf16 v[42:45], v[172:175], v[200:203], v[42:45]
	v_mfma_f32_16x16x32_bf16 v[38:41], v[164:167], v[206:209], v[38:41]
	v_mfma_f32_16x16x32_bf16 v[34:37], v[172:175], v[206:209], v[34:37]
	v_mfma_f32_16x16x32_bf16 v[30:33], v[218:221], v[176:179], v[30:33]
	v_mfma_f32_16x16x32_bf16 v[26:29], v[226:229], v[176:179], v[26:29]
	v_mfma_f32_16x16x32_bf16 v[22:25], v[218:221], v[180:183], v[22:25]
	v_mfma_f32_16x16x32_bf16 v[18:21], v[226:229], v[180:183], v[18:21]
	v_mfma_f32_16x16x32_bf16 v[14:17], v[218:221], v[192:195], v[14:17]
	v_mfma_f32_16x16x32_bf16 v[10:13], v[226:229], v[192:195], v[10:13]
	v_mfma_f32_16x16x32_bf16 v[6:9], v[218:221], v[196:199], v[6:9]
	v_mfma_f32_16x16x32_bf16 v[2:5], v[226:229], v[196:199], v[2:5]
	v_mfma_f32_16x16x32_bf16 v[30:33], v[222:225], v[184:187], v[30:33]
	v_mfma_f32_16x16x32_bf16 v[26:29], v[230:233], v[184:187], v[26:29]
	v_mfma_f32_16x16x32_bf16 v[22:25], v[222:225], v[188:191], v[22:25]
	v_mfma_f32_16x16x32_bf16 v[18:21], v[230:233], v[188:191], v[18:21]
	v_mfma_f32_16x16x32_bf16 v[14:17], v[222:225], v[200:203], v[14:17]
	v_mfma_f32_16x16x32_bf16 v[10:13], v[230:233], v[200:203], v[10:13]
	v_mfma_f32_16x16x32_bf16 v[6:9], v[222:225], v[206:209], v[6:9]
	v_mfma_f32_16x16x32_bf16 v[2:5], v[230:233], v[206:209], v[2:5]
	s_barrier
	ds_read_b128 v[168:171], v211 offset:32768
	ds_read_b128 v[172:175], v215 offset:32768
	ds_read_b128 v[176:179], v211 offset:34816
	ds_read_b128 v[180:183], v215 offset:34816
	ds_read_b128 v[184:187], v148 offset:32768
	ds_read_b128 v[188:191], v148 offset:34816
	ds_read_b128 v[192:195], v149 offset:32768
	ds_read_b128 v[196:199], v149 offset:34816
	ds_read_b128 v[200:203], v148 offset:36864
	ds_read_b128 v[206:209], v148 offset:38912
	s_mov_b32 m0, s13
	ds_read_b128 v[218:221], v149 offset:36864
	global_load_lds_dwordx4 v153, vcc
	s_mov_b32 m0, s23
	ds_read_b128 v[222:225], v149 offset:38912
	global_load_lds_dwordx4 v156, vcc
	s_waitcnt vmcnt(10) lgkmcnt(8)
	s_barrier
	s_waitcnt lgkmcnt(0)
	v_mfma_f32_16x16x32_bf16 v[126:129], v[168:171], v[184:187], v[126:129]
	v_mfma_f32_16x16x32_bf16 v[122:125], v[176:179], v[184:187], v[122:125]
	v_mfma_f32_16x16x32_bf16 v[118:121], v[168:171], v[188:191], v[118:121]
	v_mfma_f32_16x16x32_bf16 v[114:117], v[176:179], v[188:191], v[114:117]
	v_mfma_f32_16x16x32_bf16 v[110:113], v[168:171], v[200:203], v[110:113]
	v_mfma_f32_16x16x32_bf16 v[106:109], v[176:179], v[200:203], v[106:109]
	v_mfma_f32_16x16x32_bf16 v[102:105], v[168:171], v[206:209], v[102:105]
	v_mfma_f32_16x16x32_bf16 v[98:101], v[176:179], v[206:209], v[98:101]
	v_mfma_f32_16x16x32_bf16 v[126:129], v[172:175], v[192:195], v[126:129]
	v_mfma_f32_16x16x32_bf16 v[122:125], v[180:183], v[192:195], v[122:125]
	v_mfma_f32_16x16x32_bf16 v[118:121], v[172:175], v[196:199], v[118:121]
	v_mfma_f32_16x16x32_bf16 v[114:117], v[180:183], v[196:199], v[114:117]
	v_mfma_f32_16x16x32_bf16 v[110:113], v[172:175], v[218:221], v[110:113]
	v_mfma_f32_16x16x32_bf16 v[106:109], v[180:183], v[218:221], v[106:109]
	v_mfma_f32_16x16x32_bf16 v[102:105], v[172:175], v[222:225], v[102:105]
	v_mfma_f32_16x16x32_bf16 v[98:101], v[180:183], v[222:225], v[98:101]
	s_barrier
	ds_read_b128 v[226:229], v211 offset:49152
	ds_read_b128 v[230:233], v215 offset:49152
	s_mov_b32 m0, s24
	ds_read_b128 v[234:237], v211 offset:51200
	global_load_lds_dwordx4 v159, vcc
	s_mov_b32 m0, s25
	ds_read_b128 v[238:241], v215 offset:51200
	global_load_lds_dwordx4 v246, vcc
	s_waitcnt vmcnt(10) lgkmcnt(0)
	s_barrier
	v_mfma_f32_16x16x32_bf16 v[94:97], v[226:229], v[184:187], v[94:97]
	v_mfma_f32_16x16x32_bf16 v[90:93], v[234:237], v[184:187], v[90:93]
	v_mfma_f32_16x16x32_bf16 v[86:89], v[226:229], v[188:191], v[86:89]
	v_mfma_f32_16x16x32_bf16 v[82:85], v[234:237], v[188:191], v[82:85]
	v_mfma_f32_16x16x32_bf16 v[78:81], v[226:229], v[200:203], v[78:81]
	v_mfma_f32_16x16x32_bf16 v[74:77], v[234:237], v[200:203], v[74:77]
	v_mfma_f32_16x16x32_bf16 v[70:73], v[226:229], v[206:209], v[70:73]
	v_mfma_f32_16x16x32_bf16 v[66:69], v[234:237], v[206:209], v[66:69]
	v_mfma_f32_16x16x32_bf16 v[94:97], v[230:233], v[192:195], v[94:97]
	v_mfma_f32_16x16x32_bf16 v[90:93], v[238:241], v[192:195], v[90:93]
	v_mfma_f32_16x16x32_bf16 v[86:89], v[230:233], v[196:199], v[86:89]
	v_mfma_f32_16x16x32_bf16 v[82:85], v[238:241], v[196:199], v[82:85]
	v_mfma_f32_16x16x32_bf16 v[78:81], v[230:233], v[218:221], v[78:81]
	v_mfma_f32_16x16x32_bf16 v[74:77], v[238:241], v[218:221], v[74:77]
	v_mfma_f32_16x16x32_bf16 v[70:73], v[230:233], v[222:225], v[70:73]
	v_mfma_f32_16x16x32_bf16 v[66:69], v[238:241], v[222:225], v[66:69]
	s_barrier
	ds_read_b128 v[184:187], v148 offset:49152
	ds_read_b128 v[188:191], v148 offset:51200
	ds_read_b128 v[192:195], v149 offset:49152
	ds_read_b128 v[196:199], v149 offset:51200
	s_mov_b32 m0, s26
	ds_read_b128 v[200:203], v148 offset:53248
	global_load_lds_dwordx4 v210, vcc
	s_mov_b32 m0, s27
	ds_read_b128 v[206:209], v148 offset:55296
	global_load_lds_dwordx4 v214, vcc
	s_mov_b32 m0, s28
	ds_read_b128 v[218:221], v149 offset:53248
	global_load_lds_dwordx4 v242, vcc
	s_mov_b32 m0, s29
	ds_read_b128 v[222:225], v149 offset:55296
	global_load_lds_dwordx4 v244, vcc
	s_waitcnt vmcnt(10) lgkmcnt(0)
	s_barrier
	v_mfma_f32_16x16x32_bf16 v[62:65], v[168:171], v[184:187], v[62:65]
	v_mfma_f32_16x16x32_bf16 v[58:61], v[176:179], v[184:187], v[58:61]
	v_mfma_f32_16x16x32_bf16 v[54:57], v[168:171], v[188:191], v[54:57]
	v_mfma_f32_16x16x32_bf16 v[50:53], v[176:179], v[188:191], v[50:53]
	v_mfma_f32_16x16x32_bf16 v[46:49], v[168:171], v[200:203], v[46:49]
	v_mfma_f32_16x16x32_bf16 v[42:45], v[176:179], v[200:203], v[42:45]
	v_mfma_f32_16x16x32_bf16 v[38:41], v[168:171], v[206:209], v[38:41]
	v_mfma_f32_16x16x32_bf16 v[34:37], v[176:179], v[206:209], v[34:37]
	v_mfma_f32_16x16x32_bf16 v[62:65], v[172:175], v[192:195], v[62:65]
	v_mfma_f32_16x16x32_bf16 v[58:61], v[180:183], v[192:195], v[58:61]
	v_mfma_f32_16x16x32_bf16 v[54:57], v[172:175], v[196:199], v[54:57]
	v_mfma_f32_16x16x32_bf16 v[50:53], v[180:183], v[196:199], v[50:53]
	v_mfma_f32_16x16x32_bf16 v[46:49], v[172:175], v[218:221], v[46:49]
	v_mfma_f32_16x16x32_bf16 v[42:45], v[180:183], v[218:221], v[42:45]
	v_mfma_f32_16x16x32_bf16 v[38:41], v[172:175], v[222:225], v[38:41]
	v_mfma_f32_16x16x32_bf16 v[34:37], v[180:183], v[222:225], v[34:37]
	v_mfma_f32_16x16x32_bf16 v[30:33], v[226:229], v[184:187], v[30:33]
	v_mfma_f32_16x16x32_bf16 v[26:29], v[234:237], v[184:187], v[26:29]
	v_mfma_f32_16x16x32_bf16 v[22:25], v[226:229], v[188:191], v[22:25]
	v_mfma_f32_16x16x32_bf16 v[18:21], v[234:237], v[188:191], v[18:21]
	v_mfma_f32_16x16x32_bf16 v[14:17], v[226:229], v[200:203], v[14:17]
	v_mfma_f32_16x16x32_bf16 v[10:13], v[234:237], v[200:203], v[10:13]
	v_mfma_f32_16x16x32_bf16 v[6:9], v[226:229], v[206:209], v[6:9]
	v_mfma_f32_16x16x32_bf16 v[2:5], v[234:237], v[206:209], v[2:5]
	v_mfma_f32_16x16x32_bf16 v[30:33], v[230:233], v[192:195], v[30:33]
	v_mfma_f32_16x16x32_bf16 v[26:29], v[238:241], v[192:195], v[26:29]
	v_mfma_f32_16x16x32_bf16 v[22:25], v[230:233], v[196:199], v[22:25]
	v_mfma_f32_16x16x32_bf16 v[18:21], v[238:241], v[196:199], v[18:21]
	v_mfma_f32_16x16x32_bf16 v[14:17], v[230:233], v[218:221], v[14:17]
	v_mfma_f32_16x16x32_bf16 v[10:13], v[238:241], v[218:221], v[10:13]
	v_mfma_f32_16x16x32_bf16 v[6:9], v[230:233], v[222:225], v[6:9]
	v_mfma_f32_16x16x32_bf16 v[2:5], v[238:241], v[222:225], v[2:5]
	s_add_u32 vcc_lo, vcc_lo, s54
	s_addc_u32 vcc_hi, vcc_hi, s55
	s_add_i32 s4, s4, 2
	s_cmp_lt_u32 s4, 28
	v_lshl_add_u64 v[132:133], v[132:133], 0, s[54:55]
	s_barrier
	s_cbranch_scc1 .LBB0_109
	s_waitcnt vmcnt(6)
	v_or_b32_e32 v0, 0x10000, v150
	v_add_u32_e32 v153, 0x10800, v150
	v_or_b32_e32 v152, 0x10000, v151
	v_add_u32_e32 v154, 0x10800, v151
	v_or_b32_e32 v155, 0x14000, v150
	v_add_u32_e32 v157, 0x14800, v150
	v_or_b32_e32 v156, 0x14000, v151
	v_add_u32_e32 v158, 0x14800, v151
	v_or_b32_e32 v159, 0x18000, v150
	v_add_u32_e32 v161, 0x18800, v150
	v_or_b32_e32 v160, 0x18000, v151
	v_add_u32_e32 v162, 0x18800, v151
	v_or_b32_e32 v163, 0x1c000, v150
	v_add_u32_e32 v165, 0x1c800, v150
	v_or_b32_e32 v164, 0x1c000, v151
	v_add_u32_e32 v166, 0x1c800, v151
	s_mov_b64 s[2:3], 0xf80
	s_mov_b32 m0, s30
	v_lshl_add_u64 v[132:133], v[138:139], 0, s[2:3]
	ds_read_b128 v[140:143], v0
	ds_read_b128 v[144:147], v152
	ds_read_b128 v[150:153], v153
	ds_read_b128 v[168:171], v154
	ds_read_b128 v[172:175], v148
	ds_read_b128 v[176:179], v148 offset:2048
	ds_read_b128 v[180:183], v149
	ds_read_b128 v[184:187], v149 offset:2048
	ds_read_b128 v[188:191], v148 offset:4096
	ds_read_b128 v[192:195], v148 offset:6144
	ds_read_b128 v[196:199], v149 offset:4096
	ds_read_b128 v[200:203], v149 offset:6144
	global_load_lds_dwordx4 v[132:133], off
	v_lshl_add_u64 v[132:133], v[136:137], 0, s[2:3]
	s_mov_b32 m0, s5
	s_nop 0
	global_load_lds_dwordx4 v[132:133], off
	s_barrier
	s_waitcnt lgkmcnt(0)
	s_setprio 1
	s_waitcnt lgkmcnt(0)
	v_mfma_f32_16x16x32_bf16 v[126:129], v[140:143], v[172:175], v[126:129]
	v_mfma_f32_16x16x32_bf16 v[122:125], v[150:153], v[172:175], v[122:125]
	v_mfma_f32_16x16x32_bf16 v[118:121], v[140:143], v[176:179], v[118:121]
	v_mfma_f32_16x16x32_bf16 v[110:113], v[140:143], v[188:191], v[110:113]
	v_mfma_f32_16x16x32_bf16 v[106:109], v[150:153], v[188:191], v[106:109]
	v_mfma_f32_16x16x32_bf16 v[126:129], v[144:147], v[180:183], v[126:129]
	v_mfma_f32_16x16x32_bf16 v[122:125], v[168:171], v[180:183], v[122:125]
	v_mfma_f32_16x16x32_bf16 v[118:121], v[144:147], v[184:187], v[118:121]
	v_mfma_f32_16x16x32_bf16 v[114:117], v[150:153], v[176:179], v[114:117]
	v_mfma_f32_16x16x32_bf16 v[110:113], v[144:147], v[196:199], v[110:113]
	v_mfma_f32_16x16x32_bf16 v[106:109], v[168:171], v[196:199], v[106:109]
	v_mfma_f32_16x16x32_bf16 v[102:105], v[140:143], v[192:195], v[102:105]
	v_mfma_f32_16x16x32_bf16 v[98:101], v[150:153], v[192:195], v[98:101]
	v_mfma_f32_16x16x32_bf16 v[136:139], v[168:171], v[184:187], v[114:117]
	v_mfma_f32_16x16x32_bf16 v[206:209], v[144:147], v[200:203], v[102:105]
	v_mfma_f32_16x16x32_bf16 v[218:221], v[168:171], v[200:203], v[98:101]
	s_setprio 0
	s_barrier
	s_nop 2
	ds_read_b128 v[98:101], v155
	ds_read_b128 v[102:105], v156
	ds_read_b128 v[114:117], v157
	ds_read_b128 v[154:157], v158
	s_barrier
	s_waitcnt lgkmcnt(0)
	s_setprio 1
	s_waitcnt lgkmcnt(0)
	v_mfma_f32_16x16x32_bf16 v[94:97], v[98:101], v[172:175], v[94:97]
	v_mfma_f32_16x16x32_bf16 v[90:93], v[114:117], v[172:175], v[90:93]
	v_mfma_f32_16x16x32_bf16 v[78:81], v[98:101], v[188:191], v[78:81]
	v_mfma_f32_16x16x32_bf16 v[74:77], v[114:117], v[188:191], v[74:77]
	v_mfma_f32_16x16x32_bf16 v[94:97], v[102:105], v[180:183], v[94:97]
	v_mfma_f32_16x16x32_bf16 v[90:93], v[154:157], v[180:183], v[90:93]
	v_mfma_f32_16x16x32_bf16 v[86:89], v[98:101], v[176:179], v[86:89]
	v_mfma_f32_16x16x32_bf16 v[82:85], v[114:117], v[176:179], v[82:85]
	v_mfma_f32_16x16x32_bf16 v[78:81], v[102:105], v[196:199], v[78:81]
	v_mfma_f32_16x16x32_bf16 v[74:77], v[154:157], v[196:199], v[74:77]
	v_mfma_f32_16x16x32_bf16 v[70:73], v[98:101], v[192:195], v[70:73]
	v_mfma_f32_16x16x32_bf16 v[66:69], v[114:117], v[192:195], v[66:69]
	v_mfma_f32_16x16x32_bf16 v[172:175], v[102:105], v[184:187], v[86:89]
	v_mfma_f32_16x16x32_bf16 v[176:179], v[154:157], v[184:187], v[82:85]
	v_mfma_f32_16x16x32_bf16 v[180:183], v[102:105], v[200:203], v[70:73]
	v_mfma_f32_16x16x32_bf16 v[184:187], v[154:157], v[200:203], v[66:69]
	s_setprio 0
	s_barrier
	s_nop 1
	ds_read_b128 v[66:69], v148 offset:16384
	ds_read_b128 v[70:73], v148 offset:18432
	ds_read_b128 v[82:85], v149 offset:16384
	ds_read_b128 v[86:89], v149 offset:18432
	ds_read_b128 v[188:191], v148 offset:20480
	ds_read_b128 v[192:195], v148 offset:22528
	ds_read_b128 v[196:199], v149 offset:20480
	ds_read_b128 v[200:203], v149 offset:22528
	s_waitcnt vmcnt(4)
	s_barrier
	s_waitcnt lgkmcnt(0)
	s_setprio 1
	s_waitcnt lgkmcnt(0)
	v_mfma_f32_16x16x32_bf16 v[62:65], v[140:143], v[66:69], v[62:65]
	v_mfma_f32_16x16x32_bf16 v[58:61], v[150:153], v[66:69], v[58:61]
	v_mfma_f32_16x16x32_bf16 v[46:49], v[140:143], v[188:191], v[46:49]
	v_mfma_f32_16x16x32_bf16 v[42:45], v[150:153], v[188:191], v[42:45]
	v_mfma_f32_16x16x32_bf16 v[62:65], v[144:147], v[82:85], v[62:65]
	v_mfma_f32_16x16x32_bf16 v[58:61], v[168:171], v[82:85], v[58:61]
	v_mfma_f32_16x16x32_bf16 v[54:57], v[140:143], v[70:73], v[54:57]
	v_mfma_f32_16x16x32_bf16 v[50:53], v[150:153], v[70:73], v[50:53]
	v_mfma_f32_16x16x32_bf16 v[46:49], v[144:147], v[196:199], v[46:49]
	v_mfma_f32_16x16x32_bf16 v[42:45], v[168:171], v[196:199], v[42:45]
	v_mfma_f32_16x16x32_bf16 v[38:41], v[140:143], v[192:195], v[38:41]
	v_mfma_f32_16x16x32_bf16 v[34:37], v[150:153], v[192:195], v[34:37]
	v_mfma_f32_16x16x32_bf16 v[222:225], v[144:147], v[86:89], v[54:57]
	v_mfma_f32_16x16x32_bf16 v[226:229], v[168:171], v[86:89], v[50:53]
	v_mfma_f32_16x16x32_bf16 v[140:143], v[144:147], v[200:203], v[38:41]
	v_mfma_f32_16x16x32_bf16 v[144:147], v[168:171], v[200:203], v[34:37]
	s_setprio 0
	s_setprio 1
	v_mfma_f32_16x16x32_bf16 v[30:33], v[98:101], v[66:69], v[30:33]
	v_mfma_f32_16x16x32_bf16 v[26:29], v[114:117], v[66:69], v[26:29]
	v_mfma_f32_16x16x32_bf16 v[14:17], v[98:101], v[188:191], v[14:17]
	v_mfma_f32_16x16x32_bf16 v[10:13], v[114:117], v[188:191], v[10:13]
	v_mfma_f32_16x16x32_bf16 v[30:33], v[102:105], v[82:85], v[30:33]
	v_mfma_f32_16x16x32_bf16 v[26:29], v[154:157], v[82:85], v[26:29]
	v_mfma_f32_16x16x32_bf16 v[22:25], v[98:101], v[70:73], v[22:25]
	v_mfma_f32_16x16x32_bf16 v[18:21], v[114:117], v[70:73], v[18:21]
	v_mfma_f32_16x16x32_bf16 v[14:17], v[102:105], v[196:199], v[14:17]
	v_mfma_f32_16x16x32_bf16 v[10:13], v[154:157], v[196:199], v[10:13]
	v_mfma_f32_16x16x32_bf16 v[6:9], v[98:101], v[192:195], v[6:9]
	v_mfma_f32_16x16x32_bf16 v[2:5], v[114:117], v[192:195], v[2:5]
	v_mfma_f32_16x16x32_bf16 v[150:153], v[102:105], v[86:89], v[22:25]
	v_mfma_f32_16x16x32_bf16 v[168:171], v[154:157], v[86:89], v[18:21]
	v_mfma_f32_16x16x32_bf16 v[188:191], v[102:105], v[200:203], v[6:9]
	v_mfma_f32_16x16x32_bf16 v[154:157], v[154:157], v[200:203], v[2:5]
	s_setprio 0
	s_barrier
	s_nop 1
	ds_read_b128 v[2:5], v159
	ds_read_b128 v[6:9], v160
	ds_read_b128 v[158:161], v161
	ds_read_b128 v[192:195], v162
	ds_read_b128 v[18:21], v148 offset:32768
	ds_read_b128 v[22:25], v148 offset:34816
	ds_read_b128 v[34:37], v149 offset:32768
	ds_read_b128 v[38:41], v149 offset:34816
	ds_read_b128 v[50:53], v148 offset:36864
	ds_read_b128 v[54:57], v148 offset:38912
	ds_read_b128 v[196:199], v149 offset:36864
	ds_read_b128 v[200:203], v149 offset:38912
	s_waitcnt vmcnt(2)
	s_barrier
	s_waitcnt lgkmcnt(0)
	s_setprio 1
	s_waitcnt lgkmcnt(0)
	v_mfma_f32_16x16x32_bf16 v[66:69], v[2:5], v[18:21], v[126:129]
	v_mfma_f32_16x16x32_bf16 v[126:129], v[6:9], v[34:37], v[66:69]
	v_mfma_f32_16x16x32_bf16 v[66:69], v[158:161], v[18:21], v[122:125]
	v_mfma_f32_16x16x32_bf16 v[114:117], v[192:195], v[34:37], v[66:69]
	v_mfma_f32_16x16x32_bf16 v[66:69], v[2:5], v[22:25], v[118:121]
	v_mfma_f32_16x16x32_bf16 v[102:105], v[6:9], v[38:41], v[66:69]
	v_mfma_f32_16x16x32_bf16 v[66:69], v[158:161], v[22:25], v[136:139]
	v_mfma_f32_16x16x32_bf16 v[98:101], v[192:195], v[38:41], v[66:69]
	v_mfma_f32_16x16x32_bf16 v[66:69], v[2:5], v[50:53], v[110:113]
	v_mfma_f32_16x16x32_bf16 v[86:89], v[6:9], v[196:199], v[66:69]
	v_mfma_f32_16x16x32_bf16 v[66:69], v[158:161], v[50:53], v[106:109]
	v_mfma_f32_16x16x32_bf16 v[82:85], v[192:195], v[196:199], v[66:69]
	v_mfma_f32_16x16x32_bf16 v[66:69], v[2:5], v[54:57], v[206:209]
	v_mfma_f32_16x16x32_bf16 v[70:73], v[6:9], v[200:203], v[66:69]
	v_mfma_f32_16x16x32_bf16 v[66:69], v[158:161], v[54:57], v[218:221]
	v_mfma_f32_16x16x32_bf16 v[66:69], v[192:195], v[200:203], v[66:69]
	s_setprio 0
	s_barrier
	ds_read_b128 v[136:139], v163
	ds_read_b128 v[206:209], v164
	ds_read_b128 v[162:165], v165
	ds_read_b128 v[218:221], v166
	s_waitcnt vmcnt(0)
	s_barrier
	s_waitcnt lgkmcnt(0)
	s_setprio 1
	s_waitcnt lgkmcnt(0)
	v_mfma_f32_16x16x32_bf16 v[94:97], v[136:139], v[18:21], v[94:97]
	v_mfma_f32_16x16x32_bf16 v[18:21], v[162:165], v[18:21], v[90:93]
	v_mfma_f32_16x16x32_bf16 v[118:121], v[218:221], v[34:37], v[18:21]
	v_mfma_f32_16x16x32_bf16 v[18:21], v[136:139], v[22:25], v[172:175]
	v_mfma_f32_16x16x32_bf16 v[110:113], v[206:209], v[38:41], v[18:21]
	v_mfma_f32_16x16x32_bf16 v[18:21], v[162:165], v[22:25], v[176:179]
	v_mfma_f32_16x16x32_bf16 v[106:109], v[218:221], v[38:41], v[18:21]
	v_mfma_f32_16x16x32_bf16 v[18:21], v[136:139], v[50:53], v[78:81]
	v_mfma_f32_16x16x32_bf16 v[122:125], v[206:209], v[34:37], v[94:97]
	v_mfma_f32_16x16x32_bf16 v[94:97], v[206:209], v[196:199], v[18:21]
	v_mfma_f32_16x16x32_bf16 v[18:21], v[162:165], v[50:53], v[74:77]
	v_mfma_f32_16x16x32_bf16 v[90:93], v[218:221], v[196:199], v[18:21]
	v_mfma_f32_16x16x32_bf16 v[18:21], v[136:139], v[54:57], v[180:183]
	v_mfma_f32_16x16x32_bf16 v[78:81], v[206:209], v[200:203], v[18:21]
	v_mfma_f32_16x16x32_bf16 v[18:21], v[162:165], v[54:57], v[184:187]
	v_mfma_f32_16x16x32_bf16 v[74:77], v[218:221], v[200:203], v[18:21]
	s_setprio 0
	s_barrier
	ds_read_b128 v[172:175], v148 offset:49152
	ds_read_b128 v[176:179], v148 offset:51200
	ds_read_b128 v[180:183], v149 offset:49152
	ds_read_b128 v[184:187], v149 offset:51200
	ds_read_b128 v[196:199], v148 offset:53248
	ds_read_b128 v[200:203], v148 offset:55296
	ds_read_b128 v[230:233], v149 offset:53248
	ds_read_b128 v[234:237], v149 offset:55296
	s_barrier
	s_waitcnt lgkmcnt(0)
	s_setprio 1
	s_waitcnt lgkmcnt(0)
	v_mfma_f32_16x16x32_bf16 v[18:21], v[2:5], v[172:175], v[62:65]
	v_mfma_f32_16x16x32_bf16 v[54:57], v[6:9], v[180:183], v[18:21]
	v_mfma_f32_16x16x32_bf16 v[18:21], v[158:161], v[172:175], v[58:61]
	v_mfma_f32_16x16x32_bf16 v[50:53], v[192:195], v[180:183], v[18:21]
	v_mfma_f32_16x16x32_bf16 v[18:21], v[2:5], v[176:179], v[222:225]
	v_mfma_f32_16x16x32_bf16 v[38:41], v[6:9], v[184:187], v[18:21]
	v_mfma_f32_16x16x32_bf16 v[18:21], v[158:161], v[176:179], v[226:229]
	v_mfma_f32_16x16x32_bf16 v[34:37], v[192:195], v[184:187], v[18:21]
	v_mfma_f32_16x16x32_bf16 v[18:21], v[2:5], v[196:199], v[46:49]
	v_mfma_f32_16x16x32_bf16 v[2:5], v[2:5], v[200:203], v[140:143]
	v_mfma_f32_16x16x32_bf16 v[22:25], v[6:9], v[230:233], v[18:21]
	v_mfma_f32_16x16x32_bf16 v[18:21], v[158:161], v[196:199], v[42:45]
	v_mfma_f32_16x16x32_bf16 v[6:9], v[6:9], v[234:237], v[2:5]
	v_mfma_f32_16x16x32_bf16 v[2:5], v[158:161], v[200:203], v[144:147]
	v_mfma_f32_16x16x32_bf16 v[18:21], v[192:195], v[230:233], v[18:21]
	v_mfma_f32_16x16x32_bf16 v[2:5], v[192:195], v[234:237], v[2:5]
	s_setprio 0
	s_setprio 1
	v_mfma_f32_16x16x32_bf16 v[26:29], v[162:165], v[172:175], v[26:29]
	v_mfma_f32_16x16x32_bf16 v[58:61], v[218:221], v[180:183], v[26:29]
	v_mfma_f32_16x16x32_bf16 v[26:29], v[136:139], v[176:179], v[150:153]
	v_mfma_f32_16x16x32_bf16 v[46:49], v[206:209], v[184:187], v[26:29]
	v_mfma_f32_16x16x32_bf16 v[26:29], v[162:165], v[176:179], v[168:171]
	v_mfma_f32_16x16x32_bf16 v[10:13], v[162:165], v[196:199], v[10:13]
	v_mfma_f32_16x16x32_bf16 v[30:33], v[136:139], v[172:175], v[30:33]
	v_mfma_f32_16x16x32_bf16 v[42:45], v[218:221], v[184:187], v[26:29]
	v_mfma_f32_16x16x32_bf16 v[14:17], v[136:139], v[196:199], v[14:17]
	v_mfma_f32_16x16x32_bf16 v[26:29], v[218:221], v[230:233], v[10:13]
	v_mfma_f32_16x16x32_bf16 v[10:13], v[136:139], v[200:203], v[188:191]
	v_mfma_f32_16x16x32_bf16 v[62:65], v[206:209], v[180:183], v[30:33]
	v_mfma_f32_16x16x32_bf16 v[30:33], v[206:209], v[230:233], v[14:17]
	v_mfma_f32_16x16x32_bf16 v[14:17], v[206:209], v[234:237], v[10:13]
	v_mfma_f32_16x16x32_bf16 v[10:13], v[162:165], v[200:203], v[154:157]
	v_mfma_f32_16x16x32_bf16 v[10:13], v[218:221], v[234:237], v[10:13]
	s_setprio 0
	s_cmpk_gt_u32 s0, 0xff
	s_barrier
	s_cbranch_scc1 .LBB0_112
	s_barrier

.LBB0_116:
	s_lshl_b32 s27, s27, 5
	v_and_b32_e32 v0, 15, v19
	s_and_b32 s27, s27, 0x60
	v_lshlrev_b32_e32 v14, 7, v0
	v_or_b32_e32 v0, s27, v0
	s_add_i32 s27, s1, 0x18000
	s_mov_b64 s[34:35], 0x80
	v_lshl_or_b32 v14, s28, 13, v14
	v_lshl_add_u64 v[2:3], v[2:3], 0, s[34:35]
	s_mov_b32 m0, s27
	s_add_i32 s28, s1, 0x1a000
	s_waitcnt vmcnt(4)
	s_barrier
	global_load_lds_dwordx4 v[2:3], off
	v_lshl_add_u64 v[2:3], v[4:5], 0, s[34:35]
	s_mov_b32 m0, s28
	s_add_i32 s29, s1, 0x8000
	global_load_lds_dwordx4 v[2:3], off
	v_lshl_add_u64 v[2:3], v[8:9], 0, s[34:35]
	s_mov_b32 m0, s29
	s_add_i32 s30, s1, 0xa000
	global_load_lds_dwordx4 v[2:3], off
	v_lshl_add_u64 v[2:3], v[6:7], 0, s[34:35]
	s_mov_b32 m0, s30
	s_add_i32 s31, s1, 0x1c000
	global_load_lds_dwordx4 v[2:3], off
	v_lshl_add_u64 v[2:3], v[12:13], 0, s[34:35]
	s_mov_b32 m0, s31
	v_and_b32_e32 v15, 3, v20
	global_load_lds_dwordx4 v[2:3], off
	v_lshl_add_u64 v[2:3], v[10:11], 0, s[34:35]
	s_add_i32 s34, s1, 0x1e000
	s_mov_b32 m0, s34
	v_bfe_u32 v19, v19, 1, 3
	global_load_lds_dwordx4 v[2:3], off
	v_bitop3_b32 v20, v20, v19, 3 bitop3:0x6c
	v_bitop3_b32 v15, v15, v19, 4 bitop3:0x36
	v_lshlrev_b32_e32 v20, 4, v20
	v_lshlrev_b32_e32 v15, 4, v15
	v_lshlrev_b32_e32 v0, 7, v0
	v_or_b32_e32 v150, v0, v20
	v_or_b32_e32 v151, v0, v15
	s_waitcnt vmcnt(6)
	v_add_u32_e32 v0, v18, v16
	v_lshlrev_b64 v[2:3], 1, v[0:1]
	v_add_u32_e32 v0, v17, v16
	v_lshl_add_u64 v[140:141], s[12:13], 0, v[2:3]
	v_lshlrev_b64 v[4:5], 1, v[0:1]
	v_lshl_add_u64 v[144:145], s[4:5], 0, v[2:3]
	v_mov_b32_e32 v2, 0
	v_or_b32_e32 v148, v20, v14
	v_or_b32_e32 v149, v15, v14
	s_barrier
	v_lshl_add_u64 v[142:143], s[12:13], 0, v[4:5]
	v_lshl_add_u64 v[146:147], s[4:5], 0, v[4:5]
	s_mov_b32 s4, -2
	v_mov_b32_e32 v3, v2
	v_mov_b32_e32 v4, v2
	v_mov_b32_e32 v5, v2
	v_mov_b32_e32 v6, v2
	v_mov_b32_e32 v7, v2
	v_mov_b32_e32 v8, v2
	v_mov_b32_e32 v9, v2
	v_mov_b32_e32 v10, v2
	v_mov_b32_e32 v11, v2
	v_mov_b32_e32 v12, v2
	v_mov_b32_e32 v13, v2
	v_mov_b32_e32 v14, v2
	v_mov_b32_e32 v15, v2
	v_mov_b32_e32 v16, v2
	v_mov_b32_e32 v17, v2
	v_mov_b32_e32 v18, v2
	v_mov_b32_e32 v19, v2
	v_mov_b32_e32 v20, v2
	v_mov_b32_e32 v21, v2
	v_mov_b32_e32 v22, v2
	v_mov_b32_e32 v23, v2
	v_mov_b32_e32 v24, v2
	v_mov_b32_e32 v25, v2
	v_mov_b32_e32 v26, v2
	v_mov_b32_e32 v27, v2
	v_mov_b32_e32 v28, v2
	v_mov_b32_e32 v29, v2
	v_mov_b32_e32 v30, v2
	v_mov_b32_e32 v31, v2
	v_mov_b32_e32 v32, v2
	v_mov_b32_e32 v33, v2
	v_mov_b32_e32 v34, v2
	v_mov_b32_e32 v35, v2
	v_mov_b32_e32 v36, v2
	v_mov_b32_e32 v37, v2
	v_mov_b32_e32 v38, v2
	v_mov_b32_e32 v39, v2
	v_mov_b32_e32 v40, v2
	v_mov_b32_e32 v41, v2
	v_mov_b32_e32 v42, v2
	v_mov_b32_e32 v43, v2
	v_mov_b32_e32 v44, v2
	v_mov_b32_e32 v45, v2
	v_mov_b32_e32 v46, v2
	v_mov_b32_e32 v47, v2
	v_mov_b32_e32 v48, v2
	v_mov_b32_e32 v49, v2
	v_mov_b32_e32 v50, v2
	v_mov_b32_e32 v51, v2
	v_mov_b32_e32 v52, v2
	v_mov_b32_e32 v53, v2
	v_mov_b32_e32 v54, v2
	v_mov_b32_e32 v55, v2
	v_mov_b32_e32 v56, v2
	v_mov_b32_e32 v57, v2
	v_mov_b32_e32 v58, v2
	v_mov_b32_e32 v59, v2
	v_mov_b32_e32 v60, v2
	v_mov_b32_e32 v61, v2
	v_mov_b32_e32 v62, v2
	v_mov_b32_e32 v63, v2
	v_mov_b32_e32 v64, v2
	v_mov_b32_e32 v65, v2
	v_mov_b32_e32 v66, v2
	v_mov_b32_e32 v67, v2
	v_mov_b32_e32 v68, v2
	v_mov_b32_e32 v69, v2
	v_mov_b32_e32 v70, v2
	v_mov_b32_e32 v71, v2
	v_mov_b32_e32 v72, v2
	v_mov_b32_e32 v73, v2
	v_mov_b32_e32 v74, v2
	v_mov_b32_e32 v75, v2
	v_mov_b32_e32 v76, v2
	v_mov_b32_e32 v77, v2
	v_mov_b32_e32 v78, v2
	v_mov_b32_e32 v79, v2
	v_mov_b32_e32 v80, v2
	v_mov_b32_e32 v81, v2
	v_mov_b32_e32 v82, v2
	v_mov_b32_e32 v83, v2
	v_mov_b32_e32 v84, v2
	v_mov_b32_e32 v85, v2
	v_mov_b32_e32 v86, v2
	v_mov_b32_e32 v87, v2
	v_mov_b32_e32 v88, v2
	v_mov_b32_e32 v89, v2
	v_mov_b32_e32 v90, v2
	v_mov_b32_e32 v91, v2
	v_mov_b32_e32 v92, v2
	v_mov_b32_e32 v93, v2
	v_mov_b32_e32 v94, v2
	v_mov_b32_e32 v95, v2
	v_mov_b32_e32 v96, v2
	v_mov_b32_e32 v97, v2
	v_mov_b32_e32 v98, v2
	v_mov_b32_e32 v99, v2
	v_mov_b32_e32 v100, v2
	v_mov_b32_e32 v101, v2
	v_mov_b32_e32 v102, v2
	v_mov_b32_e32 v103, v2
	v_mov_b32_e32 v104, v2
	v_mov_b32_e32 v105, v2
	v_mov_b32_e32 v106, v2
	v_mov_b32_e32 v107, v2
	v_mov_b32_e32 v108, v2
	v_mov_b32_e32 v109, v2
	v_mov_b32_e32 v110, v2
	v_mov_b32_e32 v111, v2
	v_mov_b32_e32 v112, v2
	v_mov_b32_e32 v113, v2
	v_mov_b32_e32 v114, v2
	v_mov_b32_e32 v115, v2
	v_mov_b32_e32 v116, v2
	v_mov_b32_e32 v117, v2
	v_mov_b32_e32 v118, v2
	v_mov_b32_e32 v119, v2
	v_mov_b32_e32 v120, v2
	v_mov_b32_e32 v121, v2
	v_mov_b32_e32 v122, v2
	v_mov_b32_e32 v123, v2
	v_mov_b32_e32 v124, v2
	v_mov_b32_e32 v125, v2
	v_mov_b32_e32 v126, v2
	v_mov_b32_e32 v127, v2
	v_mov_b32_e32 v128, v2
	v_mov_b32_e32 v129, v2
	s_mov_b64 s[36:37], 0x82d4900
	s_mov_b64 s[38:39], 0x8254980
	s_mov_b64 s[40:41], 0x82d4980
	s_waitcnt lgkmcnt(0)
	s_sub_u32 s100, s100, 0x40000000
	s_subb_u32 s101, s101, 0
	s_mov_b64 vcc, s[100:101]
	v_lshl_add_u64 v[210:211], v[134:135], 0, v[142:143]
	v_subrev_u32_e32 v210, vcc_lo, v210
	v_lshl_add_u64 v[214:215], v[134:135], 0, v[140:141]
	v_subrev_u32_e32 v214, vcc_lo, v214
	v_lshl_add_u64 v[242:243], v[134:135], 0, v[146:147]
	v_subrev_u32_e32 v242, vcc_lo, v242
	v_lshl_add_u64 v[244:245], v[134:135], 0, v[144:145]
	v_subrev_u32_e32 v244, vcc_lo, v244
	v_add_u32_e32 v211, 0x10000, v150
	v_add_u32_e32 v215, 0x10000, v151
	v_add_u32_e32 v0, s50, v210
	v_add_u32_e32 v152, s54, v210
	v_add_u32_e32 v153, s58, v210
	v_add_u32_e32 v210, s62, v210
	v_add_u32_e32 v154, s50, v214
	v_add_u32_e32 v155, s54, v214
	v_add_u32_e32 v156, s58, v214
	v_add_u32_e32 v214, s62, v214
	v_add_u32_e32 v157, s70, v242
	v_add_u32_e32 v158, s36, v242
	v_add_u32_e32 v159, s38, v242
	v_add_u32_e32 v242, s40, v242
	v_add_u32_e32 v243, s70, v244
	v_add_u32_e32 v245, s36, v244
	v_add_u32_e32 v246, s38, v244
	v_add_u32_e32 v244, s40, v244
	s_add_i32 s12, s1, 0xc000
	s_add_i32 s5, s1, 0xe000
.LBB0_117:
	ds_read_b128 v[160:163], v211
	ds_read_b128 v[164:167], v215
	ds_read_b128 v[168:171], v211 offset:2048
	ds_read_b128 v[172:175], v215 offset:2048
	ds_read_b128 v[176:179], v148
	ds_read_b128 v[180:183], v148 offset:2048
	ds_read_b128 v[184:187], v149
	ds_read_b128 v[188:191], v149 offset:2048
	ds_read_b128 v[192:195], v148 offset:4096
	ds_read_b128 v[196:199], v148 offset:6144
	s_mov_b32 m0, s12
	ds_read_b128 v[200:203], v149 offset:4096
	global_load_lds_dwordx4 v0, vcc
	s_mov_b32 m0, s5
	ds_read_b128 v[206:209], v149 offset:6144
	global_load_lds_dwordx4 v154, vcc
	s_waitcnt vmcnt(10) lgkmcnt(8)
	s_barrier
	s_waitcnt lgkmcnt(0)
	v_mfma_f32_16x16x32_bf16 v[126:129], v[160:163], v[176:179], v[126:129]
	v_mfma_f32_16x16x32_bf16 v[122:125], v[168:171], v[176:179], v[122:125]
	v_mfma_f32_16x16x32_bf16 v[118:121], v[160:163], v[180:183], v[118:121]
	v_mfma_f32_16x16x32_bf16 v[114:117], v[168:171], v[180:183], v[114:117]
	v_mfma_f32_16x16x32_bf16 v[110:113], v[160:163], v[192:195], v[110:113]
	v_mfma_f32_16x16x32_bf16 v[106:109], v[168:171], v[192:195], v[106:109]
	v_mfma_f32_16x16x32_bf16 v[102:105], v[160:163], v[196:199], v[102:105]
	v_mfma_f32_16x16x32_bf16 v[98:101], v[168:171], v[196:199], v[98:101]
	v_mfma_f32_16x16x32_bf16 v[126:129], v[164:167], v[184:187], v[126:129]
	v_mfma_f32_16x16x32_bf16 v[122:125], v[172:175], v[184:187], v[122:125]
	v_mfma_f32_16x16x32_bf16 v[118:121], v[164:167], v[188:191], v[118:121]
	v_mfma_f32_16x16x32_bf16 v[114:117], v[172:175], v[188:191], v[114:117]
	v_mfma_f32_16x16x32_bf16 v[110:113], v[164:167], v[200:203], v[110:113]
	v_mfma_f32_16x16x32_bf16 v[106:109], v[172:175], v[200:203], v[106:109]
	v_mfma_f32_16x16x32_bf16 v[102:105], v[164:167], v[206:209], v[102:105]
	v_mfma_f32_16x16x32_bf16 v[98:101], v[172:175], v[206:209], v[98:101]
	s_barrier
	ds_read_b128 v[218:221], v211 offset:16384
	ds_read_b128 v[222:225], v215 offset:16384
	s_mov_b32 m0, s2
	ds_read_b128 v[226:229], v211 offset:18432
	global_load_lds_dwordx4 v157, vcc
	s_mov_b32 m0, s3
	ds_read_b128 v[230:233], v215 offset:18432
	global_load_lds_dwordx4 v243, vcc
	s_waitcnt vmcnt(10) lgkmcnt(0)
	s_barrier
	v_mfma_f32_16x16x32_bf16 v[94:97], v[218:221], v[176:179], v[94:97]
	v_mfma_f32_16x16x32_bf16 v[90:93], v[226:229], v[176:179], v[90:93]
	v_mfma_f32_16x16x32_bf16 v[86:89], v[218:221], v[180:183], v[86:89]
	v_mfma_f32_16x16x32_bf16 v[82:85], v[226:229], v[180:183], v[82:85]
	v_mfma_f32_16x16x32_bf16 v[78:81], v[218:221], v[192:195], v[78:81]
	v_mfma_f32_16x16x32_bf16 v[74:77], v[226:229], v[192:195], v[74:77]
	v_mfma_f32_16x16x32_bf16 v[70:73], v[218:221], v[196:199], v[70:73]
	v_mfma_f32_16x16x32_bf16 v[66:69], v[226:229], v[196:199], v[66:69]
	v_mfma_f32_16x16x32_bf16 v[94:97], v[222:225], v[184:187], v[94:97]
	v_mfma_f32_16x16x32_bf16 v[90:93], v[230:233], v[184:187], v[90:93]
	v_mfma_f32_16x16x32_bf16 v[86:89], v[222:225], v[188:191], v[86:89]
	v_mfma_f32_16x16x32_bf16 v[82:85], v[230:233], v[188:191], v[82:85]
	v_mfma_f32_16x16x32_bf16 v[78:81], v[222:225], v[200:203], v[78:81]
	v_mfma_f32_16x16x32_bf16 v[74:77], v[230:233], v[200:203], v[74:77]
	v_mfma_f32_16x16x32_bf16 v[70:73], v[222:225], v[206:209], v[70:73]
	v_mfma_f32_16x16x32_bf16 v[66:69], v[230:233], v[206:209], v[66:69]
	s_barrier
	ds_read_b128 v[176:179], v148 offset:16384
	ds_read_b128 v[180:183], v148 offset:18432
	ds_read_b128 v[184:187], v149 offset:16384
	ds_read_b128 v[188:191], v149 offset:18432
	s_mov_b32 m0, s1
	ds_read_b128 v[192:195], v148 offset:20480
	global_load_lds_dwordx4 v152, vcc
	s_mov_b32 m0, s11
	ds_read_b128 v[196:199], v148 offset:22528
	global_load_lds_dwordx4 v155, vcc
	s_mov_b32 m0, s23
	ds_read_b128 v[200:203], v149 offset:20480
	global_load_lds_dwordx4 v158, vcc
	s_mov_b32 m0, s24
	ds_read_b128 v[206:209], v149 offset:22528
	global_load_lds_dwordx4 v245, vcc
	s_waitcnt vmcnt(10) lgkmcnt(0)
	s_barrier
	v_mfma_f32_16x16x32_bf16 v[62:65], v[160:163], v[176:179], v[62:65]
	v_mfma_f32_16x16x32_bf16 v[58:61], v[168:171], v[176:179], v[58:61]
	v_mfma_f32_16x16x32_bf16 v[54:57], v[160:163], v[180:183], v[54:57]
	v_mfma_f32_16x16x32_bf16 v[50:53], v[168:171], v[180:183], v[50:53]
	v_mfma_f32_16x16x32_bf16 v[46:49], v[160:163], v[192:195], v[46:49]
	v_mfma_f32_16x16x32_bf16 v[42:45], v[168:171], v[192:195], v[42:45]
	v_mfma_f32_16x16x32_bf16 v[38:41], v[160:163], v[196:199], v[38:41]
	v_mfma_f32_16x16x32_bf16 v[34:37], v[168:171], v[196:199], v[34:37]
	v_mfma_f32_16x16x32_bf16 v[62:65], v[164:167], v[184:187], v[62:65]
	v_mfma_f32_16x16x32_bf16 v[58:61], v[172:175], v[184:187], v[58:61]
	v_mfma_f32_16x16x32_bf16 v[54:57], v[164:167], v[188:191], v[54:57]
	v_mfma_f32_16x16x32_bf16 v[50:53], v[172:175], v[188:191], v[50:53]
	v_mfma_f32_16x16x32_bf16 v[46:49], v[164:167], v[200:203], v[46:49]
	v_mfma_f32_16x16x32_bf16 v[42:45], v[172:175], v[200:203], v[42:45]
	v_mfma_f32_16x16x32_bf16 v[38:41], v[164:167], v[206:209], v[38:41]
	v_mfma_f32_16x16x32_bf16 v[34:37], v[172:175], v[206:209], v[34:37]
	v_mfma_f32_16x16x32_bf16 v[30:33], v[218:221], v[176:179], v[30:33]
	v_mfma_f32_16x16x32_bf16 v[26:29], v[226:229], v[176:179], v[26:29]
	v_mfma_f32_16x16x32_bf16 v[22:25], v[218:221], v[180:183], v[22:25]
	v_mfma_f32_16x16x32_bf16 v[18:21], v[226:229], v[180:183], v[18:21]
	v_mfma_f32_16x16x32_bf16 v[14:17], v[218:221], v[192:195], v[14:17]
	v_mfma_f32_16x16x32_bf16 v[10:13], v[226:229], v[192:195], v[10:13]
	v_mfma_f32_16x16x32_bf16 v[6:9], v[218:221], v[196:199], v[6:9]
	v_mfma_f32_16x16x32_bf16 v[2:5], v[226:229], v[196:199], v[2:5]
	v_mfma_f32_16x16x32_bf16 v[30:33], v[222:225], v[184:187], v[30:33]
	v_mfma_f32_16x16x32_bf16 v[26:29], v[230:233], v[184:187], v[26:29]
	v_mfma_f32_16x16x32_bf16 v[22:25], v[222:225], v[188:191], v[22:25]
	v_mfma_f32_16x16x32_bf16 v[18:21], v[230:233], v[188:191], v[18:21]
	v_mfma_f32_16x16x32_bf16 v[14:17], v[222:225], v[200:203], v[14:17]
	v_mfma_f32_16x16x32_bf16 v[10:13], v[230:233], v[200:203], v[10:13]
	v_mfma_f32_16x16x32_bf16 v[6:9], v[222:225], v[206:209], v[6:9]
	v_mfma_f32_16x16x32_bf16 v[2:5], v[230:233], v[206:209], v[2:5]
	s_barrier
	ds_read_b128 v[168:171], v211 offset:32768
	ds_read_b128 v[172:175], v215 offset:32768
	ds_read_b128 v[176:179], v211 offset:34816
	ds_read_b128 v[180:183], v215 offset:34816
	ds_read_b128 v[184:187], v148 offset:32768
	ds_read_b128 v[188:191], v148 offset:34816
	ds_read_b128 v[192:195], v149 offset:32768
	ds_read_b128 v[196:199], v149 offset:34816
	ds_read_b128 v[200:203], v148 offset:36864
	ds_read_b128 v[206:209], v148 offset:38912
	s_mov_b32 m0, s25
	ds_read_b128 v[218:221], v149 offset:36864
	global_load_lds_dwordx4 v153, vcc
	s_mov_b32 m0, s26
	ds_read_b128 v[222:225], v149 offset:38912
	global_load_lds_dwordx4 v156, vcc
	s_waitcnt vmcnt(10) lgkmcnt(8)
	s_barrier
	s_waitcnt lgkmcnt(0)
	v_mfma_f32_16x16x32_bf16 v[126:129], v[168:171], v[184:187], v[126:129]
	v_mfma_f32_16x16x32_bf16 v[122:125], v[176:179], v[184:187], v[122:125]
	v_mfma_f32_16x16x32_bf16 v[118:121], v[168:171], v[188:191], v[118:121]
	v_mfma_f32_16x16x32_bf16 v[114:117], v[176:179], v[188:191], v[114:117]
	v_mfma_f32_16x16x32_bf16 v[110:113], v[168:171], v[200:203], v[110:113]
	v_mfma_f32_16x16x32_bf16 v[106:109], v[176:179], v[200:203], v[106:109]
	v_mfma_f32_16x16x32_bf16 v[102:105], v[168:171], v[206:209], v[102:105]
	v_mfma_f32_16x16x32_bf16 v[98:101], v[176:179], v[206:209], v[98:101]
	v_mfma_f32_16x16x32_bf16 v[126:129], v[172:175], v[192:195], v[126:129]
	v_mfma_f32_16x16x32_bf16 v[122:125], v[180:183], v[192:195], v[122:125]
	v_mfma_f32_16x16x32_bf16 v[118:121], v[172:175], v[196:199], v[118:121]
	v_mfma_f32_16x16x32_bf16 v[114:117], v[180:183], v[196:199], v[114:117]
	v_mfma_f32_16x16x32_bf16 v[110:113], v[172:175], v[218:221], v[110:113]
	v_mfma_f32_16x16x32_bf16 v[106:109], v[180:183], v[218:221], v[106:109]
	v_mfma_f32_16x16x32_bf16 v[102:105], v[172:175], v[222:225], v[102:105]
	v_mfma_f32_16x16x32_bf16 v[98:101], v[180:183], v[222:225], v[98:101]
	s_barrier
	ds_read_b128 v[226:229], v211 offset:49152
	ds_read_b128 v[230:233], v215 offset:49152
	s_mov_b32 m0, s27
	ds_read_b128 v[234:237], v211 offset:51200
	global_load_lds_dwordx4 v159, vcc
	s_mov_b32 m0, s28
	ds_read_b128 v[238:241], v215 offset:51200
	global_load_lds_dwordx4 v246, vcc
	s_waitcnt vmcnt(10) lgkmcnt(0)
	s_barrier
	v_mfma_f32_16x16x32_bf16 v[94:97], v[226:229], v[184:187], v[94:97]
	v_mfma_f32_16x16x32_bf16 v[90:93], v[234:237], v[184:187], v[90:93]
	v_mfma_f32_16x16x32_bf16 v[86:89], v[226:229], v[188:191], v[86:89]
	v_mfma_f32_16x16x32_bf16 v[82:85], v[234:237], v[188:191], v[82:85]
	v_mfma_f32_16x16x32_bf16 v[78:81], v[226:229], v[200:203], v[78:81]
	v_mfma_f32_16x16x32_bf16 v[74:77], v[234:237], v[200:203], v[74:77]
	v_mfma_f32_16x16x32_bf16 v[70:73], v[226:229], v[206:209], v[70:73]
	v_mfma_f32_16x16x32_bf16 v[66:69], v[234:237], v[206:209], v[66:69]
	v_mfma_f32_16x16x32_bf16 v[94:97], v[230:233], v[192:195], v[94:97]
	v_mfma_f32_16x16x32_bf16 v[90:93], v[238:241], v[192:195], v[90:93]
	v_mfma_f32_16x16x32_bf16 v[86:89], v[230:233], v[196:199], v[86:89]
	v_mfma_f32_16x16x32_bf16 v[82:85], v[238:241], v[196:199], v[82:85]
	v_mfma_f32_16x16x32_bf16 v[78:81], v[230:233], v[218:221], v[78:81]
	v_mfma_f32_16x16x32_bf16 v[74:77], v[238:241], v[218:221], v[74:77]
	v_mfma_f32_16x16x32_bf16 v[70:73], v[230:233], v[222:225], v[70:73]
	v_mfma_f32_16x16x32_bf16 v[66:69], v[238:241], v[222:225], v[66:69]
	s_barrier
	ds_read_b128 v[184:187], v148 offset:49152
	ds_read_b128 v[188:191], v148 offset:51200
	ds_read_b128 v[192:195], v149 offset:49152
	ds_read_b128 v[196:199], v149 offset:51200
	s_mov_b32 m0, s29
	ds_read_b128 v[200:203], v148 offset:53248
	global_load_lds_dwordx4 v210, vcc
	s_mov_b32 m0, s30
	ds_read_b128 v[206:209], v148 offset:55296
	global_load_lds_dwordx4 v214, vcc
	s_mov_b32 m0, s31
	ds_read_b128 v[218:221], v149 offset:53248
	global_load_lds_dwordx4 v242, vcc
	s_mov_b32 m0, s34
	ds_read_b128 v[222:225], v149 offset:55296
	global_load_lds_dwordx4 v244, vcc
	s_waitcnt vmcnt(10) lgkmcnt(0)
	s_barrier
	v_mfma_f32_16x16x32_bf16 v[62:65], v[168:171], v[184:187], v[62:65]
	v_mfma_f32_16x16x32_bf16 v[58:61], v[176:179], v[184:187], v[58:61]
	v_mfma_f32_16x16x32_bf16 v[54:57], v[168:171], v[188:191], v[54:57]
	v_mfma_f32_16x16x32_bf16 v[50:53], v[176:179], v[188:191], v[50:53]
	v_mfma_f32_16x16x32_bf16 v[46:49], v[168:171], v[200:203], v[46:49]
	v_mfma_f32_16x16x32_bf16 v[42:45], v[176:179], v[200:203], v[42:45]
	v_mfma_f32_16x16x32_bf16 v[38:41], v[168:171], v[206:209], v[38:41]
	v_mfma_f32_16x16x32_bf16 v[34:37], v[176:179], v[206:209], v[34:37]
	v_mfma_f32_16x16x32_bf16 v[62:65], v[172:175], v[192:195], v[62:65]
	v_mfma_f32_16x16x32_bf16 v[58:61], v[180:183], v[192:195], v[58:61]
	v_mfma_f32_16x16x32_bf16 v[54:57], v[172:175], v[196:199], v[54:57]
	v_mfma_f32_16x16x32_bf16 v[50:53], v[180:183], v[196:199], v[50:53]
	v_mfma_f32_16x16x32_bf16 v[46:49], v[172:175], v[218:221], v[46:49]
	v_mfma_f32_16x16x32_bf16 v[42:45], v[180:183], v[218:221], v[42:45]
	v_mfma_f32_16x16x32_bf16 v[38:41], v[172:175], v[222:225], v[38:41]
	v_mfma_f32_16x16x32_bf16 v[34:37], v[180:183], v[222:225], v[34:37]
	v_mfma_f32_16x16x32_bf16 v[30:33], v[226:229], v[184:187], v[30:33]
	v_mfma_f32_16x16x32_bf16 v[26:29], v[234:237], v[184:187], v[26:29]
	v_mfma_f32_16x16x32_bf16 v[22:25], v[226:229], v[188:191], v[22:25]
	v_mfma_f32_16x16x32_bf16 v[18:21], v[234:237], v[188:191], v[18:21]
	v_mfma_f32_16x16x32_bf16 v[14:17], v[226:229], v[200:203], v[14:17]
	v_mfma_f32_16x16x32_bf16 v[10:13], v[234:237], v[200:203], v[10:13]
	v_mfma_f32_16x16x32_bf16 v[6:9], v[226:229], v[206:209], v[6:9]
	v_mfma_f32_16x16x32_bf16 v[2:5], v[234:237], v[206:209], v[2:5]
	v_mfma_f32_16x16x32_bf16 v[30:33], v[230:233], v[192:195], v[30:33]
	v_mfma_f32_16x16x32_bf16 v[26:29], v[238:241], v[192:195], v[26:29]
	v_mfma_f32_16x16x32_bf16 v[22:25], v[230:233], v[196:199], v[22:25]
	v_mfma_f32_16x16x32_bf16 v[18:21], v[238:241], v[196:199], v[18:21]
	v_mfma_f32_16x16x32_bf16 v[14:17], v[230:233], v[218:221], v[14:17]
	v_mfma_f32_16x16x32_bf16 v[10:13], v[238:241], v[218:221], v[10:13]
	v_mfma_f32_16x16x32_bf16 v[6:9], v[230:233], v[222:225], v[6:9]
	v_mfma_f32_16x16x32_bf16 v[2:5], v[238:241], v[222:225], v[2:5]
	s_add_u32 vcc_lo, vcc_lo, s54
	s_addc_u32 vcc_hi, vcc_hi, s55
	s_add_i32 s4, s4, 2
	s_cmp_lt_u32 s4, 28
	v_lshl_add_u64 v[134:135], v[134:135], 0, s[54:55]
	s_barrier
	s_cbranch_scc1 .LBB0_117
	s_waitcnt vmcnt(6)
	v_or_b32_e32 v0, 0x10000, v150
	v_add_u32_e32 v153, 0x10800, v150
	v_or_b32_e32 v152, 0x10000, v151
	v_add_u32_e32 v154, 0x10800, v151
	v_or_b32_e32 v155, 0x14000, v150
	v_add_u32_e32 v157, 0x14800, v150
	v_or_b32_e32 v156, 0x14000, v151
	v_add_u32_e32 v158, 0x14800, v151
	v_or_b32_e32 v159, 0x18000, v150
	v_add_u32_e32 v161, 0x18800, v150
	v_or_b32_e32 v160, 0x18000, v151
	v_add_u32_e32 v162, 0x18800, v151
	v_or_b32_e32 v163, 0x1c000, v150
	v_add_u32_e32 v165, 0x1c800, v150
	v_or_b32_e32 v164, 0x1c000, v151
	v_add_u32_e32 v166, 0x1c800, v151
	s_mov_b64 s[2:3], 0xf80
	s_mov_b32 m0, s12
	v_lshl_add_u64 v[134:135], v[138:139], 0, s[2:3]
	ds_read_b128 v[140:143], v0
	ds_read_b128 v[144:147], v152
	ds_read_b128 v[150:153], v153
	ds_read_b128 v[168:171], v154
	ds_read_b128 v[172:175], v148
	ds_read_b128 v[176:179], v148 offset:2048
	ds_read_b128 v[180:183], v149
	ds_read_b128 v[184:187], v149 offset:2048
	ds_read_b128 v[188:191], v148 offset:4096
	ds_read_b128 v[192:195], v148 offset:6144
	ds_read_b128 v[196:199], v149 offset:4096
	ds_read_b128 v[200:203], v149 offset:6144
	global_load_lds_dwordx4 v[134:135], off
	v_lshl_add_u64 v[134:135], v[136:137], 0, s[2:3]
	s_mov_b32 m0, s5
	s_nop 0
	global_load_lds_dwordx4 v[134:135], off
	s_barrier
	s_waitcnt lgkmcnt(0)
	s_setprio 1
	s_waitcnt lgkmcnt(0)
	v_mfma_f32_16x16x32_bf16 v[126:129], v[140:143], v[172:175], v[126:129]
	v_mfma_f32_16x16x32_bf16 v[122:125], v[150:153], v[172:175], v[122:125]
	v_mfma_f32_16x16x32_bf16 v[118:121], v[140:143], v[176:179], v[118:121]
	v_mfma_f32_16x16x32_bf16 v[110:113], v[140:143], v[188:191], v[110:113]
	v_mfma_f32_16x16x32_bf16 v[106:109], v[150:153], v[188:191], v[106:109]
	v_mfma_f32_16x16x32_bf16 v[126:129], v[144:147], v[180:183], v[126:129]
	v_mfma_f32_16x16x32_bf16 v[122:125], v[168:171], v[180:183], v[122:125]
	v_mfma_f32_16x16x32_bf16 v[118:121], v[144:147], v[184:187], v[118:121]
	v_mfma_f32_16x16x32_bf16 v[114:117], v[150:153], v[176:179], v[114:117]
	v_mfma_f32_16x16x32_bf16 v[110:113], v[144:147], v[196:199], v[110:113]
	v_mfma_f32_16x16x32_bf16 v[106:109], v[168:171], v[196:199], v[106:109]
	v_mfma_f32_16x16x32_bf16 v[102:105], v[140:143], v[192:195], v[102:105]
	v_mfma_f32_16x16x32_bf16 v[98:101], v[150:153], v[192:195], v[98:101]
	v_mfma_f32_16x16x32_bf16 v[134:137], v[168:171], v[184:187], v[114:117]
	v_mfma_f32_16x16x32_bf16 v[206:209], v[144:147], v[200:203], v[102:105]
	v_mfma_f32_16x16x32_bf16 v[218:221], v[168:171], v[200:203], v[98:101]
	s_setprio 0
	s_barrier
	s_nop 2
	ds_read_b128 v[98:101], v155
	ds_read_b128 v[102:105], v156
	ds_read_b128 v[114:117], v157
	ds_read_b128 v[154:157], v158
	s_barrier
	s_waitcnt lgkmcnt(0)
	s_setprio 1
	s_waitcnt lgkmcnt(0)
	v_mfma_f32_16x16x32_bf16 v[94:97], v[98:101], v[172:175], v[94:97]
	v_mfma_f32_16x16x32_bf16 v[90:93], v[114:117], v[172:175], v[90:93]
	v_mfma_f32_16x16x32_bf16 v[78:81], v[98:101], v[188:191], v[78:81]
	v_mfma_f32_16x16x32_bf16 v[74:77], v[114:117], v[188:191], v[74:77]
	v_mfma_f32_16x16x32_bf16 v[94:97], v[102:105], v[180:183], v[94:97]
	v_mfma_f32_16x16x32_bf16 v[90:93], v[154:157], v[180:183], v[90:93]
	v_mfma_f32_16x16x32_bf16 v[86:89], v[98:101], v[176:179], v[86:89]
	v_mfma_f32_16x16x32_bf16 v[82:85], v[114:117], v[176:179], v[82:85]
	v_mfma_f32_16x16x32_bf16 v[78:81], v[102:105], v[196:199], v[78:81]
	v_mfma_f32_16x16x32_bf16 v[74:77], v[154:157], v[196:199], v[74:77]
	v_mfma_f32_16x16x32_bf16 v[70:73], v[98:101], v[192:195], v[70:73]
	v_mfma_f32_16x16x32_bf16 v[66:69], v[114:117], v[192:195], v[66:69]
	v_mfma_f32_16x16x32_bf16 v[172:175], v[102:105], v[184:187], v[86:89]
	v_mfma_f32_16x16x32_bf16 v[176:179], v[154:157], v[184:187], v[82:85]
	v_mfma_f32_16x16x32_bf16 v[180:183], v[102:105], v[200:203], v[70:73]
	v_mfma_f32_16x16x32_bf16 v[184:187], v[154:157], v[200:203], v[66:69]
	s_setprio 0
	s_barrier
	s_nop 1
	ds_read_b128 v[66:69], v148 offset:16384
	ds_read_b128 v[70:73], v148 offset:18432
	ds_read_b128 v[82:85], v149 offset:16384
	ds_read_b128 v[86:89], v149 offset:18432
	ds_read_b128 v[188:191], v148 offset:20480
	ds_read_b128 v[192:195], v148 offset:22528
	ds_read_b128 v[196:199], v149 offset:20480
	ds_read_b128 v[200:203], v149 offset:22528
	s_waitcnt vmcnt(4)
	s_barrier
	s_waitcnt lgkmcnt(0)
	s_setprio 1
	s_waitcnt lgkmcnt(0)
	v_mfma_f32_16x16x32_bf16 v[62:65], v[140:143], v[66:69], v[62:65]
	v_mfma_f32_16x16x32_bf16 v[58:61], v[150:153], v[66:69], v[58:61]
	v_mfma_f32_16x16x32_bf16 v[46:49], v[140:143], v[188:191], v[46:49]
	v_mfma_f32_16x16x32_bf16 v[42:45], v[150:153], v[188:191], v[42:45]
	v_mfma_f32_16x16x32_bf16 v[62:65], v[144:147], v[82:85], v[62:65]
	v_mfma_f32_16x16x32_bf16 v[58:61], v[168:171], v[82:85], v[58:61]
	v_mfma_f32_16x16x32_bf16 v[54:57], v[140:143], v[70:73], v[54:57]
	v_mfma_f32_16x16x32_bf16 v[50:53], v[150:153], v[70:73], v[50:53]
	v_mfma_f32_16x16x32_bf16 v[46:49], v[144:147], v[196:199], v[46:49]
	v_mfma_f32_16x16x32_bf16 v[42:45], v[168:171], v[196:199], v[42:45]
	v_mfma_f32_16x16x32_bf16 v[38:41], v[140:143], v[192:195], v[38:41]
	v_mfma_f32_16x16x32_bf16 v[34:37], v[150:153], v[192:195], v[34:37]
	v_mfma_f32_16x16x32_bf16 v[222:225], v[144:147], v[86:89], v[54:57]
	v_mfma_f32_16x16x32_bf16 v[226:229], v[168:171], v[86:89], v[50:53]
	v_mfma_f32_16x16x32_bf16 v[138:141], v[144:147], v[200:203], v[38:41]
	v_mfma_f32_16x16x32_bf16 v[142:145], v[168:171], v[200:203], v[34:37]
	s_setprio 0
	s_setprio 1
	v_mfma_f32_16x16x32_bf16 v[30:33], v[98:101], v[66:69], v[30:33]
	v_mfma_f32_16x16x32_bf16 v[26:29], v[114:117], v[66:69], v[26:29]
	v_mfma_f32_16x16x32_bf16 v[14:17], v[98:101], v[188:191], v[14:17]
	v_mfma_f32_16x16x32_bf16 v[10:13], v[114:117], v[188:191], v[10:13]
	v_mfma_f32_16x16x32_bf16 v[30:33], v[102:105], v[82:85], v[30:33]
	v_mfma_f32_16x16x32_bf16 v[26:29], v[154:157], v[82:85], v[26:29]
	v_mfma_f32_16x16x32_bf16 v[22:25], v[98:101], v[70:73], v[22:25]
	v_mfma_f32_16x16x32_bf16 v[18:21], v[114:117], v[70:73], v[18:21]
	v_mfma_f32_16x16x32_bf16 v[14:17], v[102:105], v[196:199], v[14:17]
	v_mfma_f32_16x16x32_bf16 v[10:13], v[154:157], v[196:199], v[10:13]
	v_mfma_f32_16x16x32_bf16 v[6:9], v[98:101], v[192:195], v[6:9]
	v_mfma_f32_16x16x32_bf16 v[2:5], v[114:117], v[192:195], v[2:5]
	v_mfma_f32_16x16x32_bf16 v[150:153], v[102:105], v[86:89], v[22:25]
	v_mfma_f32_16x16x32_bf16 v[168:171], v[154:157], v[86:89], v[18:21]
	v_mfma_f32_16x16x32_bf16 v[188:191], v[102:105], v[200:203], v[6:9]
	v_mfma_f32_16x16x32_bf16 v[154:157], v[154:157], v[200:203], v[2:5]
	s_setprio 0
	s_barrier
	s_nop 1
	ds_read_b128 v[2:5], v159
	ds_read_b128 v[6:9], v160
	ds_read_b128 v[158:161], v161
	ds_read_b128 v[192:195], v162
	ds_read_b128 v[18:21], v148 offset:32768
	ds_read_b128 v[22:25], v148 offset:34816
	ds_read_b128 v[34:37], v149 offset:32768
	ds_read_b128 v[38:41], v149 offset:34816
	ds_read_b128 v[50:53], v148 offset:36864
	ds_read_b128 v[54:57], v148 offset:38912
	ds_read_b128 v[196:199], v149 offset:36864
	ds_read_b128 v[200:203], v149 offset:38912
	s_waitcnt vmcnt(2)
	s_barrier
	s_waitcnt lgkmcnt(0)
	s_setprio 1
	s_waitcnt lgkmcnt(0)
	v_mfma_f32_16x16x32_bf16 v[66:69], v[2:5], v[18:21], v[126:129]
	v_mfma_f32_16x16x32_bf16 v[126:129], v[6:9], v[34:37], v[66:69]
	v_mfma_f32_16x16x32_bf16 v[66:69], v[158:161], v[18:21], v[122:125]
	v_mfma_f32_16x16x32_bf16 v[114:117], v[192:195], v[34:37], v[66:69]
	v_mfma_f32_16x16x32_bf16 v[66:69], v[2:5], v[22:25], v[118:121]
	v_mfma_f32_16x16x32_bf16 v[102:105], v[6:9], v[38:41], v[66:69]
	v_mfma_f32_16x16x32_bf16 v[66:69], v[158:161], v[22:25], v[134:137]
	v_mfma_f32_16x16x32_bf16 v[98:101], v[192:195], v[38:41], v[66:69]
	v_mfma_f32_16x16x32_bf16 v[66:69], v[2:5], v[50:53], v[110:113]
	v_mfma_f32_16x16x32_bf16 v[86:89], v[6:9], v[196:199], v[66:69]
	v_mfma_f32_16x16x32_bf16 v[66:69], v[158:161], v[50:53], v[106:109]
	v_mfma_f32_16x16x32_bf16 v[82:85], v[192:195], v[196:199], v[66:69]
	v_mfma_f32_16x16x32_bf16 v[66:69], v[2:5], v[54:57], v[206:209]
	v_mfma_f32_16x16x32_bf16 v[70:73], v[6:9], v[200:203], v[66:69]
	v_mfma_f32_16x16x32_bf16 v[66:69], v[158:161], v[54:57], v[218:221]
	v_mfma_f32_16x16x32_bf16 v[66:69], v[192:195], v[200:203], v[66:69]
	s_setprio 0
	s_barrier
	ds_read_b128 v[134:137], v163
	ds_read_b128 v[206:209], v164
	ds_read_b128 v[162:165], v165
	ds_read_b128 v[218:221], v166
	s_waitcnt vmcnt(0)
	s_barrier
	s_waitcnt lgkmcnt(0)
	s_setprio 1
	s_waitcnt lgkmcnt(0)
	v_mfma_f32_16x16x32_bf16 v[94:97], v[134:137], v[18:21], v[94:97]
	v_mfma_f32_16x16x32_bf16 v[18:21], v[162:165], v[18:21], v[90:93]
	v_mfma_f32_16x16x32_bf16 v[118:121], v[218:221], v[34:37], v[18:21]
	v_mfma_f32_16x16x32_bf16 v[18:21], v[134:137], v[22:25], v[172:175]
	v_mfma_f32_16x16x32_bf16 v[110:113], v[206:209], v[38:41], v[18:21]
	v_mfma_f32_16x16x32_bf16 v[18:21], v[162:165], v[22:25], v[176:179]
	v_mfma_f32_16x16x32_bf16 v[106:109], v[218:221], v[38:41], v[18:21]
	v_mfma_f32_16x16x32_bf16 v[18:21], v[134:137], v[50:53], v[78:81]
	v_mfma_f32_16x16x32_bf16 v[122:125], v[206:209], v[34:37], v[94:97]
	v_mfma_f32_16x16x32_bf16 v[94:97], v[206:209], v[196:199], v[18:21]
	v_mfma_f32_16x16x32_bf16 v[18:21], v[162:165], v[50:53], v[74:77]
	v_mfma_f32_16x16x32_bf16 v[90:93], v[218:221], v[196:199], v[18:21]
	v_mfma_f32_16x16x32_bf16 v[18:21], v[134:137], v[54:57], v[180:183]
	v_mfma_f32_16x16x32_bf16 v[78:81], v[206:209], v[200:203], v[18:21]
	v_mfma_f32_16x16x32_bf16 v[18:21], v[162:165], v[54:57], v[184:187]
	v_mfma_f32_16x16x32_bf16 v[74:77], v[218:221], v[200:203], v[18:21]
	s_setprio 0
	s_barrier
	ds_read_b128 v[172:175], v148 offset:49152
	ds_read_b128 v[176:179], v148 offset:51200
	ds_read_b128 v[180:183], v149 offset:49152
	ds_read_b128 v[184:187], v149 offset:51200
	ds_read_b128 v[196:199], v148 offset:53248
	ds_read_b128 v[200:203], v148 offset:55296
	ds_read_b128 v[230:233], v149 offset:53248
	ds_read_b128 v[146:149], v149 offset:55296
	s_barrier
	s_waitcnt lgkmcnt(0)
	s_setprio 1
	s_waitcnt lgkmcnt(0)
	v_mfma_f32_16x16x32_bf16 v[18:21], v[2:5], v[172:175], v[62:65]
	v_mfma_f32_16x16x32_bf16 v[54:57], v[6:9], v[180:183], v[18:21]
	v_mfma_f32_16x16x32_bf16 v[18:21], v[158:161], v[172:175], v[58:61]
	v_mfma_f32_16x16x32_bf16 v[50:53], v[192:195], v[180:183], v[18:21]
	v_mfma_f32_16x16x32_bf16 v[18:21], v[2:5], v[176:179], v[222:225]
	v_mfma_f32_16x16x32_bf16 v[38:41], v[6:9], v[184:187], v[18:21]
	v_mfma_f32_16x16x32_bf16 v[18:21], v[158:161], v[176:179], v[226:229]
	v_mfma_f32_16x16x32_bf16 v[34:37], v[192:195], v[184:187], v[18:21]
	v_mfma_f32_16x16x32_bf16 v[18:21], v[2:5], v[196:199], v[46:49]
	v_mfma_f32_16x16x32_bf16 v[2:5], v[2:5], v[200:203], v[138:141]
	v_mfma_f32_16x16x32_bf16 v[22:25], v[6:9], v[230:233], v[18:21]
	v_mfma_f32_16x16x32_bf16 v[18:21], v[158:161], v[196:199], v[42:45]
	v_mfma_f32_16x16x32_bf16 v[6:9], v[6:9], v[146:149], v[2:5]
	v_mfma_f32_16x16x32_bf16 v[2:5], v[158:161], v[200:203], v[142:145]
	v_mfma_f32_16x16x32_bf16 v[18:21], v[192:195], v[230:233], v[18:21]
	v_mfma_f32_16x16x32_bf16 v[2:5], v[192:195], v[146:149], v[2:5]
	s_setprio 0
	s_setprio 1
	v_mfma_f32_16x16x32_bf16 v[26:29], v[162:165], v[172:175], v[26:29]
	v_mfma_f32_16x16x32_bf16 v[58:61], v[218:221], v[180:183], v[26:29]
	v_mfma_f32_16x16x32_bf16 v[26:29], v[134:137], v[176:179], v[150:153]
	v_mfma_f32_16x16x32_bf16 v[46:49], v[206:209], v[184:187], v[26:29]
	v_mfma_f32_16x16x32_bf16 v[26:29], v[162:165], v[176:179], v[168:171]
	v_mfma_f32_16x16x32_bf16 v[10:13], v[162:165], v[196:199], v[10:13]
	v_mfma_f32_16x16x32_bf16 v[30:33], v[134:137], v[172:175], v[30:33]
	v_mfma_f32_16x16x32_bf16 v[42:45], v[218:221], v[184:187], v[26:29]
	v_mfma_f32_16x16x32_bf16 v[14:17], v[134:137], v[196:199], v[14:17]
	v_mfma_f32_16x16x32_bf16 v[26:29], v[218:221], v[230:233], v[10:13]
	v_mfma_f32_16x16x32_bf16 v[10:13], v[134:137], v[200:203], v[188:191]
	v_mfma_f32_16x16x32_bf16 v[62:65], v[206:209], v[180:183], v[30:33]
	v_mfma_f32_16x16x32_bf16 v[30:33], v[206:209], v[230:233], v[14:17]
	v_mfma_f32_16x16x32_bf16 v[14:17], v[206:209], v[146:149], v[10:13]
	v_mfma_f32_16x16x32_bf16 v[10:13], v[162:165], v[200:203], v[154:157]
	v_mfma_f32_16x16x32_bf16 v[10:13], v[218:221], v[146:149], v[10:13]
	s_setprio 0
	s_cmpk_gt_u32 s0, 0xff
	s_barrier
	s_cbranch_scc1 .LBB0_90
	s_barrier
	s_branch .LBB0_90

.LBB0_340:
	s_lshl_b32 s19, s19, 5
	v_and_b32_e32 v0, 15, v17
	s_and_b32 s19, s19, 0x60
	v_lshlrev_b32_e32 v19, 7, v0
	v_or_b32_e32 v0, s19, v0
	s_add_i32 s19, s1, 0x18000
	s_mov_b64 s[24:25], 0x80
	v_lshl_or_b32 v19, s20, 13, v19
	v_lshl_add_u64 v[2:3], v[2:3], 0, s[24:25]
	s_mov_b32 m0, s19
	s_add_i32 s20, s1, 0x1a000
	s_waitcnt vmcnt(4)
	s_barrier
	global_load_lds_dwordx4 v[2:3], off
	v_lshl_add_u64 v[2:3], v[4:5], 0, s[24:25]
	s_mov_b32 m0, s20
	s_add_i32 s21, s1, 0x8000
	global_load_lds_dwordx4 v[2:3], off
	v_lshl_add_u64 v[2:3], v[8:9], 0, s[24:25]
	s_mov_b32 m0, s21
	s_add_i32 s22, s1, 0xa000
	global_load_lds_dwordx4 v[2:3], off
	v_lshl_add_u64 v[2:3], v[6:7], 0, s[24:25]
	s_mov_b32 m0, s22
	s_add_i32 s23, s1, 0x1c000
	global_load_lds_dwordx4 v[2:3], off
	v_lshl_add_u64 v[2:3], v[12:13], 0, s[24:25]
	s_mov_b32 m0, s23
	v_and_b32_e32 v20, 3, v18
	global_load_lds_dwordx4 v[2:3], off
	v_lshl_add_u64 v[2:3], v[10:11], 0, s[24:25]
	s_add_i32 s24, s1, 0x1e000
	s_mov_b32 m0, s24
	v_bfe_u32 v17, v17, 1, 3
	global_load_lds_dwordx4 v[2:3], off
	v_bitop3_b32 v18, v18, v17, 3 bitop3:0x6c
	v_bitop3_b32 v17, v20, v17, 4 bitop3:0x36
	v_lshlrev_b32_e32 v18, 4, v18
	v_lshlrev_b32_e32 v17, 4, v17
	v_lshlrev_b32_e32 v0, 7, v0
	v_or_b32_e32 v152, v0, v18
	v_or_b32_e32 v153, v0, v17
	v_add_u32_e32 v0, v16, v14
	s_waitcnt vmcnt(6)
	v_lshlrev_b64 v[2:3], 1, v[0:1]
	v_add_u32_e32 v0, v15, v14
	v_lshl_add_u64 v[140:141], s[12:13], 0, v[2:3]
	v_lshlrev_b64 v[4:5], 1, v[0:1]
	v_lshl_add_u64 v[144:145], s[4:5], 0, v[2:3]
	v_mov_b32_e32 v2, 0
	v_or_b32_e32 v150, v18, v19
	v_or_b32_e32 v151, v17, v19
	v_lshl_add_u64 v[142:143], s[12:13], 0, v[4:5]
	v_lshl_add_u64 v[146:147], s[4:5], 0, v[4:5]
	s_mov_b32 s4, -2
	v_mov_b64_e32 v[148:149], v[132:133]
	v_mov_b32_e32 v3, v2
	v_mov_b32_e32 v4, v2
	v_mov_b32_e32 v5, v2
	v_mov_b32_e32 v6, v2
	v_mov_b32_e32 v7, v2
	v_mov_b32_e32 v8, v2
	v_mov_b32_e32 v9, v2
	v_mov_b32_e32 v10, v2
	v_mov_b32_e32 v11, v2
	v_mov_b32_e32 v12, v2
	v_mov_b32_e32 v13, v2
	v_mov_b32_e32 v14, v2
	v_mov_b32_e32 v15, v2
	v_mov_b32_e32 v16, v2
	v_mov_b32_e32 v17, v2
	v_mov_b32_e32 v18, v2
	v_mov_b32_e32 v19, v2
	v_mov_b32_e32 v20, v2
	v_mov_b32_e32 v21, v2
	v_mov_b32_e32 v22, v2
	v_mov_b32_e32 v23, v2
	v_mov_b32_e32 v24, v2
	v_mov_b32_e32 v25, v2
	v_mov_b32_e32 v26, v2
	v_mov_b32_e32 v27, v2
	v_mov_b32_e32 v28, v2
	v_mov_b32_e32 v29, v2
	v_mov_b32_e32 v30, v2
	v_mov_b32_e32 v31, v2
	v_mov_b32_e32 v32, v2
	v_mov_b32_e32 v33, v2
	v_mov_b32_e32 v34, v2
	v_mov_b32_e32 v35, v2
	v_mov_b32_e32 v36, v2
	v_mov_b32_e32 v37, v2
	v_mov_b32_e32 v38, v2
	v_mov_b32_e32 v39, v2
	v_mov_b32_e32 v40, v2
	v_mov_b32_e32 v41, v2
	v_mov_b32_e32 v42, v2
	v_mov_b32_e32 v43, v2
	v_mov_b32_e32 v44, v2
	v_mov_b32_e32 v45, v2
	v_mov_b32_e32 v46, v2
	v_mov_b32_e32 v47, v2
	v_mov_b32_e32 v48, v2
	v_mov_b32_e32 v49, v2
	v_mov_b32_e32 v50, v2
	v_mov_b32_e32 v51, v2
	v_mov_b32_e32 v52, v2
	v_mov_b32_e32 v53, v2
	v_mov_b32_e32 v54, v2
	v_mov_b32_e32 v55, v2
	v_mov_b32_e32 v56, v2
	v_mov_b32_e32 v57, v2
	v_mov_b32_e32 v58, v2
	v_mov_b32_e32 v59, v2
	v_mov_b32_e32 v60, v2
	v_mov_b32_e32 v61, v2
	v_mov_b32_e32 v62, v2
	v_mov_b32_e32 v63, v2
	v_mov_b32_e32 v64, v2
	v_mov_b32_e32 v65, v2
	v_mov_b32_e32 v66, v2
	v_mov_b32_e32 v67, v2
	v_mov_b32_e32 v68, v2
	v_mov_b32_e32 v69, v2
	v_mov_b32_e32 v70, v2
	v_mov_b32_e32 v71, v2
	v_mov_b32_e32 v72, v2
	v_mov_b32_e32 v73, v2
	v_mov_b32_e32 v74, v2
	v_mov_b32_e32 v75, v2
	v_mov_b32_e32 v76, v2
	v_mov_b32_e32 v77, v2
	v_mov_b32_e32 v78, v2
	v_mov_b32_e32 v79, v2
	v_mov_b32_e32 v80, v2
	v_mov_b32_e32 v81, v2
	v_mov_b32_e32 v82, v2
	v_mov_b32_e32 v83, v2
	v_mov_b32_e32 v84, v2
	v_mov_b32_e32 v85, v2
	v_mov_b32_e32 v86, v2
	v_mov_b32_e32 v87, v2
	v_mov_b32_e32 v88, v2
	v_mov_b32_e32 v89, v2
	v_mov_b32_e32 v90, v2
	v_mov_b32_e32 v91, v2
	v_mov_b32_e32 v92, v2
	v_mov_b32_e32 v93, v2
	v_mov_b32_e32 v94, v2
	v_mov_b32_e32 v95, v2
	v_mov_b32_e32 v96, v2
	v_mov_b32_e32 v97, v2
	v_mov_b32_e32 v98, v2
	v_mov_b32_e32 v99, v2
	v_mov_b32_e32 v100, v2
	v_mov_b32_e32 v101, v2
	v_mov_b32_e32 v102, v2
	v_mov_b32_e32 v103, v2
	v_mov_b32_e32 v104, v2
	v_mov_b32_e32 v105, v2
	v_mov_b32_e32 v106, v2
	v_mov_b32_e32 v107, v2
	v_mov_b32_e32 v108, v2
	v_mov_b32_e32 v109, v2
	v_mov_b32_e32 v110, v2
	v_mov_b32_e32 v111, v2
	v_mov_b32_e32 v112, v2
	v_mov_b32_e32 v113, v2
	v_mov_b32_e32 v114, v2
	v_mov_b32_e32 v115, v2
	v_mov_b32_e32 v116, v2
	v_mov_b32_e32 v117, v2
	v_mov_b32_e32 v118, v2
	v_mov_b32_e32 v119, v2
	v_mov_b32_e32 v120, v2
	v_mov_b32_e32 v121, v2
	v_mov_b32_e32 v122, v2
	v_mov_b32_e32 v123, v2
	v_mov_b32_e32 v124, v2
	v_mov_b32_e32 v125, v2
	v_mov_b32_e32 v126, v2
	v_mov_b32_e32 v127, v2
	v_mov_b32_e32 v128, v2
	v_mov_b32_e32 v129, v2
	s_mov_b64 s[26:27], 0x82d4900
	s_mov_b64 s[28:29], 0x8254980
	s_mov_b64 s[30:31], 0x82d4980
	s_waitcnt lgkmcnt(0)
	s_sub_u32 s100, s100, 0x40000000
	s_subb_u32 s101, s101, 0
	s_mov_b64 vcc, s[100:101]
	v_lshl_add_u64 v[202:203], v[148:149], 0, v[142:143]
	v_subrev_u32_e32 v202, vcc_lo, v202
	v_lshl_add_u64 v[206:207], v[148:149], 0, v[140:141]
	v_subrev_u32_e32 v206, vcc_lo, v206
	v_lshl_add_u64 v[208:209], v[148:149], 0, v[146:147]
	v_subrev_u32_e32 v208, vcc_lo, v208
	v_lshl_add_u64 v[210:211], v[148:149], 0, v[144:145]
	v_subrev_u32_e32 v210, vcc_lo, v210
	v_add_u32_e32 v203, 0x10000, v152
	v_add_u32_e32 v207, 0x10000, v153
	v_add_u32_e32 v0, s50, v202
	v_add_u32_e32 v154, s54, v202
	v_add_u32_e32 v155, s58, v202
	v_add_u32_e32 v202, s62, v202
	v_add_u32_e32 v156, s50, v206
	v_add_u32_e32 v157, s54, v206
	v_add_u32_e32 v158, s58, v206
	v_add_u32_e32 v206, s62, v206
	v_add_u32_e32 v159, s70, v208
	v_add_u32_e32 v160, s26, v208
	v_add_u32_e32 v161, s28, v208
	v_add_u32_e32 v208, s30, v208
	v_add_u32_e32 v209, s70, v210
	v_add_u32_e32 v211, s26, v210
	v_add_u32_e32 v214, s28, v210
	v_add_u32_e32 v210, s30, v210
	s_add_i32 s12, s1, 0xc000
	s_add_i32 s5, s1, 0xe000
	s_barrier
.LBB0_341:
	ds_read_b128 v[162:165], v203
	ds_read_b128 v[166:169], v207
	ds_read_b128 v[170:173], v203 offset:2048
	ds_read_b128 v[174:177], v207 offset:2048
	ds_read_b128 v[178:181], v150
	ds_read_b128 v[182:185], v150 offset:2048
	ds_read_b128 v[186:189], v151
	ds_read_b128 v[190:193], v151 offset:2048
	ds_read_b128 v[194:197], v150 offset:4096
	ds_read_b128 v[198:201], v150 offset:6144
	s_mov_b32 m0, s12
	ds_read_b128 v[218:221], v151 offset:4096
	global_load_lds_dwordx4 v0, vcc
	s_mov_b32 m0, s5
	ds_read_b128 v[222:225], v151 offset:6144
	global_load_lds_dwordx4 v156, vcc
	s_waitcnt vmcnt(10) lgkmcnt(8)
	s_barrier
	s_waitcnt lgkmcnt(0)
	v_mfma_f32_16x16x32_bf16 v[126:129], v[178:181], v[162:165], v[126:129]
	v_mfma_f32_16x16x32_bf16 v[122:125], v[178:181], v[170:173], v[122:125]
	v_mfma_f32_16x16x32_bf16 v[118:121], v[182:185], v[162:165], v[118:121]
	v_mfma_f32_16x16x32_bf16 v[114:117], v[182:185], v[170:173], v[114:117]
	v_mfma_f32_16x16x32_bf16 v[110:113], v[194:197], v[162:165], v[110:113]
	v_mfma_f32_16x16x32_bf16 v[106:109], v[194:197], v[170:173], v[106:109]
	v_mfma_f32_16x16x32_bf16 v[102:105], v[198:201], v[162:165], v[102:105]
	v_mfma_f32_16x16x32_bf16 v[98:101], v[198:201], v[170:173], v[98:101]
	v_mfma_f32_16x16x32_bf16 v[126:129], v[186:189], v[166:169], v[126:129]
	v_mfma_f32_16x16x32_bf16 v[122:125], v[186:189], v[174:177], v[122:125]
	v_mfma_f32_16x16x32_bf16 v[118:121], v[190:193], v[166:169], v[118:121]
	v_mfma_f32_16x16x32_bf16 v[114:117], v[190:193], v[174:177], v[114:117]
	v_mfma_f32_16x16x32_bf16 v[110:113], v[218:221], v[166:169], v[110:113]
	v_mfma_f32_16x16x32_bf16 v[106:109], v[218:221], v[174:177], v[106:109]
	v_mfma_f32_16x16x32_bf16 v[102:105], v[222:225], v[166:169], v[102:105]
	v_mfma_f32_16x16x32_bf16 v[98:101], v[222:225], v[174:177], v[98:101]
	s_barrier
	ds_read_b128 v[226:229], v203 offset:16384
	ds_read_b128 v[230:233], v207 offset:16384
	s_mov_b32 m0, s2
	ds_read_b128 v[234:237], v203 offset:18432
	global_load_lds_dwordx4 v159, vcc
	s_mov_b32 m0, s3
	ds_read_b128 v[238:241], v207 offset:18432
	global_load_lds_dwordx4 v209, vcc
	s_waitcnt vmcnt(10) lgkmcnt(0)
	s_barrier
	v_mfma_f32_16x16x32_bf16 v[94:97], v[178:181], v[226:229], v[94:97]
	v_mfma_f32_16x16x32_bf16 v[90:93], v[178:181], v[234:237], v[90:93]
	v_mfma_f32_16x16x32_bf16 v[86:89], v[182:185], v[226:229], v[86:89]
	v_mfma_f32_16x16x32_bf16 v[82:85], v[182:185], v[234:237], v[82:85]
	v_mfma_f32_16x16x32_bf16 v[78:81], v[194:197], v[226:229], v[78:81]
	v_mfma_f32_16x16x32_bf16 v[74:77], v[194:197], v[234:237], v[74:77]
	v_mfma_f32_16x16x32_bf16 v[70:73], v[198:201], v[226:229], v[70:73]
	v_mfma_f32_16x16x32_bf16 v[66:69], v[198:201], v[234:237], v[66:69]
	v_mfma_f32_16x16x32_bf16 v[94:97], v[186:189], v[230:233], v[94:97]
	v_mfma_f32_16x16x32_bf16 v[90:93], v[186:189], v[238:241], v[90:93]
	v_mfma_f32_16x16x32_bf16 v[86:89], v[190:193], v[230:233], v[86:89]
	v_mfma_f32_16x16x32_bf16 v[82:85], v[190:193], v[238:241], v[82:85]
	v_mfma_f32_16x16x32_bf16 v[78:81], v[218:221], v[230:233], v[78:81]
	v_mfma_f32_16x16x32_bf16 v[74:77], v[218:221], v[238:241], v[74:77]
	v_mfma_f32_16x16x32_bf16 v[70:73], v[222:225], v[230:233], v[70:73]
	v_mfma_f32_16x16x32_bf16 v[66:69], v[222:225], v[238:241], v[66:69]
	s_barrier
	ds_read_b128 v[178:181], v150 offset:16384
	ds_read_b128 v[182:185], v150 offset:18432
	ds_read_b128 v[186:189], v151 offset:16384
	ds_read_b128 v[190:193], v151 offset:18432
	s_mov_b32 m0, s1
	ds_read_b128 v[194:197], v150 offset:20480
	global_load_lds_dwordx4 v154, vcc
	s_mov_b32 m0, s9
	ds_read_b128 v[198:201], v150 offset:22528
	global_load_lds_dwordx4 v157, vcc
	s_mov_b32 m0, s11
	ds_read_b128 v[218:221], v151 offset:20480
	global_load_lds_dwordx4 v160, vcc
	s_mov_b32 m0, s16
	ds_read_b128 v[222:225], v151 offset:22528
	global_load_lds_dwordx4 v211, vcc
	s_waitcnt vmcnt(10) lgkmcnt(0)
	s_barrier
	v_mfma_f32_16x16x32_bf16 v[62:65], v[178:181], v[162:165], v[62:65]
	v_mfma_f32_16x16x32_bf16 v[58:61], v[178:181], v[170:173], v[58:61]
	v_mfma_f32_16x16x32_bf16 v[54:57], v[182:185], v[162:165], v[54:57]
	v_mfma_f32_16x16x32_bf16 v[50:53], v[182:185], v[170:173], v[50:53]
	v_mfma_f32_16x16x32_bf16 v[46:49], v[194:197], v[162:165], v[46:49]
	v_mfma_f32_16x16x32_bf16 v[42:45], v[194:197], v[170:173], v[42:45]
	v_mfma_f32_16x16x32_bf16 v[38:41], v[198:201], v[162:165], v[38:41]
	v_mfma_f32_16x16x32_bf16 v[34:37], v[198:201], v[170:173], v[34:37]
	v_mfma_f32_16x16x32_bf16 v[62:65], v[186:189], v[166:169], v[62:65]
	v_mfma_f32_16x16x32_bf16 v[58:61], v[186:189], v[174:177], v[58:61]
	v_mfma_f32_16x16x32_bf16 v[54:57], v[190:193], v[166:169], v[54:57]
	v_mfma_f32_16x16x32_bf16 v[50:53], v[190:193], v[174:177], v[50:53]
	v_mfma_f32_16x16x32_bf16 v[46:49], v[218:221], v[166:169], v[46:49]
	v_mfma_f32_16x16x32_bf16 v[42:45], v[218:221], v[174:177], v[42:45]
	v_mfma_f32_16x16x32_bf16 v[38:41], v[222:225], v[166:169], v[38:41]
	v_mfma_f32_16x16x32_bf16 v[34:37], v[222:225], v[174:177], v[34:37]
	v_mfma_f32_16x16x32_bf16 v[30:33], v[178:181], v[226:229], v[30:33]
	v_mfma_f32_16x16x32_bf16 v[26:29], v[178:181], v[234:237], v[26:29]
	v_mfma_f32_16x16x32_bf16 v[22:25], v[182:185], v[226:229], v[22:25]
	v_mfma_f32_16x16x32_bf16 v[18:21], v[182:185], v[234:237], v[18:21]
	v_mfma_f32_16x16x32_bf16 v[14:17], v[194:197], v[226:229], v[14:17]
	v_mfma_f32_16x16x32_bf16 v[10:13], v[194:197], v[234:237], v[10:13]
	v_mfma_f32_16x16x32_bf16 v[6:9], v[198:201], v[226:229], v[6:9]
	v_mfma_f32_16x16x32_bf16 v[2:5], v[198:201], v[234:237], v[2:5]
	v_mfma_f32_16x16x32_bf16 v[30:33], v[186:189], v[230:233], v[30:33]
	v_mfma_f32_16x16x32_bf16 v[26:29], v[186:189], v[238:241], v[26:29]
	v_mfma_f32_16x16x32_bf16 v[22:25], v[190:193], v[230:233], v[22:25]
	v_mfma_f32_16x16x32_bf16 v[18:21], v[190:193], v[238:241], v[18:21]
	v_mfma_f32_16x16x32_bf16 v[14:17], v[218:221], v[230:233], v[14:17]
	v_mfma_f32_16x16x32_bf16 v[10:13], v[218:221], v[238:241], v[10:13]
	v_mfma_f32_16x16x32_bf16 v[6:9], v[222:225], v[230:233], v[6:9]
	v_mfma_f32_16x16x32_bf16 v[2:5], v[222:225], v[238:241], v[2:5]
	s_barrier
	ds_read_b128 v[170:173], v203 offset:32768
	ds_read_b128 v[174:177], v207 offset:32768
	ds_read_b128 v[178:181], v203 offset:34816
	ds_read_b128 v[182:185], v207 offset:34816
	ds_read_b128 v[186:189], v150 offset:32768
	ds_read_b128 v[190:193], v150 offset:34816
	ds_read_b128 v[194:197], v151 offset:32768
	ds_read_b128 v[198:201], v151 offset:34816
	ds_read_b128 v[218:221], v150 offset:36864
	ds_read_b128 v[222:225], v150 offset:38912
	s_mov_b32 m0, s17
	ds_read_b128 v[226:229], v151 offset:36864
	global_load_lds_dwordx4 v155, vcc
	s_mov_b32 m0, s18
	ds_read_b128 v[230:233], v151 offset:38912
	global_load_lds_dwordx4 v158, vcc
	s_waitcnt vmcnt(10) lgkmcnt(8)
	s_barrier
	s_waitcnt lgkmcnt(0)
	v_mfma_f32_16x16x32_bf16 v[126:129], v[186:189], v[170:173], v[126:129]
	v_mfma_f32_16x16x32_bf16 v[122:125], v[186:189], v[178:181], v[122:125]
	v_mfma_f32_16x16x32_bf16 v[118:121], v[190:193], v[170:173], v[118:121]
	v_mfma_f32_16x16x32_bf16 v[114:117], v[190:193], v[178:181], v[114:117]
	v_mfma_f32_16x16x32_bf16 v[110:113], v[218:221], v[170:173], v[110:113]
	v_mfma_f32_16x16x32_bf16 v[106:109], v[218:221], v[178:181], v[106:109]
	v_mfma_f32_16x16x32_bf16 v[102:105], v[222:225], v[170:173], v[102:105]
	v_mfma_f32_16x16x32_bf16 v[98:101], v[222:225], v[178:181], v[98:101]
	v_mfma_f32_16x16x32_bf16 v[126:129], v[194:197], v[174:177], v[126:129]
	v_mfma_f32_16x16x32_bf16 v[122:125], v[194:197], v[182:185], v[122:125]
	v_mfma_f32_16x16x32_bf16 v[118:121], v[198:201], v[174:177], v[118:121]
	v_mfma_f32_16x16x32_bf16 v[114:117], v[198:201], v[182:185], v[114:117]
	v_mfma_f32_16x16x32_bf16 v[110:113], v[226:229], v[174:177], v[110:113]
	v_mfma_f32_16x16x32_bf16 v[106:109], v[226:229], v[182:185], v[106:109]
	v_mfma_f32_16x16x32_bf16 v[102:105], v[230:233], v[174:177], v[102:105]
	v_mfma_f32_16x16x32_bf16 v[98:101], v[230:233], v[182:185], v[98:101]
	s_barrier
	ds_read_b128 v[234:237], v203 offset:49152
	ds_read_b128 v[238:241], v207 offset:49152
	s_mov_b32 m0, s19
	ds_read_b128 v[242:245], v203 offset:51200
	global_load_lds_dwordx4 v161, vcc
	s_mov_b32 m0, s20
	ds_read_b128 v[246:249], v207 offset:51200
	global_load_lds_dwordx4 v214, vcc
	s_waitcnt vmcnt(10) lgkmcnt(0)
	s_barrier
	v_mfma_f32_16x16x32_bf16 v[94:97], v[186:189], v[234:237], v[94:97]
	v_mfma_f32_16x16x32_bf16 v[90:93], v[186:189], v[242:245], v[90:93]
	v_mfma_f32_16x16x32_bf16 v[86:89], v[190:193], v[234:237], v[86:89]
	v_mfma_f32_16x16x32_bf16 v[82:85], v[190:193], v[242:245], v[82:85]
	v_mfma_f32_16x16x32_bf16 v[78:81], v[218:221], v[234:237], v[78:81]
	v_mfma_f32_16x16x32_bf16 v[74:77], v[218:221], v[242:245], v[74:77]
	v_mfma_f32_16x16x32_bf16 v[70:73], v[222:225], v[234:237], v[70:73]
	v_mfma_f32_16x16x32_bf16 v[66:69], v[222:225], v[242:245], v[66:69]
	v_mfma_f32_16x16x32_bf16 v[94:97], v[194:197], v[238:241], v[94:97]
	v_mfma_f32_16x16x32_bf16 v[90:93], v[194:197], v[246:249], v[90:93]
	v_mfma_f32_16x16x32_bf16 v[86:89], v[198:201], v[238:241], v[86:89]
	v_mfma_f32_16x16x32_bf16 v[82:85], v[198:201], v[246:249], v[82:85]
	v_mfma_f32_16x16x32_bf16 v[78:81], v[226:229], v[238:241], v[78:81]
	v_mfma_f32_16x16x32_bf16 v[74:77], v[226:229], v[246:249], v[74:77]
	v_mfma_f32_16x16x32_bf16 v[70:73], v[230:233], v[238:241], v[70:73]
	v_mfma_f32_16x16x32_bf16 v[66:69], v[230:233], v[246:249], v[66:69]
	s_barrier
	ds_read_b128 v[186:189], v150 offset:49152
	ds_read_b128 v[190:193], v150 offset:51200
	ds_read_b128 v[194:197], v151 offset:49152
	ds_read_b128 v[198:201], v151 offset:51200
	s_mov_b32 m0, s21
	ds_read_b128 v[218:221], v150 offset:53248
	global_load_lds_dwordx4 v202, vcc
	s_mov_b32 m0, s22
	ds_read_b128 v[222:225], v150 offset:55296
	global_load_lds_dwordx4 v206, vcc
	s_mov_b32 m0, s23
	ds_read_b128 v[226:229], v151 offset:53248
	global_load_lds_dwordx4 v208, vcc
	s_mov_b32 m0, s24
	ds_read_b128 v[230:233], v151 offset:55296
	global_load_lds_dwordx4 v210, vcc
	s_waitcnt vmcnt(10) lgkmcnt(0)
	s_barrier
	v_mfma_f32_16x16x32_bf16 v[62:65], v[186:189], v[170:173], v[62:65]
	v_mfma_f32_16x16x32_bf16 v[58:61], v[186:189], v[178:181], v[58:61]
	v_mfma_f32_16x16x32_bf16 v[54:57], v[190:193], v[170:173], v[54:57]
	v_mfma_f32_16x16x32_bf16 v[50:53], v[190:193], v[178:181], v[50:53]
	v_mfma_f32_16x16x32_bf16 v[46:49], v[218:221], v[170:173], v[46:49]
	v_mfma_f32_16x16x32_bf16 v[42:45], v[218:221], v[178:181], v[42:45]
	v_mfma_f32_16x16x32_bf16 v[38:41], v[222:225], v[170:173], v[38:41]
	v_mfma_f32_16x16x32_bf16 v[34:37], v[222:225], v[178:181], v[34:37]
	v_mfma_f32_16x16x32_bf16 v[62:65], v[194:197], v[174:177], v[62:65]
	v_mfma_f32_16x16x32_bf16 v[58:61], v[194:197], v[182:185], v[58:61]
	v_mfma_f32_16x16x32_bf16 v[54:57], v[198:201], v[174:177], v[54:57]
	v_mfma_f32_16x16x32_bf16 v[50:53], v[198:201], v[182:185], v[50:53]
	v_mfma_f32_16x16x32_bf16 v[46:49], v[226:229], v[174:177], v[46:49]
	v_mfma_f32_16x16x32_bf16 v[42:45], v[226:229], v[182:185], v[42:45]
	v_mfma_f32_16x16x32_bf16 v[38:41], v[230:233], v[174:177], v[38:41]
	v_mfma_f32_16x16x32_bf16 v[34:37], v[230:233], v[182:185], v[34:37]
	v_mfma_f32_16x16x32_bf16 v[30:33], v[186:189], v[234:237], v[30:33]
	v_mfma_f32_16x16x32_bf16 v[26:29], v[186:189], v[242:245], v[26:29]
	v_mfma_f32_16x16x32_bf16 v[22:25], v[190:193], v[234:237], v[22:25]
	v_mfma_f32_16x16x32_bf16 v[18:21], v[190:193], v[242:245], v[18:21]
	v_mfma_f32_16x16x32_bf16 v[14:17], v[218:221], v[234:237], v[14:17]
	v_mfma_f32_16x16x32_bf16 v[10:13], v[218:221], v[242:245], v[10:13]
	v_mfma_f32_16x16x32_bf16 v[6:9], v[222:225], v[234:237], v[6:9]
	v_mfma_f32_16x16x32_bf16 v[2:5], v[222:225], v[242:245], v[2:5]
	v_mfma_f32_16x16x32_bf16 v[30:33], v[194:197], v[238:241], v[30:33]
	v_mfma_f32_16x16x32_bf16 v[26:29], v[194:197], v[246:249], v[26:29]
	v_mfma_f32_16x16x32_bf16 v[22:25], v[198:201], v[238:241], v[22:25]
	v_mfma_f32_16x16x32_bf16 v[18:21], v[198:201], v[246:249], v[18:21]
	v_mfma_f32_16x16x32_bf16 v[14:17], v[226:229], v[238:241], v[14:17]
	v_mfma_f32_16x16x32_bf16 v[10:13], v[226:229], v[246:249], v[10:13]
	v_mfma_f32_16x16x32_bf16 v[6:9], v[230:233], v[238:241], v[6:9]
	v_mfma_f32_16x16x32_bf16 v[2:5], v[230:233], v[246:249], v[2:5]
	s_add_u32 vcc_lo, vcc_lo, s54
	s_addc_u32 vcc_hi, vcc_hi, s55
	s_add_i32 s4, s4, 2
	s_cmp_lt_u32 s4, 28
	v_lshl_add_u64 v[148:149], v[148:149], 0, s[54:55]
	s_barrier
	s_cbranch_scc1 .LBB0_341
	s_waitcnt vmcnt(6)
	v_or_b32_e32 v0, 0x10000, v152
	v_add_u32_e32 v155, 0x10800, v152
	v_or_b32_e32 v154, 0x10000, v153
	v_add_u32_e32 v156, 0x10800, v153
	v_or_b32_e32 v157, 0x14000, v152
	v_add_u32_e32 v159, 0x14800, v152
	v_or_b32_e32 v158, 0x14000, v153
	v_add_u32_e32 v160, 0x14800, v153
	v_or_b32_e32 v161, 0x18000, v152
	v_add_u32_e32 v163, 0x18800, v152
	v_or_b32_e32 v162, 0x18000, v153
	v_add_u32_e32 v164, 0x18800, v153
	v_or_b32_e32 v165, 0x1c000, v152
	v_add_u32_e32 v167, 0x1c800, v152
	v_or_b32_e32 v166, 0x1c000, v153
	v_add_u32_e32 v168, 0x1c800, v153
	s_mov_b64 s[2:3], 0xf80
	s_mov_b32 m0, s12
	v_lshl_add_u64 v[138:139], v[138:139], 0, s[2:3]
	ds_read_b128 v[140:143], v0
	ds_read_b128 v[144:147], v154
	ds_read_b128 v[152:155], v155
	ds_read_b128 v[170:173], v156
	ds_read_b128 v[174:177], v150
	ds_read_b128 v[178:181], v150 offset:2048
	ds_read_b128 v[182:185], v151
	ds_read_b128 v[186:189], v151 offset:2048
	ds_read_b128 v[190:193], v150 offset:4096
	ds_read_b128 v[194:197], v150 offset:6144
	ds_read_b128 v[198:201], v151 offset:4096
	ds_read_b128 v[218:221], v151 offset:6144
	global_load_lds_dwordx4 v[138:139], off
	v_lshl_add_u64 v[136:137], v[136:137], 0, s[2:3]
	s_mov_b32 m0, s5
	s_nop 0
	global_load_lds_dwordx4 v[136:137], off
	s_barrier
	s_waitcnt lgkmcnt(0)
	s_setprio 1
	s_waitcnt lgkmcnt(0)
	v_mfma_f32_16x16x32_bf16 v[126:129], v[174:177], v[140:143], v[126:129]
	v_mfma_f32_16x16x32_bf16 v[114:117], v[178:181], v[152:155], v[114:117]
	v_mfma_f32_16x16x32_bf16 v[110:113], v[190:193], v[140:143], v[110:113]
	v_mfma_f32_16x16x32_bf16 v[106:109], v[190:193], v[152:155], v[106:109]
	v_mfma_f32_16x16x32_bf16 v[126:129], v[182:185], v[144:147], v[126:129]
	v_mfma_f32_16x16x32_bf16 v[122:125], v[174:177], v[152:155], v[122:125]
	v_mfma_f32_16x16x32_bf16 v[118:121], v[178:181], v[140:143], v[118:121]
	v_mfma_f32_16x16x32_bf16 v[114:117], v[186:189], v[170:173], v[114:117]
	v_mfma_f32_16x16x32_bf16 v[110:113], v[198:201], v[144:147], v[110:113]
	v_mfma_f32_16x16x32_bf16 v[106:109], v[198:201], v[170:173], v[106:109]
	v_mfma_f32_16x16x32_bf16 v[102:105], v[194:197], v[140:143], v[102:105]
	v_mfma_f32_16x16x32_bf16 v[98:101], v[194:197], v[152:155], v[98:101]
	v_mfma_f32_16x16x32_bf16 v[136:139], v[182:185], v[170:173], v[122:125]
	v_mfma_f32_16x16x32_bf16 v[222:225], v[186:189], v[144:147], v[118:121]
	v_mfma_f32_16x16x32_bf16 v[226:229], v[218:221], v[144:147], v[102:105]
	v_mfma_f32_16x16x32_bf16 v[230:233], v[218:221], v[170:173], v[98:101]
	s_setprio 0
	s_barrier
	s_nop 1
	ds_read_b128 v[98:101], v157
	ds_read_b128 v[102:105], v158
	ds_read_b128 v[118:121], v159
	ds_read_b128 v[122:125], v160
	s_barrier
	s_waitcnt lgkmcnt(0)
	s_setprio 1
	s_waitcnt lgkmcnt(0)
	v_mfma_f32_16x16x32_bf16 v[94:97], v[174:177], v[98:101], v[94:97]
	v_mfma_f32_16x16x32_bf16 v[90:93], v[174:177], v[118:121], v[90:93]
	v_mfma_f32_16x16x32_bf16 v[78:81], v[190:193], v[98:101], v[78:81]
	v_mfma_f32_16x16x32_bf16 v[74:77], v[190:193], v[118:121], v[74:77]
	v_mfma_f32_16x16x32_bf16 v[94:97], v[182:185], v[102:105], v[94:97]
	v_mfma_f32_16x16x32_bf16 v[90:93], v[182:185], v[122:125], v[90:93]
	v_mfma_f32_16x16x32_bf16 v[86:89], v[178:181], v[98:101], v[86:89]
	v_mfma_f32_16x16x32_bf16 v[82:85], v[178:181], v[118:121], v[82:85]
	v_mfma_f32_16x16x32_bf16 v[78:81], v[198:201], v[102:105], v[78:81]
	v_mfma_f32_16x16x32_bf16 v[74:77], v[198:201], v[122:125], v[74:77]
	v_mfma_f32_16x16x32_bf16 v[70:73], v[194:197], v[98:101], v[70:73]
	v_mfma_f32_16x16x32_bf16 v[66:69], v[194:197], v[118:121], v[66:69]
	v_mfma_f32_16x16x32_bf16 v[156:159], v[186:189], v[102:105], v[86:89]
	v_mfma_f32_16x16x32_bf16 v[174:177], v[186:189], v[122:125], v[82:85]
	v_mfma_f32_16x16x32_bf16 v[178:181], v[218:221], v[102:105], v[70:73]
	v_mfma_f32_16x16x32_bf16 v[182:185], v[218:221], v[122:125], v[66:69]
	s_setprio 0
	s_barrier
	s_nop 1
	ds_read_b128 v[66:69], v150 offset:16384
	ds_read_b128 v[70:73], v150 offset:18432
	ds_read_b128 v[82:85], v151 offset:16384
	ds_read_b128 v[86:89], v151 offset:18432
	ds_read_b128 v[186:189], v150 offset:20480
	ds_read_b128 v[190:193], v150 offset:22528
	ds_read_b128 v[194:197], v151 offset:20480
	ds_read_b128 v[198:201], v151 offset:22528
	s_waitcnt vmcnt(4)
	s_barrier
	s_waitcnt lgkmcnt(0)
	s_setprio 1
	s_waitcnt lgkmcnt(0)
	v_mfma_f32_16x16x32_bf16 v[62:65], v[66:69], v[140:143], v[62:65]
	v_mfma_f32_16x16x32_bf16 v[54:57], v[70:73], v[140:143], v[54:57]
	v_mfma_f32_16x16x32_bf16 v[46:49], v[186:189], v[140:143], v[46:49]
	v_mfma_f32_16x16x32_bf16 v[38:41], v[190:193], v[140:143], v[38:41]
	v_mfma_f32_16x16x32_bf16 v[62:65], v[82:85], v[144:147], v[62:65]
	v_mfma_f32_16x16x32_bf16 v[58:61], v[66:69], v[152:155], v[58:61]
	v_mfma_f32_16x16x32_bf16 v[54:57], v[86:89], v[144:147], v[54:57]
	v_mfma_f32_16x16x32_bf16 v[50:53], v[70:73], v[152:155], v[50:53]
	v_mfma_f32_16x16x32_bf16 v[46:49], v[194:197], v[144:147], v[46:49]
	v_mfma_f32_16x16x32_bf16 v[42:45], v[186:189], v[152:155], v[42:45]
	v_mfma_f32_16x16x32_bf16 v[38:41], v[198:201], v[144:147], v[38:41]
	v_mfma_f32_16x16x32_bf16 v[34:37], v[190:193], v[152:155], v[34:37]
	v_mfma_f32_16x16x32_bf16 v[218:221], v[82:85], v[170:173], v[58:61]
	v_mfma_f32_16x16x32_bf16 v[234:237], v[86:89], v[170:173], v[50:53]
	v_mfma_f32_16x16x32_bf16 v[238:241], v[194:197], v[170:173], v[42:45]
	v_mfma_f32_16x16x32_bf16 v[140:143], v[198:201], v[170:173], v[34:37]
	s_setprio 0
	s_setprio 1
	v_mfma_f32_16x16x32_bf16 v[30:33], v[66:69], v[98:101], v[30:33]
	v_mfma_f32_16x16x32_bf16 v[22:25], v[70:73], v[98:101], v[22:25]
	v_mfma_f32_16x16x32_bf16 v[14:17], v[186:189], v[98:101], v[14:17]
	v_mfma_f32_16x16x32_bf16 v[6:9], v[190:193], v[98:101], v[6:9]
	v_mfma_f32_16x16x32_bf16 v[30:33], v[82:85], v[102:105], v[30:33]
	v_mfma_f32_16x16x32_bf16 v[26:29], v[66:69], v[118:121], v[26:29]
	v_mfma_f32_16x16x32_bf16 v[22:25], v[86:89], v[102:105], v[22:25]
	v_mfma_f32_16x16x32_bf16 v[18:21], v[70:73], v[118:121], v[18:21]
	v_mfma_f32_16x16x32_bf16 v[14:17], v[194:197], v[102:105], v[14:17]
	v_mfma_f32_16x16x32_bf16 v[10:13], v[186:189], v[118:121], v[10:13]
	v_mfma_f32_16x16x32_bf16 v[6:9], v[198:201], v[102:105], v[6:9]
	v_mfma_f32_16x16x32_bf16 v[2:5], v[190:193], v[118:121], v[2:5]
	v_mfma_f32_16x16x32_bf16 v[144:147], v[82:85], v[122:125], v[26:29]
	v_mfma_f32_16x16x32_bf16 v[152:155], v[86:89], v[122:125], v[18:21]
	v_mfma_f32_16x16x32_bf16 v[170:173], v[194:197], v[122:125], v[10:13]
	v_mfma_f32_16x16x32_bf16 v[186:189], v[198:201], v[122:125], v[2:5]
	s_setprio 0
	s_barrier
	s_nop 1
	ds_read_b128 v[2:5], v161
	ds_read_b128 v[10:13], v162
	ds_read_b128 v[160:163], v163
	ds_read_b128 v[190:193], v164
	ds_read_b128 v[18:21], v150 offset:32768
	ds_read_b128 v[26:29], v150 offset:34816
	ds_read_b128 v[34:37], v151 offset:32768
	ds_read_b128 v[42:45], v151 offset:34816
	ds_read_b128 v[50:53], v150 offset:36864
	ds_read_b128 v[58:61], v150 offset:38912
	ds_read_b128 v[194:197], v151 offset:36864
	ds_read_b128 v[198:201], v151 offset:38912
	s_waitcnt vmcnt(2)
	s_barrier
	s_waitcnt lgkmcnt(0)
	s_setprio 1
	s_waitcnt lgkmcnt(0)
	v_mfma_f32_16x16x32_bf16 v[66:69], v[18:21], v[2:5], v[126:129]
	v_mfma_f32_16x16x32_bf16 v[122:125], v[34:37], v[10:13], v[66:69]
	v_mfma_f32_16x16x32_bf16 v[66:69], v[18:21], v[160:163], v[136:139]
	v_mfma_f32_16x16x32_bf16 v[118:121], v[34:37], v[190:193], v[66:69]
	v_mfma_f32_16x16x32_bf16 v[66:69], v[26:29], v[2:5], v[222:225]
	v_mfma_f32_16x16x32_bf16 v[102:105], v[42:45], v[10:13], v[66:69]
	v_mfma_f32_16x16x32_bf16 v[66:69], v[26:29], v[160:163], v[114:117]
	v_mfma_f32_16x16x32_bf16 v[98:101], v[42:45], v[190:193], v[66:69]
	v_mfma_f32_16x16x32_bf16 v[66:69], v[50:53], v[2:5], v[110:113]
	v_mfma_f32_16x16x32_bf16 v[86:89], v[194:197], v[10:13], v[66:69]
	v_mfma_f32_16x16x32_bf16 v[66:69], v[50:53], v[160:163], v[106:109]
	v_mfma_f32_16x16x32_bf16 v[82:85], v[194:197], v[190:193], v[66:69]
	v_mfma_f32_16x16x32_bf16 v[66:69], v[58:61], v[2:5], v[226:229]
	v_mfma_f32_16x16x32_bf16 v[70:73], v[198:201], v[10:13], v[66:69]
	v_mfma_f32_16x16x32_bf16 v[66:69], v[58:61], v[160:163], v[230:233]
	v_mfma_f32_16x16x32_bf16 v[66:69], v[198:201], v[190:193], v[66:69]
	s_setprio 0
	s_barrier
	ds_read_b128 v[136:139], v165
	ds_read_b128 v[222:225], v166
	ds_read_b128 v[164:167], v167
	ds_read_b128 v[226:229], v168
	s_waitcnt vmcnt(0)
	s_barrier
	s_waitcnt lgkmcnt(0)
	s_setprio 1
	s_waitcnt lgkmcnt(0)
	v_mfma_f32_16x16x32_bf16 v[94:97], v[18:21], v[136:139], v[94:97]
	v_mfma_f32_16x16x32_bf16 v[18:21], v[18:21], v[164:167], v[90:93]
	v_mfma_f32_16x16x32_bf16 v[114:117], v[34:37], v[226:229], v[18:21]
	v_mfma_f32_16x16x32_bf16 v[18:21], v[26:29], v[136:139], v[156:159]
	v_mfma_f32_16x16x32_bf16 v[110:113], v[42:45], v[222:225], v[18:21]
	v_mfma_f32_16x16x32_bf16 v[18:21], v[26:29], v[164:167], v[174:177]
	v_mfma_f32_16x16x32_bf16 v[106:109], v[42:45], v[226:229], v[18:21]
	v_mfma_f32_16x16x32_bf16 v[18:21], v[50:53], v[136:139], v[78:81]
	v_mfma_f32_16x16x32_bf16 v[126:129], v[34:37], v[222:225], v[94:97]
	v_mfma_f32_16x16x32_bf16 v[94:97], v[194:197], v[222:225], v[18:21]
	v_mfma_f32_16x16x32_bf16 v[18:21], v[50:53], v[164:167], v[74:77]
	v_mfma_f32_16x16x32_bf16 v[90:93], v[194:197], v[226:229], v[18:21]
	v_mfma_f32_16x16x32_bf16 v[18:21], v[58:61], v[136:139], v[178:181]
	v_mfma_f32_16x16x32_bf16 v[78:81], v[198:201], v[222:225], v[18:21]
	v_mfma_f32_16x16x32_bf16 v[18:21], v[58:61], v[164:167], v[182:185]
	v_mfma_f32_16x16x32_bf16 v[74:77], v[198:201], v[226:229], v[18:21]
	s_setprio 0
	s_barrier
	ds_read_b128 v[156:159], v150 offset:49152
	ds_read_b128 v[174:177], v150 offset:51200
	ds_read_b128 v[178:181], v151 offset:49152
	ds_read_b128 v[182:185], v151 offset:51200
	ds_read_b128 v[194:197], v150 offset:53248
	ds_read_b128 v[198:201], v150 offset:55296
	ds_read_b128 v[230:233], v151 offset:53248
	ds_read_b128 v[148:151], v151 offset:55296
	s_barrier
	s_waitcnt lgkmcnt(0)
	s_setprio 1
	s_waitcnt lgkmcnt(0)
	v_mfma_f32_16x16x32_bf16 v[18:21], v[156:159], v[2:5], v[62:65]
	v_mfma_f32_16x16x32_bf16 v[58:61], v[178:181], v[10:13], v[18:21]
	v_mfma_f32_16x16x32_bf16 v[18:21], v[156:159], v[160:163], v[218:221]
	v_mfma_f32_16x16x32_bf16 v[50:53], v[178:181], v[190:193], v[18:21]
	v_mfma_f32_16x16x32_bf16 v[18:21], v[174:177], v[2:5], v[54:57]
	v_mfma_f32_16x16x32_bf16 v[42:45], v[182:185], v[10:13], v[18:21]
	v_mfma_f32_16x16x32_bf16 v[18:21], v[174:177], v[160:163], v[234:237]
	v_mfma_f32_16x16x32_bf16 v[34:37], v[182:185], v[190:193], v[18:21]
	v_mfma_f32_16x16x32_bf16 v[18:21], v[194:197], v[2:5], v[46:49]
	v_mfma_f32_16x16x32_bf16 v[2:5], v[198:201], v[2:5], v[38:41]
	v_mfma_f32_16x16x32_bf16 v[26:29], v[230:233], v[10:13], v[18:21]
	v_mfma_f32_16x16x32_bf16 v[18:21], v[194:197], v[160:163], v[238:241]
	v_mfma_f32_16x16x32_bf16 v[10:13], v[148:151], v[10:13], v[2:5]
	v_mfma_f32_16x16x32_bf16 v[2:5], v[198:201], v[160:163], v[140:143]
	v_mfma_f32_16x16x32_bf16 v[18:21], v[230:233], v[190:193], v[18:21]
	v_mfma_f32_16x16x32_bf16 v[2:5], v[148:151], v[190:193], v[2:5]
	s_setprio 0
	s_setprio 1
	v_mfma_f32_16x16x32_bf16 v[30:33], v[156:159], v[136:139], v[30:33]
	v_mfma_f32_16x16x32_bf16 v[62:65], v[178:181], v[222:225], v[30:33]
	v_mfma_f32_16x16x32_bf16 v[30:33], v[156:159], v[164:167], v[144:147]
	v_mfma_f32_16x16x32_bf16 v[22:25], v[174:177], v[136:139], v[22:25]
	v_mfma_f32_16x16x32_bf16 v[14:17], v[194:197], v[136:139], v[14:17]
	v_mfma_f32_16x16x32_bf16 v[54:57], v[178:181], v[226:229], v[30:33]
	v_mfma_f32_16x16x32_bf16 v[46:49], v[182:185], v[222:225], v[22:25]
	v_mfma_f32_16x16x32_bf16 v[22:25], v[174:177], v[164:167], v[152:155]
	v_mfma_f32_16x16x32_bf16 v[30:33], v[230:233], v[222:225], v[14:17]
	v_mfma_f32_16x16x32_bf16 v[14:17], v[194:197], v[164:167], v[170:173]
	v_mfma_f32_16x16x32_bf16 v[6:9], v[198:201], v[136:139], v[6:9]
	v_mfma_f32_16x16x32_bf16 v[38:41], v[182:185], v[226:229], v[22:25]
	v_mfma_f32_16x16x32_bf16 v[22:25], v[230:233], v[226:229], v[14:17]
	v_mfma_f32_16x16x32_bf16 v[14:17], v[148:151], v[222:225], v[6:9]
	v_mfma_f32_16x16x32_bf16 v[6:9], v[198:201], v[164:167], v[186:189]
	v_mfma_f32_16x16x32_bf16 v[6:9], v[148:151], v[226:229], v[6:9]
	s_setprio 0
	s_cmpk_gt_u32 s0, 0xff
	s_barrier
	s_cbranch_scc1 .LBB0_344
	s_barrier

.LBB0_348:
	s_lshl_b32 s16, s16, 5
	v_and_b32_e32 v19, 15, v17
	s_and_b32 s16, s16, 0x60
	v_lshlrev_b32_e32 v20, 7, v19
	v_or_b32_e32 v19, s16, v19
	s_add_i32 s16, s1, 0x18000
	s_mov_b64 s[20:21], 0x80
	v_lshl_or_b32 v20, s17, 13, v20
	v_lshl_add_u64 v[6:7], v[6:7], 0, s[20:21]
	s_mov_b32 m0, s16
	s_add_i32 s17, s1, 0x1a000
	s_waitcnt vmcnt(4)
	s_barrier
	global_load_lds_dwordx4 v[6:7], off
	v_lshl_add_u64 v[6:7], v[8:9], 0, s[20:21]
	s_mov_b32 m0, s17
	s_add_i32 s18, s1, 0x8000
	global_load_lds_dwordx4 v[6:7], off
	v_lshl_add_u64 v[6:7], v[12:13], 0, s[20:21]
	s_mov_b32 m0, s18
	s_add_i32 s19, s1, 0xa000
	global_load_lds_dwordx4 v[6:7], off
	v_lshl_add_u64 v[6:7], v[10:11], 0, s[20:21]
	s_mov_b32 m0, s19
	v_lshl_add_u64 v[4:5], v[4:5], 0, s[50:51]
	s_add_i32 s20, s1, 0x1c000
	global_load_lds_dwordx4 v[6:7], off
	v_lshl_add_u64 v[6:7], v[0:1], 1, v[4:5]
	s_mov_b32 m0, s20
	s_add_i32 s21, s1, 0x1e000
	global_load_lds_dwordx4 v[6:7], off
	v_lshl_add_u64 v[2:3], v[2:3], 1, v[4:5]
	s_mov_b32 m0, s21
	v_and_b32_e32 v21, 3, v18
	global_load_lds_dwordx4 v[2:3], off
	v_bfe_u32 v17, v17, 1, 3
	v_add_u32_e32 v0, v16, v14
	v_bitop3_b32 v18, v18, v17, 3 bitop3:0x6c
	v_bitop3_b32 v17, v21, v17, 4 bitop3:0x36
	s_waitcnt vmcnt(6)
	v_lshlrev_b64 v[2:3], 1, v[0:1]
	v_add_u32_e32 v0, v15, v14
	v_lshlrev_b32_e32 v18, 4, v18
	v_lshlrev_b32_e32 v17, 4, v17
	v_lshlrev_b32_e32 v19, 7, v19
	v_lshl_add_u64 v[140:141], s[4:5], 0, v[2:3]
	v_lshlrev_b64 v[4:5], 1, v[0:1]
	v_lshl_add_u64 v[144:145], v[2:3], 0, s[90:91]
	v_mov_b32_e32 v2, 0
	v_or_b32_e32 v148, v18, v20
	v_or_b32_e32 v150, v19, v18
	v_or_b32_e32 v149, v17, v20
	v_or_b32_e32 v151, v19, v17
	v_lshl_add_u64 v[142:143], s[4:5], 0, v[4:5]
	v_lshl_add_u64 v[146:147], v[4:5], 0, s[90:91]
	s_mov_b32 s4, -2
	v_mov_b32_e32 v3, v2
	v_mov_b32_e32 v4, v2
	v_mov_b32_e32 v5, v2
	v_mov_b32_e32 v6, v2
	v_mov_b32_e32 v7, v2
	v_mov_b32_e32 v8, v2
	v_mov_b32_e32 v9, v2
	v_mov_b32_e32 v10, v2
	v_mov_b32_e32 v11, v2
	v_mov_b32_e32 v12, v2
	v_mov_b32_e32 v13, v2
	v_mov_b32_e32 v14, v2
	v_mov_b32_e32 v15, v2
	v_mov_b32_e32 v16, v2
	v_mov_b32_e32 v17, v2
	v_mov_b32_e32 v18, v2
	v_mov_b32_e32 v19, v2
	v_mov_b32_e32 v20, v2
	v_mov_b32_e32 v21, v2
	v_mov_b32_e32 v22, v2
	v_mov_b32_e32 v23, v2
	v_mov_b32_e32 v24, v2
	v_mov_b32_e32 v25, v2
	v_mov_b32_e32 v26, v2
	v_mov_b32_e32 v27, v2
	v_mov_b32_e32 v28, v2
	v_mov_b32_e32 v29, v2
	v_mov_b32_e32 v30, v2
	v_mov_b32_e32 v31, v2
	v_mov_b32_e32 v32, v2
	v_mov_b32_e32 v33, v2
	v_mov_b32_e32 v34, v2
	v_mov_b32_e32 v35, v2
	v_mov_b32_e32 v36, v2
	v_mov_b32_e32 v37, v2
	v_mov_b32_e32 v38, v2
	v_mov_b32_e32 v39, v2
	v_mov_b32_e32 v40, v2
	v_mov_b32_e32 v41, v2
	v_mov_b32_e32 v42, v2
	v_mov_b32_e32 v43, v2
	v_mov_b32_e32 v44, v2
	v_mov_b32_e32 v45, v2
	v_mov_b32_e32 v46, v2
	v_mov_b32_e32 v47, v2
	v_mov_b32_e32 v48, v2
	v_mov_b32_e32 v49, v2
	v_mov_b32_e32 v50, v2
	v_mov_b32_e32 v51, v2
	v_mov_b32_e32 v52, v2
	v_mov_b32_e32 v53, v2
	v_mov_b32_e32 v54, v2
	v_mov_b32_e32 v55, v2
	v_mov_b32_e32 v56, v2
	v_mov_b32_e32 v57, v2
	v_mov_b32_e32 v58, v2
	v_mov_b32_e32 v59, v2
	v_mov_b32_e32 v60, v2
	v_mov_b32_e32 v61, v2
	v_mov_b32_e32 v62, v2
	v_mov_b32_e32 v63, v2
	v_mov_b32_e32 v64, v2
	v_mov_b32_e32 v65, v2
	v_mov_b32_e32 v66, v2
	v_mov_b32_e32 v67, v2
	v_mov_b32_e32 v68, v2
	v_mov_b32_e32 v69, v2
	v_mov_b32_e32 v70, v2
	v_mov_b32_e32 v71, v2
	v_mov_b32_e32 v72, v2
	v_mov_b32_e32 v73, v2
	v_mov_b32_e32 v74, v2
	v_mov_b32_e32 v75, v2
	v_mov_b32_e32 v76, v2
	v_mov_b32_e32 v77, v2
	v_mov_b32_e32 v78, v2
	v_mov_b32_e32 v79, v2
	v_mov_b32_e32 v80, v2
	v_mov_b32_e32 v81, v2
	v_mov_b32_e32 v82, v2
	v_mov_b32_e32 v83, v2
	v_mov_b32_e32 v84, v2
	v_mov_b32_e32 v85, v2
	v_mov_b32_e32 v86, v2
	v_mov_b32_e32 v87, v2
	v_mov_b32_e32 v88, v2
	v_mov_b32_e32 v89, v2
	v_mov_b32_e32 v90, v2
	v_mov_b32_e32 v91, v2
	v_mov_b32_e32 v92, v2
	v_mov_b32_e32 v93, v2
	v_mov_b32_e32 v94, v2
	v_mov_b32_e32 v95, v2
	v_mov_b32_e32 v96, v2
	v_mov_b32_e32 v97, v2
	v_mov_b32_e32 v98, v2
	v_mov_b32_e32 v99, v2
	v_mov_b32_e32 v100, v2
	v_mov_b32_e32 v101, v2
	v_mov_b32_e32 v102, v2
	v_mov_b32_e32 v103, v2
	v_mov_b32_e32 v104, v2
	v_mov_b32_e32 v105, v2
	v_mov_b32_e32 v106, v2
	v_mov_b32_e32 v107, v2
	v_mov_b32_e32 v108, v2
	v_mov_b32_e32 v109, v2
	v_mov_b32_e32 v110, v2
	v_mov_b32_e32 v111, v2
	v_mov_b32_e32 v112, v2
	v_mov_b32_e32 v113, v2
	v_mov_b32_e32 v114, v2
	v_mov_b32_e32 v115, v2
	v_mov_b32_e32 v116, v2
	v_mov_b32_e32 v117, v2
	v_mov_b32_e32 v118, v2
	v_mov_b32_e32 v119, v2
	v_mov_b32_e32 v120, v2
	v_mov_b32_e32 v121, v2
	v_mov_b32_e32 v122, v2
	v_mov_b32_e32 v123, v2
	v_mov_b32_e32 v124, v2
	v_mov_b32_e32 v125, v2
	v_mov_b32_e32 v126, v2
	v_mov_b32_e32 v127, v2
	v_mov_b32_e32 v128, v2
	v_mov_b32_e32 v129, v2
	s_mov_b64 s[24:25], 0x82d4900
	s_mov_b64 s[26:27], 0x8254980
	s_mov_b64 s[28:29], 0x82d4980
	s_waitcnt lgkmcnt(0)
	s_sub_u32 s100, s100, 0x40000000
	s_subb_u32 s101, s101, 0
	s_mov_b64 vcc, s[100:101]
	v_lshl_add_u64 v[206:207], v[132:133], 0, v[142:143]
	v_subrev_u32_e32 v206, vcc_lo, v206
	v_lshl_add_u64 v[208:209], v[132:133], 0, v[140:141]
	v_subrev_u32_e32 v208, vcc_lo, v208
	v_lshl_add_u64 v[210:211], v[132:133], 0, v[146:147]
	v_subrev_u32_e32 v210, vcc_lo, v210
	v_lshl_add_u64 v[214:215], v[132:133], 0, v[144:145]
	v_subrev_u32_e32 v214, vcc_lo, v214
	v_add_u32_e32 v207, 0x10000, v150
	v_add_u32_e32 v209, 0x10000, v151
	v_add_u32_e32 v0, s50, v206
	v_add_u32_e32 v152, s54, v206
	v_add_u32_e32 v153, s58, v206
	v_add_u32_e32 v206, s62, v206
	v_add_u32_e32 v154, s50, v208
	v_add_u32_e32 v155, s54, v208
	v_add_u32_e32 v156, s58, v208
	v_add_u32_e32 v208, s62, v208
	v_add_u32_e32 v157, s70, v210
	v_add_u32_e32 v158, s24, v210
	v_add_u32_e32 v159, s26, v210
	v_add_u32_e32 v210, s28, v210
	v_add_u32_e32 v211, s70, v214
	v_add_u32_e32 v215, s24, v214
	v_add_u32_e32 v246, s26, v214
	v_add_u32_e32 v214, s28, v214
	s_add_i32 s22, s1, 0xc000
	s_add_i32 s5, s1, 0xe000
	s_barrier
.LBB0_349:
	ds_read_b128 v[160:163], v207
	ds_read_b128 v[164:167], v209
	ds_read_b128 v[168:171], v207 offset:2048
	ds_read_b128 v[172:175], v209 offset:2048
	ds_read_b128 v[176:179], v148
	ds_read_b128 v[180:183], v148 offset:2048
	ds_read_b128 v[184:187], v149
	ds_read_b128 v[188:191], v149 offset:2048
	ds_read_b128 v[192:195], v148 offset:4096
	ds_read_b128 v[196:199], v148 offset:6144
	s_mov_b32 m0, s22
	ds_read_b128 v[200:203], v149 offset:4096
	global_load_lds_dwordx4 v0, vcc
	s_mov_b32 m0, s5
	ds_read_b128 v[218:221], v149 offset:6144
	global_load_lds_dwordx4 v154, vcc
	s_waitcnt vmcnt(10) lgkmcnt(8)
	s_barrier
	s_waitcnt lgkmcnt(0)
	v_mfma_f32_16x16x32_bf16 v[126:129], v[160:163], v[176:179], v[126:129]
	v_mfma_f32_16x16x32_bf16 v[122:125], v[168:171], v[176:179], v[122:125]
	v_mfma_f32_16x16x32_bf16 v[118:121], v[160:163], v[180:183], v[118:121]
	v_mfma_f32_16x16x32_bf16 v[114:117], v[168:171], v[180:183], v[114:117]
	v_mfma_f32_16x16x32_bf16 v[110:113], v[160:163], v[192:195], v[110:113]
	v_mfma_f32_16x16x32_bf16 v[106:109], v[168:171], v[192:195], v[106:109]
	v_mfma_f32_16x16x32_bf16 v[102:105], v[160:163], v[196:199], v[102:105]
	v_mfma_f32_16x16x32_bf16 v[98:101], v[168:171], v[196:199], v[98:101]
	v_mfma_f32_16x16x32_bf16 v[126:129], v[164:167], v[184:187], v[126:129]
	v_mfma_f32_16x16x32_bf16 v[122:125], v[172:175], v[184:187], v[122:125]
	v_mfma_f32_16x16x32_bf16 v[118:121], v[164:167], v[188:191], v[118:121]
	v_mfma_f32_16x16x32_bf16 v[114:117], v[172:175], v[188:191], v[114:117]
	v_mfma_f32_16x16x32_bf16 v[110:113], v[164:167], v[200:203], v[110:113]
	v_mfma_f32_16x16x32_bf16 v[106:109], v[172:175], v[200:203], v[106:109]
	v_mfma_f32_16x16x32_bf16 v[102:105], v[164:167], v[218:221], v[102:105]
	v_mfma_f32_16x16x32_bf16 v[98:101], v[172:175], v[218:221], v[98:101]
	s_barrier
	ds_read_b128 v[222:225], v207 offset:16384
	ds_read_b128 v[226:229], v209 offset:16384
	s_mov_b32 m0, s2
	ds_read_b128 v[230:233], v207 offset:18432
	global_load_lds_dwordx4 v157, vcc
	s_mov_b32 m0, s3
	ds_read_b128 v[234:237], v209 offset:18432
	global_load_lds_dwordx4 v211, vcc
	s_waitcnt vmcnt(10) lgkmcnt(0)
	s_barrier
	v_mfma_f32_16x16x32_bf16 v[94:97], v[222:225], v[176:179], v[94:97]
	v_mfma_f32_16x16x32_bf16 v[90:93], v[230:233], v[176:179], v[90:93]
	v_mfma_f32_16x16x32_bf16 v[86:89], v[222:225], v[180:183], v[86:89]
	v_mfma_f32_16x16x32_bf16 v[82:85], v[230:233], v[180:183], v[82:85]
	v_mfma_f32_16x16x32_bf16 v[78:81], v[222:225], v[192:195], v[78:81]
	v_mfma_f32_16x16x32_bf16 v[74:77], v[230:233], v[192:195], v[74:77]
	v_mfma_f32_16x16x32_bf16 v[70:73], v[222:225], v[196:199], v[70:73]
	v_mfma_f32_16x16x32_bf16 v[66:69], v[230:233], v[196:199], v[66:69]
	v_mfma_f32_16x16x32_bf16 v[94:97], v[226:229], v[184:187], v[94:97]
	v_mfma_f32_16x16x32_bf16 v[90:93], v[234:237], v[184:187], v[90:93]
	v_mfma_f32_16x16x32_bf16 v[86:89], v[226:229], v[188:191], v[86:89]
	v_mfma_f32_16x16x32_bf16 v[82:85], v[234:237], v[188:191], v[82:85]
	v_mfma_f32_16x16x32_bf16 v[78:81], v[226:229], v[200:203], v[78:81]
	v_mfma_f32_16x16x32_bf16 v[74:77], v[234:237], v[200:203], v[74:77]
	v_mfma_f32_16x16x32_bf16 v[70:73], v[226:229], v[218:221], v[70:73]
	v_mfma_f32_16x16x32_bf16 v[66:69], v[234:237], v[218:221], v[66:69]
	s_barrier
	ds_read_b128 v[176:179], v148 offset:16384
	ds_read_b128 v[180:183], v148 offset:18432
	ds_read_b128 v[184:187], v149 offset:16384
	ds_read_b128 v[188:191], v149 offset:18432
	s_mov_b32 m0, s1
	ds_read_b128 v[192:195], v148 offset:20480
	global_load_lds_dwordx4 v152, vcc
	s_mov_b32 m0, s9
	ds_read_b128 v[196:199], v148 offset:22528
	global_load_lds_dwordx4 v155, vcc
	s_mov_b32 m0, s11
	ds_read_b128 v[200:203], v149 offset:20480
	global_load_lds_dwordx4 v158, vcc
	s_mov_b32 m0, s12
	ds_read_b128 v[218:221], v149 offset:22528
	global_load_lds_dwordx4 v215, vcc
	s_waitcnt vmcnt(10) lgkmcnt(0)
	s_barrier
	v_mfma_f32_16x16x32_bf16 v[62:65], v[160:163], v[176:179], v[62:65]
	v_mfma_f32_16x16x32_bf16 v[58:61], v[168:171], v[176:179], v[58:61]
	v_mfma_f32_16x16x32_bf16 v[54:57], v[160:163], v[180:183], v[54:57]
	v_mfma_f32_16x16x32_bf16 v[50:53], v[168:171], v[180:183], v[50:53]
	v_mfma_f32_16x16x32_bf16 v[46:49], v[160:163], v[192:195], v[46:49]
	v_mfma_f32_16x16x32_bf16 v[42:45], v[168:171], v[192:195], v[42:45]
	v_mfma_f32_16x16x32_bf16 v[38:41], v[160:163], v[196:199], v[38:41]
	v_mfma_f32_16x16x32_bf16 v[34:37], v[168:171], v[196:199], v[34:37]
	v_mfma_f32_16x16x32_bf16 v[62:65], v[164:167], v[184:187], v[62:65]
	v_mfma_f32_16x16x32_bf16 v[58:61], v[172:175], v[184:187], v[58:61]
	v_mfma_f32_16x16x32_bf16 v[54:57], v[164:167], v[188:191], v[54:57]
	v_mfma_f32_16x16x32_bf16 v[50:53], v[172:175], v[188:191], v[50:53]
	v_mfma_f32_16x16x32_bf16 v[46:49], v[164:167], v[200:203], v[46:49]
	v_mfma_f32_16x16x32_bf16 v[42:45], v[172:175], v[200:203], v[42:45]
	v_mfma_f32_16x16x32_bf16 v[38:41], v[164:167], v[218:221], v[38:41]
	v_mfma_f32_16x16x32_bf16 v[34:37], v[172:175], v[218:221], v[34:37]
	v_mfma_f32_16x16x32_bf16 v[30:33], v[222:225], v[176:179], v[30:33]
	v_mfma_f32_16x16x32_bf16 v[26:29], v[230:233], v[176:179], v[26:29]
	v_mfma_f32_16x16x32_bf16 v[22:25], v[222:225], v[180:183], v[22:25]
	v_mfma_f32_16x16x32_bf16 v[18:21], v[230:233], v[180:183], v[18:21]
	v_mfma_f32_16x16x32_bf16 v[14:17], v[222:225], v[192:195], v[14:17]
	v_mfma_f32_16x16x32_bf16 v[10:13], v[230:233], v[192:195], v[10:13]
	v_mfma_f32_16x16x32_bf16 v[6:9], v[222:225], v[196:199], v[6:9]
	v_mfma_f32_16x16x32_bf16 v[2:5], v[230:233], v[196:199], v[2:5]
	v_mfma_f32_16x16x32_bf16 v[30:33], v[226:229], v[184:187], v[30:33]
	v_mfma_f32_16x16x32_bf16 v[26:29], v[234:237], v[184:187], v[26:29]
	v_mfma_f32_16x16x32_bf16 v[22:25], v[226:229], v[188:191], v[22:25]
	v_mfma_f32_16x16x32_bf16 v[18:21], v[234:237], v[188:191], v[18:21]
	v_mfma_f32_16x16x32_bf16 v[14:17], v[226:229], v[200:203], v[14:17]
	v_mfma_f32_16x16x32_bf16 v[10:13], v[234:237], v[200:203], v[10:13]
	v_mfma_f32_16x16x32_bf16 v[6:9], v[226:229], v[218:221], v[6:9]
	v_mfma_f32_16x16x32_bf16 v[2:5], v[234:237], v[218:221], v[2:5]
	s_barrier
	ds_read_b128 v[168:171], v207 offset:32768
	ds_read_b128 v[172:175], v209 offset:32768
	ds_read_b128 v[176:179], v207 offset:34816
	ds_read_b128 v[180:183], v209 offset:34816
	ds_read_b128 v[184:187], v148 offset:32768
	ds_read_b128 v[188:191], v148 offset:34816
	ds_read_b128 v[192:195], v149 offset:32768
	ds_read_b128 v[196:199], v149 offset:34816
	ds_read_b128 v[200:203], v148 offset:36864
	ds_read_b128 v[218:221], v148 offset:38912
	s_mov_b32 m0, s13
	ds_read_b128 v[222:225], v149 offset:36864
	global_load_lds_dwordx4 v153, vcc
	s_mov_b32 m0, s15
	ds_read_b128 v[226:229], v149 offset:38912
	global_load_lds_dwordx4 v156, vcc
	s_waitcnt vmcnt(10) lgkmcnt(8)
	s_barrier
	s_waitcnt lgkmcnt(0)
	v_mfma_f32_16x16x32_bf16 v[126:129], v[168:171], v[184:187], v[126:129]
	v_mfma_f32_16x16x32_bf16 v[122:125], v[176:179], v[184:187], v[122:125]
	v_mfma_f32_16x16x32_bf16 v[118:121], v[168:171], v[188:191], v[118:121]
	v_mfma_f32_16x16x32_bf16 v[114:117], v[176:179], v[188:191], v[114:117]
	v_mfma_f32_16x16x32_bf16 v[110:113], v[168:171], v[200:203], v[110:113]
	v_mfma_f32_16x16x32_bf16 v[106:109], v[176:179], v[200:203], v[106:109]
	v_mfma_f32_16x16x32_bf16 v[102:105], v[168:171], v[218:221], v[102:105]
	v_mfma_f32_16x16x32_bf16 v[98:101], v[176:179], v[218:221], v[98:101]
	v_mfma_f32_16x16x32_bf16 v[126:129], v[172:175], v[192:195], v[126:129]
	v_mfma_f32_16x16x32_bf16 v[122:125], v[180:183], v[192:195], v[122:125]
	v_mfma_f32_16x16x32_bf16 v[118:121], v[172:175], v[196:199], v[118:121]
	v_mfma_f32_16x16x32_bf16 v[114:117], v[180:183], v[196:199], v[114:117]
	v_mfma_f32_16x16x32_bf16 v[110:113], v[172:175], v[222:225], v[110:113]
	v_mfma_f32_16x16x32_bf16 v[106:109], v[180:183], v[222:225], v[106:109]
	v_mfma_f32_16x16x32_bf16 v[102:105], v[172:175], v[226:229], v[102:105]
	v_mfma_f32_16x16x32_bf16 v[98:101], v[180:183], v[226:229], v[98:101]
	s_barrier
	ds_read_b128 v[230:233], v207 offset:49152
	ds_read_b128 v[234:237], v209 offset:49152
	s_mov_b32 m0, s16
	ds_read_b128 v[238:241], v207 offset:51200
	global_load_lds_dwordx4 v159, vcc
	s_mov_b32 m0, s17
	ds_read_b128 v[242:245], v209 offset:51200
	global_load_lds_dwordx4 v246, vcc
	s_waitcnt vmcnt(10) lgkmcnt(0)
	s_barrier
	v_mfma_f32_16x16x32_bf16 v[94:97], v[230:233], v[184:187], v[94:97]
	v_mfma_f32_16x16x32_bf16 v[90:93], v[238:241], v[184:187], v[90:93]
	v_mfma_f32_16x16x32_bf16 v[86:89], v[230:233], v[188:191], v[86:89]
	v_mfma_f32_16x16x32_bf16 v[82:85], v[238:241], v[188:191], v[82:85]
	v_mfma_f32_16x16x32_bf16 v[78:81], v[230:233], v[200:203], v[78:81]
	v_mfma_f32_16x16x32_bf16 v[74:77], v[238:241], v[200:203], v[74:77]
	v_mfma_f32_16x16x32_bf16 v[70:73], v[230:233], v[218:221], v[70:73]
	v_mfma_f32_16x16x32_bf16 v[66:69], v[238:241], v[218:221], v[66:69]
	v_mfma_f32_16x16x32_bf16 v[94:97], v[234:237], v[192:195], v[94:97]
	v_mfma_f32_16x16x32_bf16 v[90:93], v[242:245], v[192:195], v[90:93]
	v_mfma_f32_16x16x32_bf16 v[86:89], v[234:237], v[196:199], v[86:89]
	v_mfma_f32_16x16x32_bf16 v[82:85], v[242:245], v[196:199], v[82:85]
	v_mfma_f32_16x16x32_bf16 v[78:81], v[234:237], v[222:225], v[78:81]
	v_mfma_f32_16x16x32_bf16 v[74:77], v[242:245], v[222:225], v[74:77]
	v_mfma_f32_16x16x32_bf16 v[70:73], v[234:237], v[226:229], v[70:73]
	v_mfma_f32_16x16x32_bf16 v[66:69], v[242:245], v[226:229], v[66:69]
	s_barrier
	ds_read_b128 v[184:187], v148 offset:49152
	ds_read_b128 v[188:191], v148 offset:51200
	ds_read_b128 v[192:195], v149 offset:49152
	ds_read_b128 v[196:199], v149 offset:51200
	s_mov_b32 m0, s18
	ds_read_b128 v[200:203], v148 offset:53248
	global_load_lds_dwordx4 v206, vcc
	s_mov_b32 m0, s19
	ds_read_b128 v[218:221], v148 offset:55296
	global_load_lds_dwordx4 v208, vcc
	s_mov_b32 m0, s20
	ds_read_b128 v[222:225], v149 offset:53248
	global_load_lds_dwordx4 v210, vcc
	s_mov_b32 m0, s21
	ds_read_b128 v[226:229], v149 offset:55296
	global_load_lds_dwordx4 v214, vcc
	s_waitcnt vmcnt(10) lgkmcnt(0)
	s_barrier
	v_mfma_f32_16x16x32_bf16 v[62:65], v[168:171], v[184:187], v[62:65]
	v_mfma_f32_16x16x32_bf16 v[58:61], v[176:179], v[184:187], v[58:61]
	v_mfma_f32_16x16x32_bf16 v[54:57], v[168:171], v[188:191], v[54:57]
	v_mfma_f32_16x16x32_bf16 v[50:53], v[176:179], v[188:191], v[50:53]
	v_mfma_f32_16x16x32_bf16 v[46:49], v[168:171], v[200:203], v[46:49]
	v_mfma_f32_16x16x32_bf16 v[42:45], v[176:179], v[200:203], v[42:45]
	v_mfma_f32_16x16x32_bf16 v[38:41], v[168:171], v[218:221], v[38:41]
	v_mfma_f32_16x16x32_bf16 v[34:37], v[176:179], v[218:221], v[34:37]
	v_mfma_f32_16x16x32_bf16 v[62:65], v[172:175], v[192:195], v[62:65]
	v_mfma_f32_16x16x32_bf16 v[58:61], v[180:183], v[192:195], v[58:61]
	v_mfma_f32_16x16x32_bf16 v[54:57], v[172:175], v[196:199], v[54:57]
	v_mfma_f32_16x16x32_bf16 v[50:53], v[180:183], v[196:199], v[50:53]
	v_mfma_f32_16x16x32_bf16 v[46:49], v[172:175], v[222:225], v[46:49]
	v_mfma_f32_16x16x32_bf16 v[42:45], v[180:183], v[222:225], v[42:45]
	v_mfma_f32_16x16x32_bf16 v[38:41], v[172:175], v[226:229], v[38:41]
	v_mfma_f32_16x16x32_bf16 v[34:37], v[180:183], v[226:229], v[34:37]
	v_mfma_f32_16x16x32_bf16 v[30:33], v[230:233], v[184:187], v[30:33]
	v_mfma_f32_16x16x32_bf16 v[26:29], v[238:241], v[184:187], v[26:29]
	v_mfma_f32_16x16x32_bf16 v[22:25], v[230:233], v[188:191], v[22:25]
	v_mfma_f32_16x16x32_bf16 v[18:21], v[238:241], v[188:191], v[18:21]
	v_mfma_f32_16x16x32_bf16 v[14:17], v[230:233], v[200:203], v[14:17]
	v_mfma_f32_16x16x32_bf16 v[10:13], v[238:241], v[200:203], v[10:13]
	v_mfma_f32_16x16x32_bf16 v[6:9], v[230:233], v[218:221], v[6:9]
	v_mfma_f32_16x16x32_bf16 v[2:5], v[238:241], v[218:221], v[2:5]
	v_mfma_f32_16x16x32_bf16 v[30:33], v[234:237], v[192:195], v[30:33]
	v_mfma_f32_16x16x32_bf16 v[26:29], v[242:245], v[192:195], v[26:29]
	v_mfma_f32_16x16x32_bf16 v[22:25], v[234:237], v[196:199], v[22:25]
	v_mfma_f32_16x16x32_bf16 v[18:21], v[242:245], v[196:199], v[18:21]
	v_mfma_f32_16x16x32_bf16 v[14:17], v[234:237], v[222:225], v[14:17]
	v_mfma_f32_16x16x32_bf16 v[10:13], v[242:245], v[222:225], v[10:13]
	v_mfma_f32_16x16x32_bf16 v[6:9], v[234:237], v[226:229], v[6:9]
	v_mfma_f32_16x16x32_bf16 v[2:5], v[242:245], v[226:229], v[2:5]
	s_add_u32 vcc_lo, vcc_lo, s54
	s_addc_u32 vcc_hi, vcc_hi, s55
	s_add_i32 s4, s4, 2
	s_cmp_lt_u32 s4, 28
	v_lshl_add_u64 v[132:133], v[132:133], 0, s[54:55]
	s_barrier
	s_cbranch_scc1 .LBB0_349
	s_waitcnt vmcnt(6)
	v_or_b32_e32 v0, 0x10000, v150
	v_add_u32_e32 v153, 0x10800, v150
	v_or_b32_e32 v152, 0x10000, v151
	v_add_u32_e32 v154, 0x10800, v151
	v_or_b32_e32 v155, 0x14000, v150
	v_add_u32_e32 v157, 0x14800, v150
	v_or_b32_e32 v156, 0x14000, v151
	v_add_u32_e32 v158, 0x14800, v151
	v_or_b32_e32 v159, 0x18000, v150
	v_add_u32_e32 v161, 0x18800, v150
	v_or_b32_e32 v160, 0x18000, v151
	v_add_u32_e32 v162, 0x18800, v151
	v_or_b32_e32 v163, 0x1c000, v150
	v_add_u32_e32 v165, 0x1c800, v150
	v_or_b32_e32 v164, 0x1c000, v151
	v_add_u32_e32 v166, 0x1c800, v151
	s_mov_b64 s[2:3], 0xf80
	s_mov_b32 m0, s22
	v_lshl_add_u64 v[132:133], v[138:139], 0, s[2:3]
	ds_read_b128 v[140:143], v0
	ds_read_b128 v[144:147], v152
	ds_read_b128 v[150:153], v153
	ds_read_b128 v[168:171], v154
	ds_read_b128 v[172:175], v148
	ds_read_b128 v[176:179], v148 offset:2048
	ds_read_b128 v[180:183], v149
	ds_read_b128 v[184:187], v149 offset:2048
	ds_read_b128 v[188:191], v148 offset:4096
	ds_read_b128 v[192:195], v148 offset:6144
	ds_read_b128 v[196:199], v149 offset:4096
	ds_read_b128 v[200:203], v149 offset:6144
	global_load_lds_dwordx4 v[132:133], off
	v_lshl_add_u64 v[132:133], v[136:137], 0, s[2:3]
	s_mov_b32 m0, s5
	s_nop 0
	global_load_lds_dwordx4 v[132:133], off
	s_barrier
	s_waitcnt lgkmcnt(0)
	s_setprio 1
	s_waitcnt lgkmcnt(0)
	v_mfma_f32_16x16x32_bf16 v[126:129], v[140:143], v[172:175], v[126:129]
	v_mfma_f32_16x16x32_bf16 v[122:125], v[150:153], v[172:175], v[122:125]
	v_mfma_f32_16x16x32_bf16 v[118:121], v[140:143], v[176:179], v[118:121]
	v_mfma_f32_16x16x32_bf16 v[110:113], v[140:143], v[188:191], v[110:113]
	v_mfma_f32_16x16x32_bf16 v[106:109], v[150:153], v[188:191], v[106:109]
	v_mfma_f32_16x16x32_bf16 v[126:129], v[144:147], v[180:183], v[126:129]
	v_mfma_f32_16x16x32_bf16 v[122:125], v[168:171], v[180:183], v[122:125]
	v_mfma_f32_16x16x32_bf16 v[118:121], v[144:147], v[184:187], v[118:121]
	v_mfma_f32_16x16x32_bf16 v[114:117], v[150:153], v[176:179], v[114:117]
	v_mfma_f32_16x16x32_bf16 v[110:113], v[144:147], v[196:199], v[110:113]
	v_mfma_f32_16x16x32_bf16 v[106:109], v[168:171], v[196:199], v[106:109]
	v_mfma_f32_16x16x32_bf16 v[102:105], v[140:143], v[192:195], v[102:105]
	v_mfma_f32_16x16x32_bf16 v[98:101], v[150:153], v[192:195], v[98:101]
	v_mfma_f32_16x16x32_bf16 v[136:139], v[168:171], v[184:187], v[114:117]
	v_mfma_f32_16x16x32_bf16 v[218:221], v[144:147], v[200:203], v[102:105]
	v_mfma_f32_16x16x32_bf16 v[222:225], v[168:171], v[200:203], v[98:101]
	s_setprio 0
	s_barrier
	s_nop 2
	ds_read_b128 v[98:101], v155
	ds_read_b128 v[102:105], v156
	ds_read_b128 v[114:117], v157
	ds_read_b128 v[154:157], v158
	s_barrier
	s_waitcnt lgkmcnt(0)
	s_setprio 1
	s_waitcnt lgkmcnt(0)
	v_mfma_f32_16x16x32_bf16 v[94:97], v[98:101], v[172:175], v[94:97]
	v_mfma_f32_16x16x32_bf16 v[90:93], v[114:117], v[172:175], v[90:93]
	v_mfma_f32_16x16x32_bf16 v[78:81], v[98:101], v[188:191], v[78:81]
	v_mfma_f32_16x16x32_bf16 v[74:77], v[114:117], v[188:191], v[74:77]
	v_mfma_f32_16x16x32_bf16 v[94:97], v[102:105], v[180:183], v[94:97]
	v_mfma_f32_16x16x32_bf16 v[90:93], v[154:157], v[180:183], v[90:93]
	v_mfma_f32_16x16x32_bf16 v[86:89], v[98:101], v[176:179], v[86:89]
	v_mfma_f32_16x16x32_bf16 v[82:85], v[114:117], v[176:179], v[82:85]
	v_mfma_f32_16x16x32_bf16 v[78:81], v[102:105], v[196:199], v[78:81]
	v_mfma_f32_16x16x32_bf16 v[74:77], v[154:157], v[196:199], v[74:77]
	v_mfma_f32_16x16x32_bf16 v[70:73], v[98:101], v[192:195], v[70:73]
	v_mfma_f32_16x16x32_bf16 v[66:69], v[114:117], v[192:195], v[66:69]
	v_mfma_f32_16x16x32_bf16 v[172:175], v[102:105], v[184:187], v[86:89]
	v_mfma_f32_16x16x32_bf16 v[176:179], v[154:157], v[184:187], v[82:85]
	v_mfma_f32_16x16x32_bf16 v[180:183], v[102:105], v[200:203], v[70:73]
	v_mfma_f32_16x16x32_bf16 v[184:187], v[154:157], v[200:203], v[66:69]
	s_setprio 0
	s_barrier
	s_nop 1
	ds_read_b128 v[66:69], v148 offset:16384
	ds_read_b128 v[70:73], v148 offset:18432
	ds_read_b128 v[82:85], v149 offset:16384
	ds_read_b128 v[86:89], v149 offset:18432
	ds_read_b128 v[188:191], v148 offset:20480
	ds_read_b128 v[192:195], v148 offset:22528
	ds_read_b128 v[196:199], v149 offset:20480
	ds_read_b128 v[200:203], v149 offset:22528
	s_waitcnt vmcnt(4)
	s_barrier
	s_waitcnt lgkmcnt(0)
	s_setprio 1
	s_waitcnt lgkmcnt(0)
	v_mfma_f32_16x16x32_bf16 v[62:65], v[140:143], v[66:69], v[62:65]
	v_mfma_f32_16x16x32_bf16 v[58:61], v[150:153], v[66:69], v[58:61]
	v_mfma_f32_16x16x32_bf16 v[46:49], v[140:143], v[188:191], v[46:49]
	v_mfma_f32_16x16x32_bf16 v[42:45], v[150:153], v[188:191], v[42:45]
	v_mfma_f32_16x16x32_bf16 v[62:65], v[144:147], v[82:85], v[62:65]
	v_mfma_f32_16x16x32_bf16 v[58:61], v[168:171], v[82:85], v[58:61]
	v_mfma_f32_16x16x32_bf16 v[54:57], v[140:143], v[70:73], v[54:57]
	v_mfma_f32_16x16x32_bf16 v[50:53], v[150:153], v[70:73], v[50:53]
	v_mfma_f32_16x16x32_bf16 v[46:49], v[144:147], v[196:199], v[46:49]
	v_mfma_f32_16x16x32_bf16 v[42:45], v[168:171], v[196:199], v[42:45]
	v_mfma_f32_16x16x32_bf16 v[38:41], v[140:143], v[192:195], v[38:41]
	v_mfma_f32_16x16x32_bf16 v[34:37], v[150:153], v[192:195], v[34:37]
	v_mfma_f32_16x16x32_bf16 v[226:229], v[144:147], v[86:89], v[54:57]
	v_mfma_f32_16x16x32_bf16 v[230:233], v[168:171], v[86:89], v[50:53]
	v_mfma_f32_16x16x32_bf16 v[140:143], v[144:147], v[200:203], v[38:41]
	v_mfma_f32_16x16x32_bf16 v[144:147], v[168:171], v[200:203], v[34:37]
	s_setprio 0
	s_setprio 1
	v_mfma_f32_16x16x32_bf16 v[30:33], v[98:101], v[66:69], v[30:33]
	v_mfma_f32_16x16x32_bf16 v[26:29], v[114:117], v[66:69], v[26:29]
	v_mfma_f32_16x16x32_bf16 v[14:17], v[98:101], v[188:191], v[14:17]
	v_mfma_f32_16x16x32_bf16 v[10:13], v[114:117], v[188:191], v[10:13]
	v_mfma_f32_16x16x32_bf16 v[30:33], v[102:105], v[82:85], v[30:33]
	v_mfma_f32_16x16x32_bf16 v[26:29], v[154:157], v[82:85], v[26:29]
	v_mfma_f32_16x16x32_bf16 v[22:25], v[98:101], v[70:73], v[22:25]
	v_mfma_f32_16x16x32_bf16 v[18:21], v[114:117], v[70:73], v[18:21]
	v_mfma_f32_16x16x32_bf16 v[14:17], v[102:105], v[196:199], v[14:17]
	v_mfma_f32_16x16x32_bf16 v[10:13], v[154:157], v[196:199], v[10:13]
	v_mfma_f32_16x16x32_bf16 v[6:9], v[98:101], v[192:195], v[6:9]
	v_mfma_f32_16x16x32_bf16 v[2:5], v[114:117], v[192:195], v[2:5]
	v_mfma_f32_16x16x32_bf16 v[150:153], v[102:105], v[86:89], v[22:25]
	v_mfma_f32_16x16x32_bf16 v[168:171], v[154:157], v[86:89], v[18:21]
	v_mfma_f32_16x16x32_bf16 v[188:191], v[102:105], v[200:203], v[6:9]
	v_mfma_f32_16x16x32_bf16 v[154:157], v[154:157], v[200:203], v[2:5]
	s_setprio 0
	s_barrier
	s_nop 1
	ds_read_b128 v[2:5], v159
	ds_read_b128 v[6:9], v160
	ds_read_b128 v[158:161], v161
	ds_read_b128 v[192:195], v162
	ds_read_b128 v[18:21], v148 offset:32768
	ds_read_b128 v[22:25], v148 offset:34816
	ds_read_b128 v[34:37], v149 offset:32768
	ds_read_b128 v[38:41], v149 offset:34816
	ds_read_b128 v[50:53], v148 offset:36864
	ds_read_b128 v[54:57], v148 offset:38912
	ds_read_b128 v[196:199], v149 offset:36864
	ds_read_b128 v[200:203], v149 offset:38912
	s_waitcnt vmcnt(2)
	s_barrier
	s_waitcnt lgkmcnt(0)
	s_setprio 1
	s_waitcnt lgkmcnt(0)
	v_mfma_f32_16x16x32_bf16 v[66:69], v[2:5], v[18:21], v[126:129]
	v_mfma_f32_16x16x32_bf16 v[126:129], v[6:9], v[34:37], v[66:69]
	v_mfma_f32_16x16x32_bf16 v[66:69], v[158:161], v[18:21], v[122:125]
	v_mfma_f32_16x16x32_bf16 v[114:117], v[192:195], v[34:37], v[66:69]
	v_mfma_f32_16x16x32_bf16 v[66:69], v[2:5], v[22:25], v[118:121]
	v_mfma_f32_16x16x32_bf16 v[102:105], v[6:9], v[38:41], v[66:69]
	v_mfma_f32_16x16x32_bf16 v[66:69], v[158:161], v[22:25], v[136:139]
	v_mfma_f32_16x16x32_bf16 v[98:101], v[192:195], v[38:41], v[66:69]
	v_mfma_f32_16x16x32_bf16 v[66:69], v[2:5], v[50:53], v[110:113]
	v_mfma_f32_16x16x32_bf16 v[86:89], v[6:9], v[196:199], v[66:69]
	v_mfma_f32_16x16x32_bf16 v[66:69], v[158:161], v[50:53], v[106:109]
	v_mfma_f32_16x16x32_bf16 v[82:85], v[192:195], v[196:199], v[66:69]
	v_mfma_f32_16x16x32_bf16 v[66:69], v[2:5], v[54:57], v[218:221]
	v_mfma_f32_16x16x32_bf16 v[70:73], v[6:9], v[200:203], v[66:69]
	v_mfma_f32_16x16x32_bf16 v[66:69], v[158:161], v[54:57], v[222:225]
	v_mfma_f32_16x16x32_bf16 v[66:69], v[192:195], v[200:203], v[66:69]
	s_setprio 0
	s_barrier
	ds_read_b128 v[136:139], v163
	ds_read_b128 v[218:221], v164
	ds_read_b128 v[162:165], v165
	ds_read_b128 v[222:225], v166
	s_waitcnt vmcnt(0)
	s_barrier
	s_waitcnt lgkmcnt(0)
	s_setprio 1
	s_waitcnt lgkmcnt(0)
	v_mfma_f32_16x16x32_bf16 v[94:97], v[136:139], v[18:21], v[94:97]
	v_mfma_f32_16x16x32_bf16 v[18:21], v[162:165], v[18:21], v[90:93]
	v_mfma_f32_16x16x32_bf16 v[118:121], v[222:225], v[34:37], v[18:21]
	v_mfma_f32_16x16x32_bf16 v[18:21], v[136:139], v[22:25], v[172:175]
	v_mfma_f32_16x16x32_bf16 v[110:113], v[218:221], v[38:41], v[18:21]
	v_mfma_f32_16x16x32_bf16 v[18:21], v[162:165], v[22:25], v[176:179]
	v_mfma_f32_16x16x32_bf16 v[106:109], v[222:225], v[38:41], v[18:21]
	v_mfma_f32_16x16x32_bf16 v[18:21], v[136:139], v[50:53], v[78:81]
	v_mfma_f32_16x16x32_bf16 v[122:125], v[218:221], v[34:37], v[94:97]
	v_mfma_f32_16x16x32_bf16 v[94:97], v[218:221], v[196:199], v[18:21]
	v_mfma_f32_16x16x32_bf16 v[18:21], v[162:165], v[50:53], v[74:77]
	v_mfma_f32_16x16x32_bf16 v[90:93], v[222:225], v[196:199], v[18:21]
	v_mfma_f32_16x16x32_bf16 v[18:21], v[136:139], v[54:57], v[180:183]
	v_mfma_f32_16x16x32_bf16 v[78:81], v[218:221], v[200:203], v[18:21]
	v_mfma_f32_16x16x32_bf16 v[18:21], v[162:165], v[54:57], v[184:187]
	v_mfma_f32_16x16x32_bf16 v[74:77], v[222:225], v[200:203], v[18:21]
	s_setprio 0
	s_barrier
	ds_read_b128 v[172:175], v148 offset:49152
	ds_read_b128 v[176:179], v148 offset:51200
	ds_read_b128 v[180:183], v149 offset:49152
	ds_read_b128 v[184:187], v149 offset:51200
	ds_read_b128 v[196:199], v148 offset:53248
	ds_read_b128 v[200:203], v148 offset:55296
	ds_read_b128 v[234:237], v149 offset:53248
	ds_read_b128 v[238:241], v149 offset:55296
	s_barrier
	s_waitcnt lgkmcnt(0)
	s_setprio 1
	s_waitcnt lgkmcnt(0)
	v_mfma_f32_16x16x32_bf16 v[18:21], v[2:5], v[172:175], v[62:65]
	v_mfma_f32_16x16x32_bf16 v[54:57], v[6:9], v[180:183], v[18:21]
	v_mfma_f32_16x16x32_bf16 v[18:21], v[158:161], v[172:175], v[58:61]
	v_mfma_f32_16x16x32_bf16 v[50:53], v[192:195], v[180:183], v[18:21]
	v_mfma_f32_16x16x32_bf16 v[18:21], v[2:5], v[176:179], v[226:229]
	v_mfma_f32_16x16x32_bf16 v[38:41], v[6:9], v[184:187], v[18:21]
	v_mfma_f32_16x16x32_bf16 v[18:21], v[158:161], v[176:179], v[230:233]
	v_mfma_f32_16x16x32_bf16 v[34:37], v[192:195], v[184:187], v[18:21]
	v_mfma_f32_16x16x32_bf16 v[18:21], v[2:5], v[196:199], v[46:49]
	v_mfma_f32_16x16x32_bf16 v[2:5], v[2:5], v[200:203], v[140:143]
	v_mfma_f32_16x16x32_bf16 v[22:25], v[6:9], v[234:237], v[18:21]
	v_mfma_f32_16x16x32_bf16 v[18:21], v[158:161], v[196:199], v[42:45]
	v_mfma_f32_16x16x32_bf16 v[6:9], v[6:9], v[238:241], v[2:5]
	v_mfma_f32_16x16x32_bf16 v[2:5], v[158:161], v[200:203], v[144:147]
	v_mfma_f32_16x16x32_bf16 v[18:21], v[192:195], v[234:237], v[18:21]
	v_mfma_f32_16x16x32_bf16 v[2:5], v[192:195], v[238:241], v[2:5]
	s_setprio 0
	s_setprio 1
	v_mfma_f32_16x16x32_bf16 v[26:29], v[162:165], v[172:175], v[26:29]
	v_mfma_f32_16x16x32_bf16 v[58:61], v[222:225], v[180:183], v[26:29]
	v_mfma_f32_16x16x32_bf16 v[26:29], v[136:139], v[176:179], v[150:153]
	v_mfma_f32_16x16x32_bf16 v[46:49], v[218:221], v[184:187], v[26:29]
	v_mfma_f32_16x16x32_bf16 v[26:29], v[162:165], v[176:179], v[168:171]
	v_mfma_f32_16x16x32_bf16 v[10:13], v[162:165], v[196:199], v[10:13]
	v_mfma_f32_16x16x32_bf16 v[30:33], v[136:139], v[172:175], v[30:33]
	v_mfma_f32_16x16x32_bf16 v[42:45], v[222:225], v[184:187], v[26:29]
	v_mfma_f32_16x16x32_bf16 v[14:17], v[136:139], v[196:199], v[14:17]
	v_mfma_f32_16x16x32_bf16 v[26:29], v[222:225], v[234:237], v[10:13]
	v_mfma_f32_16x16x32_bf16 v[10:13], v[136:139], v[200:203], v[188:191]
	v_mfma_f32_16x16x32_bf16 v[62:65], v[218:221], v[180:183], v[30:33]
	v_mfma_f32_16x16x32_bf16 v[30:33], v[218:221], v[234:237], v[14:17]
	v_mfma_f32_16x16x32_bf16 v[14:17], v[218:221], v[238:241], v[10:13]
	v_mfma_f32_16x16x32_bf16 v[10:13], v[162:165], v[200:203], v[154:157]
	v_mfma_f32_16x16x32_bf16 v[10:13], v[222:225], v[238:241], v[10:13]
	s_setprio 0
	s_cmpk_gt_u32 s0, 0xff
	s_barrier
	s_cbranch_scc1 .LBB0_352
	s_barrier

.LBB0_356:
	s_lshl_b32 s19, s19, 5
	v_and_b32_e32 v0, 15, v19
	s_and_b32 s19, s19, 0x60
	v_lshlrev_b32_e32 v14, 7, v0
	v_or_b32_e32 v0, s19, v0
	s_add_i32 s19, s1, 0x18000
	s_mov_b64 s[24:25], 0x80
	v_lshl_or_b32 v14, s20, 13, v14
	v_lshl_add_u64 v[2:3], v[2:3], 0, s[24:25]
	s_mov_b32 m0, s19
	s_add_i32 s20, s1, 0x1a000
	s_waitcnt vmcnt(4)
	s_barrier
	global_load_lds_dwordx4 v[2:3], off
	v_lshl_add_u64 v[2:3], v[4:5], 0, s[24:25]
	s_mov_b32 m0, s20
	s_add_i32 s21, s1, 0x8000
	global_load_lds_dwordx4 v[2:3], off
	v_lshl_add_u64 v[2:3], v[8:9], 0, s[24:25]
	s_mov_b32 m0, s21
	s_add_i32 s22, s1, 0xa000
	global_load_lds_dwordx4 v[2:3], off
	v_lshl_add_u64 v[2:3], v[6:7], 0, s[24:25]
	s_mov_b32 m0, s22
	s_add_i32 s23, s1, 0x1c000
	global_load_lds_dwordx4 v[2:3], off
	v_lshl_add_u64 v[2:3], v[12:13], 0, s[24:25]
	s_mov_b32 m0, s23
	v_and_b32_e32 v15, 3, v20
	global_load_lds_dwordx4 v[2:3], off
	v_lshl_add_u64 v[2:3], v[10:11], 0, s[24:25]
	s_add_i32 s24, s1, 0x1e000
	s_mov_b32 m0, s24
	v_bfe_u32 v19, v19, 1, 3
	global_load_lds_dwordx4 v[2:3], off
	v_bitop3_b32 v20, v20, v19, 3 bitop3:0x6c
	v_bitop3_b32 v15, v15, v19, 4 bitop3:0x36
	v_lshlrev_b32_e32 v20, 4, v20
	v_lshlrev_b32_e32 v15, 4, v15
	v_lshlrev_b32_e32 v0, 7, v0
	v_or_b32_e32 v150, v0, v20
	v_or_b32_e32 v151, v0, v15
	v_add_u32_e32 v0, v18, v16
	s_waitcnt vmcnt(6)
	v_lshlrev_b64 v[2:3], 1, v[0:1]
	v_add_u32_e32 v0, v17, v16
	v_lshl_add_u64 v[140:141], s[12:13], 0, v[2:3]
	v_lshlrev_b64 v[4:5], 1, v[0:1]
	v_lshl_add_u64 v[144:145], s[4:5], 0, v[2:3]
	v_mov_b32_e32 v2, 0
	v_or_b32_e32 v148, v20, v14
	v_or_b32_e32 v149, v15, v14
	v_lshl_add_u64 v[142:143], s[12:13], 0, v[4:5]
	v_lshl_add_u64 v[146:147], s[4:5], 0, v[4:5]
	s_mov_b32 s4, -2
	v_mov_b32_e32 v3, v2
	v_mov_b32_e32 v4, v2
	v_mov_b32_e32 v5, v2
	v_mov_b32_e32 v6, v2
	v_mov_b32_e32 v7, v2
	v_mov_b32_e32 v8, v2
	v_mov_b32_e32 v9, v2
	v_mov_b32_e32 v10, v2
	v_mov_b32_e32 v11, v2
	v_mov_b32_e32 v12, v2
	v_mov_b32_e32 v13, v2
	v_mov_b32_e32 v14, v2
	v_mov_b32_e32 v15, v2
	v_mov_b32_e32 v16, v2
	v_mov_b32_e32 v17, v2
	v_mov_b32_e32 v18, v2
	v_mov_b32_e32 v19, v2
	v_mov_b32_e32 v20, v2
	v_mov_b32_e32 v21, v2
	v_mov_b32_e32 v22, v2
	v_mov_b32_e32 v23, v2
	v_mov_b32_e32 v24, v2
	v_mov_b32_e32 v25, v2
	v_mov_b32_e32 v26, v2
	v_mov_b32_e32 v27, v2
	v_mov_b32_e32 v28, v2
	v_mov_b32_e32 v29, v2
	v_mov_b32_e32 v30, v2
	v_mov_b32_e32 v31, v2
	v_mov_b32_e32 v32, v2
	v_mov_b32_e32 v33, v2
	v_mov_b32_e32 v34, v2
	v_mov_b32_e32 v35, v2
	v_mov_b32_e32 v36, v2
	v_mov_b32_e32 v37, v2
	v_mov_b32_e32 v38, v2
	v_mov_b32_e32 v39, v2
	v_mov_b32_e32 v40, v2
	v_mov_b32_e32 v41, v2
	v_mov_b32_e32 v42, v2
	v_mov_b32_e32 v43, v2
	v_mov_b32_e32 v44, v2
	v_mov_b32_e32 v45, v2
	v_mov_b32_e32 v46, v2
	v_mov_b32_e32 v47, v2
	v_mov_b32_e32 v48, v2
	v_mov_b32_e32 v49, v2
	v_mov_b32_e32 v50, v2
	v_mov_b32_e32 v51, v2
	v_mov_b32_e32 v52, v2
	v_mov_b32_e32 v53, v2
	v_mov_b32_e32 v54, v2
	v_mov_b32_e32 v55, v2
	v_mov_b32_e32 v56, v2
	v_mov_b32_e32 v57, v2
	v_mov_b32_e32 v58, v2
	v_mov_b32_e32 v59, v2
	v_mov_b32_e32 v60, v2
	v_mov_b32_e32 v61, v2
	v_mov_b32_e32 v62, v2
	v_mov_b32_e32 v63, v2
	v_mov_b32_e32 v64, v2
	v_mov_b32_e32 v65, v2
	v_mov_b32_e32 v66, v2
	v_mov_b32_e32 v67, v2
	v_mov_b32_e32 v68, v2
	v_mov_b32_e32 v69, v2
	v_mov_b32_e32 v70, v2
	v_mov_b32_e32 v71, v2
	v_mov_b32_e32 v72, v2
	v_mov_b32_e32 v73, v2
	v_mov_b32_e32 v74, v2
	v_mov_b32_e32 v75, v2
	v_mov_b32_e32 v76, v2
	v_mov_b32_e32 v77, v2
	v_mov_b32_e32 v78, v2
	v_mov_b32_e32 v79, v2
	v_mov_b32_e32 v80, v2
	v_mov_b32_e32 v81, v2
	v_mov_b32_e32 v82, v2
	v_mov_b32_e32 v83, v2
	v_mov_b32_e32 v84, v2
	v_mov_b32_e32 v85, v2
	v_mov_b32_e32 v86, v2
	v_mov_b32_e32 v87, v2
	v_mov_b32_e32 v88, v2
	v_mov_b32_e32 v89, v2
	v_mov_b32_e32 v90, v2
	v_mov_b32_e32 v91, v2
	v_mov_b32_e32 v92, v2
	v_mov_b32_e32 v93, v2
	v_mov_b32_e32 v94, v2
	v_mov_b32_e32 v95, v2
	v_mov_b32_e32 v96, v2
	v_mov_b32_e32 v97, v2
	v_mov_b32_e32 v98, v2
	v_mov_b32_e32 v99, v2
	v_mov_b32_e32 v100, v2
	v_mov_b32_e32 v101, v2
	v_mov_b32_e32 v102, v2
	v_mov_b32_e32 v103, v2
	v_mov_b32_e32 v104, v2
	v_mov_b32_e32 v105, v2
	v_mov_b32_e32 v106, v2
	v_mov_b32_e32 v107, v2
	v_mov_b32_e32 v108, v2
	v_mov_b32_e32 v109, v2
	v_mov_b32_e32 v110, v2
	v_mov_b32_e32 v111, v2
	v_mov_b32_e32 v112, v2
	v_mov_b32_e32 v113, v2
	v_mov_b32_e32 v114, v2
	v_mov_b32_e32 v115, v2
	v_mov_b32_e32 v116, v2
	v_mov_b32_e32 v117, v2
	v_mov_b32_e32 v118, v2
	v_mov_b32_e32 v119, v2
	v_mov_b32_e32 v120, v2
	v_mov_b32_e32 v121, v2
	v_mov_b32_e32 v122, v2
	v_mov_b32_e32 v123, v2
	v_mov_b32_e32 v124, v2
	v_mov_b32_e32 v125, v2
	v_mov_b32_e32 v126, v2
	v_mov_b32_e32 v127, v2
	v_mov_b32_e32 v128, v2
	v_mov_b32_e32 v129, v2
	s_mov_b64 s[26:27], 0x82d4900
	s_mov_b64 s[28:29], 0x8254980
	s_mov_b64 s[30:31], 0x82d4980
	s_waitcnt lgkmcnt(0)
	s_sub_u32 s100, s100, 0x40000000
	s_subb_u32 s101, s101, 0
	s_mov_b64 vcc, s[100:101]
	v_lshl_add_u64 v[206:207], v[134:135], 0, v[142:143]
	v_subrev_u32_e32 v206, vcc_lo, v206
	v_lshl_add_u64 v[208:209], v[134:135], 0, v[140:141]
	v_subrev_u32_e32 v208, vcc_lo, v208
	v_lshl_add_u64 v[210:211], v[134:135], 0, v[146:147]
	v_subrev_u32_e32 v210, vcc_lo, v210
	v_lshl_add_u64 v[214:215], v[134:135], 0, v[144:145]
	v_subrev_u32_e32 v214, vcc_lo, v214
	v_add_u32_e32 v207, 0x10000, v150
	v_add_u32_e32 v209, 0x10000, v151
	v_add_u32_e32 v0, s50, v206
	v_add_u32_e32 v152, s54, v206
	v_add_u32_e32 v153, s58, v206
	v_add_u32_e32 v206, s62, v206
	v_add_u32_e32 v154, s50, v208
	v_add_u32_e32 v155, s54, v208
	v_add_u32_e32 v156, s58, v208
	v_add_u32_e32 v208, s62, v208
	v_add_u32_e32 v157, s70, v210
	v_add_u32_e32 v158, s26, v210
	v_add_u32_e32 v159, s28, v210
	v_add_u32_e32 v210, s30, v210
	v_add_u32_e32 v211, s70, v214
	v_add_u32_e32 v215, s26, v214
	v_add_u32_e32 v246, s28, v214
	v_add_u32_e32 v214, s30, v214
	s_add_i32 s12, s1, 0xc000
	s_add_i32 s5, s1, 0xe000
	s_barrier
.LBB0_357:
	ds_read_b128 v[160:163], v207
	ds_read_b128 v[164:167], v209
	ds_read_b128 v[168:171], v207 offset:2048
	ds_read_b128 v[172:175], v209 offset:2048
	ds_read_b128 v[176:179], v148
	ds_read_b128 v[180:183], v148 offset:2048
	ds_read_b128 v[184:187], v149
	ds_read_b128 v[188:191], v149 offset:2048
	ds_read_b128 v[192:195], v148 offset:4096
	ds_read_b128 v[196:199], v148 offset:6144
	s_mov_b32 m0, s12
	ds_read_b128 v[200:203], v149 offset:4096
	global_load_lds_dwordx4 v0, vcc
	s_mov_b32 m0, s5
	ds_read_b128 v[218:221], v149 offset:6144
	global_load_lds_dwordx4 v154, vcc
	s_waitcnt vmcnt(10) lgkmcnt(8)
	s_barrier
	s_waitcnt lgkmcnt(0)
	v_mfma_f32_16x16x32_bf16 v[126:129], v[160:163], v[176:179], v[126:129]
	v_mfma_f32_16x16x32_bf16 v[122:125], v[168:171], v[176:179], v[122:125]
	v_mfma_f32_16x16x32_bf16 v[118:121], v[160:163], v[180:183], v[118:121]
	v_mfma_f32_16x16x32_bf16 v[114:117], v[168:171], v[180:183], v[114:117]
	v_mfma_f32_16x16x32_bf16 v[110:113], v[160:163], v[192:195], v[110:113]
	v_mfma_f32_16x16x32_bf16 v[106:109], v[168:171], v[192:195], v[106:109]
	v_mfma_f32_16x16x32_bf16 v[102:105], v[160:163], v[196:199], v[102:105]
	v_mfma_f32_16x16x32_bf16 v[98:101], v[168:171], v[196:199], v[98:101]
	v_mfma_f32_16x16x32_bf16 v[126:129], v[164:167], v[184:187], v[126:129]
	v_mfma_f32_16x16x32_bf16 v[122:125], v[172:175], v[184:187], v[122:125]
	v_mfma_f32_16x16x32_bf16 v[118:121], v[164:167], v[188:191], v[118:121]
	v_mfma_f32_16x16x32_bf16 v[114:117], v[172:175], v[188:191], v[114:117]
	v_mfma_f32_16x16x32_bf16 v[110:113], v[164:167], v[200:203], v[110:113]
	v_mfma_f32_16x16x32_bf16 v[106:109], v[172:175], v[200:203], v[106:109]
	v_mfma_f32_16x16x32_bf16 v[102:105], v[164:167], v[218:221], v[102:105]
	v_mfma_f32_16x16x32_bf16 v[98:101], v[172:175], v[218:221], v[98:101]
	s_barrier
	ds_read_b128 v[222:225], v207 offset:16384
	ds_read_b128 v[226:229], v209 offset:16384
	s_mov_b32 m0, s2
	ds_read_b128 v[230:233], v207 offset:18432
	global_load_lds_dwordx4 v157, vcc
	s_mov_b32 m0, s3
	ds_read_b128 v[234:237], v209 offset:18432
	global_load_lds_dwordx4 v211, vcc
	s_waitcnt vmcnt(10) lgkmcnt(0)
	s_barrier
	v_mfma_f32_16x16x32_bf16 v[94:97], v[222:225], v[176:179], v[94:97]
	v_mfma_f32_16x16x32_bf16 v[90:93], v[230:233], v[176:179], v[90:93]
	v_mfma_f32_16x16x32_bf16 v[86:89], v[222:225], v[180:183], v[86:89]
	v_mfma_f32_16x16x32_bf16 v[82:85], v[230:233], v[180:183], v[82:85]
	v_mfma_f32_16x16x32_bf16 v[78:81], v[222:225], v[192:195], v[78:81]
	v_mfma_f32_16x16x32_bf16 v[74:77], v[230:233], v[192:195], v[74:77]
	v_mfma_f32_16x16x32_bf16 v[70:73], v[222:225], v[196:199], v[70:73]
	v_mfma_f32_16x16x32_bf16 v[66:69], v[230:233], v[196:199], v[66:69]
	v_mfma_f32_16x16x32_bf16 v[94:97], v[226:229], v[184:187], v[94:97]
	v_mfma_f32_16x16x32_bf16 v[90:93], v[234:237], v[184:187], v[90:93]
	v_mfma_f32_16x16x32_bf16 v[86:89], v[226:229], v[188:191], v[86:89]
	v_mfma_f32_16x16x32_bf16 v[82:85], v[234:237], v[188:191], v[82:85]
	v_mfma_f32_16x16x32_bf16 v[78:81], v[226:229], v[200:203], v[78:81]
	v_mfma_f32_16x16x32_bf16 v[74:77], v[234:237], v[200:203], v[74:77]
	v_mfma_f32_16x16x32_bf16 v[70:73], v[226:229], v[218:221], v[70:73]
	v_mfma_f32_16x16x32_bf16 v[66:69], v[234:237], v[218:221], v[66:69]
	s_barrier
	ds_read_b128 v[176:179], v148 offset:16384
	ds_read_b128 v[180:183], v148 offset:18432
	ds_read_b128 v[184:187], v149 offset:16384
	ds_read_b128 v[188:191], v149 offset:18432
	s_mov_b32 m0, s1
	ds_read_b128 v[192:195], v148 offset:20480
	global_load_lds_dwordx4 v152, vcc
	s_mov_b32 m0, s11
	ds_read_b128 v[196:199], v148 offset:22528
	global_load_lds_dwordx4 v155, vcc
	s_mov_b32 m0, s15
	ds_read_b128 v[200:203], v149 offset:20480
	global_load_lds_dwordx4 v158, vcc
	s_mov_b32 m0, s16
	ds_read_b128 v[218:221], v149 offset:22528
	global_load_lds_dwordx4 v215, vcc
	s_waitcnt vmcnt(10) lgkmcnt(0)
	s_barrier
	v_mfma_f32_16x16x32_bf16 v[62:65], v[160:163], v[176:179], v[62:65]
	v_mfma_f32_16x16x32_bf16 v[58:61], v[168:171], v[176:179], v[58:61]
	v_mfma_f32_16x16x32_bf16 v[54:57], v[160:163], v[180:183], v[54:57]
	v_mfma_f32_16x16x32_bf16 v[50:53], v[168:171], v[180:183], v[50:53]
	v_mfma_f32_16x16x32_bf16 v[46:49], v[160:163], v[192:195], v[46:49]
	v_mfma_f32_16x16x32_bf16 v[42:45], v[168:171], v[192:195], v[42:45]
	v_mfma_f32_16x16x32_bf16 v[38:41], v[160:163], v[196:199], v[38:41]
	v_mfma_f32_16x16x32_bf16 v[34:37], v[168:171], v[196:199], v[34:37]
	v_mfma_f32_16x16x32_bf16 v[62:65], v[164:167], v[184:187], v[62:65]
	v_mfma_f32_16x16x32_bf16 v[58:61], v[172:175], v[184:187], v[58:61]
	v_mfma_f32_16x16x32_bf16 v[54:57], v[164:167], v[188:191], v[54:57]
	v_mfma_f32_16x16x32_bf16 v[50:53], v[172:175], v[188:191], v[50:53]
	v_mfma_f32_16x16x32_bf16 v[46:49], v[164:167], v[200:203], v[46:49]
	v_mfma_f32_16x16x32_bf16 v[42:45], v[172:175], v[200:203], v[42:45]
	v_mfma_f32_16x16x32_bf16 v[38:41], v[164:167], v[218:221], v[38:41]
	v_mfma_f32_16x16x32_bf16 v[34:37], v[172:175], v[218:221], v[34:37]
	v_mfma_f32_16x16x32_bf16 v[30:33], v[222:225], v[176:179], v[30:33]
	v_mfma_f32_16x16x32_bf16 v[26:29], v[230:233], v[176:179], v[26:29]
	v_mfma_f32_16x16x32_bf16 v[22:25], v[222:225], v[180:183], v[22:25]
	v_mfma_f32_16x16x32_bf16 v[18:21], v[230:233], v[180:183], v[18:21]
	v_mfma_f32_16x16x32_bf16 v[14:17], v[222:225], v[192:195], v[14:17]
	v_mfma_f32_16x16x32_bf16 v[10:13], v[230:233], v[192:195], v[10:13]
	v_mfma_f32_16x16x32_bf16 v[6:9], v[222:225], v[196:199], v[6:9]
	v_mfma_f32_16x16x32_bf16 v[2:5], v[230:233], v[196:199], v[2:5]
	v_mfma_f32_16x16x32_bf16 v[30:33], v[226:229], v[184:187], v[30:33]
	v_mfma_f32_16x16x32_bf16 v[26:29], v[234:237], v[184:187], v[26:29]
	v_mfma_f32_16x16x32_bf16 v[22:25], v[226:229], v[188:191], v[22:25]
	v_mfma_f32_16x16x32_bf16 v[18:21], v[234:237], v[188:191], v[18:21]
	v_mfma_f32_16x16x32_bf16 v[14:17], v[226:229], v[200:203], v[14:17]
	v_mfma_f32_16x16x32_bf16 v[10:13], v[234:237], v[200:203], v[10:13]
	v_mfma_f32_16x16x32_bf16 v[6:9], v[226:229], v[218:221], v[6:9]
	v_mfma_f32_16x16x32_bf16 v[2:5], v[234:237], v[218:221], v[2:5]
	s_barrier
	ds_read_b128 v[168:171], v207 offset:32768
	ds_read_b128 v[172:175], v209 offset:32768
	ds_read_b128 v[176:179], v207 offset:34816
	ds_read_b128 v[180:183], v209 offset:34816
	ds_read_b128 v[184:187], v148 offset:32768
	ds_read_b128 v[188:191], v148 offset:34816
	ds_read_b128 v[192:195], v149 offset:32768
	ds_read_b128 v[196:199], v149 offset:34816
	ds_read_b128 v[200:203], v148 offset:36864
	ds_read_b128 v[218:221], v148 offset:38912
	s_mov_b32 m0, s17
	ds_read_b128 v[222:225], v149 offset:36864
	global_load_lds_dwordx4 v153, vcc
	s_mov_b32 m0, s18
	ds_read_b128 v[226:229], v149 offset:38912
	global_load_lds_dwordx4 v156, vcc
	s_waitcnt vmcnt(10) lgkmcnt(8)
	s_barrier
	s_waitcnt lgkmcnt(0)
	v_mfma_f32_16x16x32_bf16 v[126:129], v[168:171], v[184:187], v[126:129]
	v_mfma_f32_16x16x32_bf16 v[122:125], v[176:179], v[184:187], v[122:125]
	v_mfma_f32_16x16x32_bf16 v[118:121], v[168:171], v[188:191], v[118:121]
	v_mfma_f32_16x16x32_bf16 v[114:117], v[176:179], v[188:191], v[114:117]
	v_mfma_f32_16x16x32_bf16 v[110:113], v[168:171], v[200:203], v[110:113]
	v_mfma_f32_16x16x32_bf16 v[106:109], v[176:179], v[200:203], v[106:109]
	v_mfma_f32_16x16x32_bf16 v[102:105], v[168:171], v[218:221], v[102:105]
	v_mfma_f32_16x16x32_bf16 v[98:101], v[176:179], v[218:221], v[98:101]
	v_mfma_f32_16x16x32_bf16 v[126:129], v[172:175], v[192:195], v[126:129]
	v_mfma_f32_16x16x32_bf16 v[122:125], v[180:183], v[192:195], v[122:125]
	v_mfma_f32_16x16x32_bf16 v[118:121], v[172:175], v[196:199], v[118:121]
	v_mfma_f32_16x16x32_bf16 v[114:117], v[180:183], v[196:199], v[114:117]
	v_mfma_f32_16x16x32_bf16 v[110:113], v[172:175], v[222:225], v[110:113]
	v_mfma_f32_16x16x32_bf16 v[106:109], v[180:183], v[222:225], v[106:109]
	v_mfma_f32_16x16x32_bf16 v[102:105], v[172:175], v[226:229], v[102:105]
	v_mfma_f32_16x16x32_bf16 v[98:101], v[180:183], v[226:229], v[98:101]
	s_barrier
	ds_read_b128 v[230:233], v207 offset:49152
	ds_read_b128 v[234:237], v209 offset:49152
	s_mov_b32 m0, s19
	ds_read_b128 v[238:241], v207 offset:51200
	global_load_lds_dwordx4 v159, vcc
	s_mov_b32 m0, s20
	ds_read_b128 v[242:245], v209 offset:51200
	global_load_lds_dwordx4 v246, vcc
	s_waitcnt vmcnt(10) lgkmcnt(0)
	s_barrier
	v_mfma_f32_16x16x32_bf16 v[94:97], v[230:233], v[184:187], v[94:97]
	v_mfma_f32_16x16x32_bf16 v[90:93], v[238:241], v[184:187], v[90:93]
	v_mfma_f32_16x16x32_bf16 v[86:89], v[230:233], v[188:191], v[86:89]
	v_mfma_f32_16x16x32_bf16 v[82:85], v[238:241], v[188:191], v[82:85]
	v_mfma_f32_16x16x32_bf16 v[78:81], v[230:233], v[200:203], v[78:81]
	v_mfma_f32_16x16x32_bf16 v[74:77], v[238:241], v[200:203], v[74:77]
	v_mfma_f32_16x16x32_bf16 v[70:73], v[230:233], v[218:221], v[70:73]
	v_mfma_f32_16x16x32_bf16 v[66:69], v[238:241], v[218:221], v[66:69]
	v_mfma_f32_16x16x32_bf16 v[94:97], v[234:237], v[192:195], v[94:97]
	v_mfma_f32_16x16x32_bf16 v[90:93], v[242:245], v[192:195], v[90:93]
	v_mfma_f32_16x16x32_bf16 v[86:89], v[234:237], v[196:199], v[86:89]
	v_mfma_f32_16x16x32_bf16 v[82:85], v[242:245], v[196:199], v[82:85]
	v_mfma_f32_16x16x32_bf16 v[78:81], v[234:237], v[222:225], v[78:81]
	v_mfma_f32_16x16x32_bf16 v[74:77], v[242:245], v[222:225], v[74:77]
	v_mfma_f32_16x16x32_bf16 v[70:73], v[234:237], v[226:229], v[70:73]
	v_mfma_f32_16x16x32_bf16 v[66:69], v[242:245], v[226:229], v[66:69]
	s_barrier
	ds_read_b128 v[184:187], v148 offset:49152
	ds_read_b128 v[188:191], v148 offset:51200
	ds_read_b128 v[192:195], v149 offset:49152
	ds_read_b128 v[196:199], v149 offset:51200
	s_mov_b32 m0, s21
	ds_read_b128 v[200:203], v148 offset:53248
	global_load_lds_dwordx4 v206, vcc
	s_mov_b32 m0, s22
	ds_read_b128 v[218:221], v148 offset:55296
	global_load_lds_dwordx4 v208, vcc
	s_mov_b32 m0, s23
	ds_read_b128 v[222:225], v149 offset:53248
	global_load_lds_dwordx4 v210, vcc
	s_mov_b32 m0, s24
	ds_read_b128 v[226:229], v149 offset:55296
	global_load_lds_dwordx4 v214, vcc
	s_waitcnt vmcnt(10) lgkmcnt(0)
	s_barrier
	v_mfma_f32_16x16x32_bf16 v[62:65], v[168:171], v[184:187], v[62:65]
	v_mfma_f32_16x16x32_bf16 v[58:61], v[176:179], v[184:187], v[58:61]
	v_mfma_f32_16x16x32_bf16 v[54:57], v[168:171], v[188:191], v[54:57]
	v_mfma_f32_16x16x32_bf16 v[50:53], v[176:179], v[188:191], v[50:53]
	v_mfma_f32_16x16x32_bf16 v[46:49], v[168:171], v[200:203], v[46:49]
	v_mfma_f32_16x16x32_bf16 v[42:45], v[176:179], v[200:203], v[42:45]
	v_mfma_f32_16x16x32_bf16 v[38:41], v[168:171], v[218:221], v[38:41]
	v_mfma_f32_16x16x32_bf16 v[34:37], v[176:179], v[218:221], v[34:37]
	v_mfma_f32_16x16x32_bf16 v[62:65], v[172:175], v[192:195], v[62:65]
	v_mfma_f32_16x16x32_bf16 v[58:61], v[180:183], v[192:195], v[58:61]
	v_mfma_f32_16x16x32_bf16 v[54:57], v[172:175], v[196:199], v[54:57]
	v_mfma_f32_16x16x32_bf16 v[50:53], v[180:183], v[196:199], v[50:53]
	v_mfma_f32_16x16x32_bf16 v[46:49], v[172:175], v[222:225], v[46:49]
	v_mfma_f32_16x16x32_bf16 v[42:45], v[180:183], v[222:225], v[42:45]
	v_mfma_f32_16x16x32_bf16 v[38:41], v[172:175], v[226:229], v[38:41]
	v_mfma_f32_16x16x32_bf16 v[34:37], v[180:183], v[226:229], v[34:37]
	v_mfma_f32_16x16x32_bf16 v[30:33], v[230:233], v[184:187], v[30:33]
	v_mfma_f32_16x16x32_bf16 v[26:29], v[238:241], v[184:187], v[26:29]
	v_mfma_f32_16x16x32_bf16 v[22:25], v[230:233], v[188:191], v[22:25]
	v_mfma_f32_16x16x32_bf16 v[18:21], v[238:241], v[188:191], v[18:21]
	v_mfma_f32_16x16x32_bf16 v[14:17], v[230:233], v[200:203], v[14:17]
	v_mfma_f32_16x16x32_bf16 v[10:13], v[238:241], v[200:203], v[10:13]
	v_mfma_f32_16x16x32_bf16 v[6:9], v[230:233], v[218:221], v[6:9]
	v_mfma_f32_16x16x32_bf16 v[2:5], v[238:241], v[218:221], v[2:5]
	v_mfma_f32_16x16x32_bf16 v[30:33], v[234:237], v[192:195], v[30:33]
	v_mfma_f32_16x16x32_bf16 v[26:29], v[242:245], v[192:195], v[26:29]
	v_mfma_f32_16x16x32_bf16 v[22:25], v[234:237], v[196:199], v[22:25]
	v_mfma_f32_16x16x32_bf16 v[18:21], v[242:245], v[196:199], v[18:21]
	v_mfma_f32_16x16x32_bf16 v[14:17], v[234:237], v[222:225], v[14:17]
	v_mfma_f32_16x16x32_bf16 v[10:13], v[242:245], v[222:225], v[10:13]
	v_mfma_f32_16x16x32_bf16 v[6:9], v[234:237], v[226:229], v[6:9]
	v_mfma_f32_16x16x32_bf16 v[2:5], v[242:245], v[226:229], v[2:5]
	s_add_u32 vcc_lo, vcc_lo, s54
	s_addc_u32 vcc_hi, vcc_hi, s55
	s_add_i32 s4, s4, 2
	s_cmp_lt_u32 s4, 28
	v_lshl_add_u64 v[134:135], v[134:135], 0, s[54:55]
	s_barrier
	s_cbranch_scc1 .LBB0_357
	s_waitcnt vmcnt(6)
	v_or_b32_e32 v0, 0x10000, v150
	v_add_u32_e32 v153, 0x10800, v150
	v_or_b32_e32 v152, 0x10000, v151
	v_add_u32_e32 v154, 0x10800, v151
	v_or_b32_e32 v155, 0x14000, v150
	v_add_u32_e32 v157, 0x14800, v150
	v_or_b32_e32 v156, 0x14000, v151
	v_add_u32_e32 v158, 0x14800, v151
	v_or_b32_e32 v159, 0x18000, v150
	v_add_u32_e32 v161, 0x18800, v150
	v_or_b32_e32 v160, 0x18000, v151
	v_add_u32_e32 v162, 0x18800, v151
	v_or_b32_e32 v163, 0x1c000, v150
	v_add_u32_e32 v165, 0x1c800, v150
	v_or_b32_e32 v164, 0x1c000, v151
	v_add_u32_e32 v166, 0x1c800, v151
	s_mov_b64 s[2:3], 0xf80
	s_mov_b32 m0, s12
	v_lshl_add_u64 v[134:135], v[138:139], 0, s[2:3]
	ds_read_b128 v[140:143], v0
	ds_read_b128 v[144:147], v152
	ds_read_b128 v[150:153], v153
	ds_read_b128 v[168:171], v154
	ds_read_b128 v[172:175], v148
	ds_read_b128 v[176:179], v148 offset:2048
	ds_read_b128 v[180:183], v149
	ds_read_b128 v[184:187], v149 offset:2048
	ds_read_b128 v[188:191], v148 offset:4096
	ds_read_b128 v[192:195], v148 offset:6144
	ds_read_b128 v[196:199], v149 offset:4096
	ds_read_b128 v[200:203], v149 offset:6144
	global_load_lds_dwordx4 v[134:135], off
	v_lshl_add_u64 v[134:135], v[136:137], 0, s[2:3]
	s_mov_b32 m0, s5
	s_nop 0
	global_load_lds_dwordx4 v[134:135], off
	s_barrier
	s_waitcnt lgkmcnt(0)
	s_setprio 1
	s_waitcnt lgkmcnt(0)
	v_mfma_f32_16x16x32_bf16 v[126:129], v[140:143], v[172:175], v[126:129]
	v_mfma_f32_16x16x32_bf16 v[122:125], v[150:153], v[172:175], v[122:125]
	v_mfma_f32_16x16x32_bf16 v[118:121], v[140:143], v[176:179], v[118:121]
	v_mfma_f32_16x16x32_bf16 v[110:113], v[140:143], v[188:191], v[110:113]
	v_mfma_f32_16x16x32_bf16 v[106:109], v[150:153], v[188:191], v[106:109]
	v_mfma_f32_16x16x32_bf16 v[126:129], v[144:147], v[180:183], v[126:129]
	v_mfma_f32_16x16x32_bf16 v[122:125], v[168:171], v[180:183], v[122:125]
	v_mfma_f32_16x16x32_bf16 v[118:121], v[144:147], v[184:187], v[118:121]
	v_mfma_f32_16x16x32_bf16 v[114:117], v[150:153], v[176:179], v[114:117]
	v_mfma_f32_16x16x32_bf16 v[110:113], v[144:147], v[196:199], v[110:113]
	v_mfma_f32_16x16x32_bf16 v[106:109], v[168:171], v[196:199], v[106:109]
	v_mfma_f32_16x16x32_bf16 v[102:105], v[140:143], v[192:195], v[102:105]
	v_mfma_f32_16x16x32_bf16 v[98:101], v[150:153], v[192:195], v[98:101]
	v_mfma_f32_16x16x32_bf16 v[134:137], v[168:171], v[184:187], v[114:117]
	v_mfma_f32_16x16x32_bf16 v[218:221], v[144:147], v[200:203], v[102:105]
	v_mfma_f32_16x16x32_bf16 v[222:225], v[168:171], v[200:203], v[98:101]
	s_setprio 0
	s_barrier
	s_nop 2
	ds_read_b128 v[98:101], v155
	ds_read_b128 v[102:105], v156
	ds_read_b128 v[114:117], v157
	ds_read_b128 v[154:157], v158
	s_barrier
	s_waitcnt lgkmcnt(0)
	s_setprio 1
	s_waitcnt lgkmcnt(0)
	v_mfma_f32_16x16x32_bf16 v[94:97], v[98:101], v[172:175], v[94:97]
	v_mfma_f32_16x16x32_bf16 v[90:93], v[114:117], v[172:175], v[90:93]
	v_mfma_f32_16x16x32_bf16 v[78:81], v[98:101], v[188:191], v[78:81]
	v_mfma_f32_16x16x32_bf16 v[74:77], v[114:117], v[188:191], v[74:77]
	v_mfma_f32_16x16x32_bf16 v[94:97], v[102:105], v[180:183], v[94:97]
	v_mfma_f32_16x16x32_bf16 v[90:93], v[154:157], v[180:183], v[90:93]
	v_mfma_f32_16x16x32_bf16 v[86:89], v[98:101], v[176:179], v[86:89]
	v_mfma_f32_16x16x32_bf16 v[82:85], v[114:117], v[176:179], v[82:85]
	v_mfma_f32_16x16x32_bf16 v[78:81], v[102:105], v[196:199], v[78:81]
	v_mfma_f32_16x16x32_bf16 v[74:77], v[154:157], v[196:199], v[74:77]
	v_mfma_f32_16x16x32_bf16 v[70:73], v[98:101], v[192:195], v[70:73]
	v_mfma_f32_16x16x32_bf16 v[66:69], v[114:117], v[192:195], v[66:69]
	v_mfma_f32_16x16x32_bf16 v[172:175], v[102:105], v[184:187], v[86:89]
	v_mfma_f32_16x16x32_bf16 v[176:179], v[154:157], v[184:187], v[82:85]
	v_mfma_f32_16x16x32_bf16 v[180:183], v[102:105], v[200:203], v[70:73]
	v_mfma_f32_16x16x32_bf16 v[184:187], v[154:157], v[200:203], v[66:69]
	s_setprio 0
	s_barrier
	s_nop 1
	ds_read_b128 v[66:69], v148 offset:16384
	ds_read_b128 v[70:73], v148 offset:18432
	ds_read_b128 v[82:85], v149 offset:16384
	ds_read_b128 v[86:89], v149 offset:18432
	ds_read_b128 v[188:191], v148 offset:20480
	ds_read_b128 v[192:195], v148 offset:22528
	ds_read_b128 v[196:199], v149 offset:20480
	ds_read_b128 v[200:203], v149 offset:22528
	s_waitcnt vmcnt(4)
	s_barrier
	s_waitcnt lgkmcnt(0)
	s_setprio 1
	s_waitcnt lgkmcnt(0)
	v_mfma_f32_16x16x32_bf16 v[62:65], v[140:143], v[66:69], v[62:65]
	v_mfma_f32_16x16x32_bf16 v[58:61], v[150:153], v[66:69], v[58:61]
	v_mfma_f32_16x16x32_bf16 v[46:49], v[140:143], v[188:191], v[46:49]
	v_mfma_f32_16x16x32_bf16 v[42:45], v[150:153], v[188:191], v[42:45]
	v_mfma_f32_16x16x32_bf16 v[62:65], v[144:147], v[82:85], v[62:65]
	v_mfma_f32_16x16x32_bf16 v[58:61], v[168:171], v[82:85], v[58:61]
	v_mfma_f32_16x16x32_bf16 v[54:57], v[140:143], v[70:73], v[54:57]
	v_mfma_f32_16x16x32_bf16 v[50:53], v[150:153], v[70:73], v[50:53]
	v_mfma_f32_16x16x32_bf16 v[46:49], v[144:147], v[196:199], v[46:49]
	v_mfma_f32_16x16x32_bf16 v[42:45], v[168:171], v[196:199], v[42:45]
	v_mfma_f32_16x16x32_bf16 v[38:41], v[140:143], v[192:195], v[38:41]
	v_mfma_f32_16x16x32_bf16 v[34:37], v[150:153], v[192:195], v[34:37]
	v_mfma_f32_16x16x32_bf16 v[226:229], v[144:147], v[86:89], v[54:57]
	v_mfma_f32_16x16x32_bf16 v[230:233], v[168:171], v[86:89], v[50:53]
	v_mfma_f32_16x16x32_bf16 v[138:141], v[144:147], v[200:203], v[38:41]
	v_mfma_f32_16x16x32_bf16 v[142:145], v[168:171], v[200:203], v[34:37]
	s_setprio 0
	s_setprio 1
	v_mfma_f32_16x16x32_bf16 v[30:33], v[98:101], v[66:69], v[30:33]
	v_mfma_f32_16x16x32_bf16 v[26:29], v[114:117], v[66:69], v[26:29]
	v_mfma_f32_16x16x32_bf16 v[14:17], v[98:101], v[188:191], v[14:17]
	v_mfma_f32_16x16x32_bf16 v[10:13], v[114:117], v[188:191], v[10:13]
	v_mfma_f32_16x16x32_bf16 v[30:33], v[102:105], v[82:85], v[30:33]
	v_mfma_f32_16x16x32_bf16 v[26:29], v[154:157], v[82:85], v[26:29]
	v_mfma_f32_16x16x32_bf16 v[22:25], v[98:101], v[70:73], v[22:25]
	v_mfma_f32_16x16x32_bf16 v[18:21], v[114:117], v[70:73], v[18:21]
	v_mfma_f32_16x16x32_bf16 v[14:17], v[102:105], v[196:199], v[14:17]
	v_mfma_f32_16x16x32_bf16 v[10:13], v[154:157], v[196:199], v[10:13]
	v_mfma_f32_16x16x32_bf16 v[6:9], v[98:101], v[192:195], v[6:9]
	v_mfma_f32_16x16x32_bf16 v[2:5], v[114:117], v[192:195], v[2:5]
	v_mfma_f32_16x16x32_bf16 v[150:153], v[102:105], v[86:89], v[22:25]
	v_mfma_f32_16x16x32_bf16 v[168:171], v[154:157], v[86:89], v[18:21]
	v_mfma_f32_16x16x32_bf16 v[188:191], v[102:105], v[200:203], v[6:9]
	v_mfma_f32_16x16x32_bf16 v[154:157], v[154:157], v[200:203], v[2:5]
	s_setprio 0
	s_barrier
	s_nop 1
	ds_read_b128 v[2:5], v159
	ds_read_b128 v[6:9], v160
	ds_read_b128 v[158:161], v161
	ds_read_b128 v[192:195], v162
	ds_read_b128 v[18:21], v148 offset:32768
	ds_read_b128 v[22:25], v148 offset:34816
	ds_read_b128 v[34:37], v149 offset:32768
	ds_read_b128 v[38:41], v149 offset:34816
	ds_read_b128 v[50:53], v148 offset:36864
	ds_read_b128 v[54:57], v148 offset:38912
	ds_read_b128 v[196:199], v149 offset:36864
	ds_read_b128 v[200:203], v149 offset:38912
	s_waitcnt vmcnt(2)
	s_barrier
	s_waitcnt lgkmcnt(0)
	s_setprio 1
	s_waitcnt lgkmcnt(0)
	v_mfma_f32_16x16x32_bf16 v[66:69], v[2:5], v[18:21], v[126:129]
	v_mfma_f32_16x16x32_bf16 v[126:129], v[6:9], v[34:37], v[66:69]
	v_mfma_f32_16x16x32_bf16 v[66:69], v[158:161], v[18:21], v[122:125]
	v_mfma_f32_16x16x32_bf16 v[114:117], v[192:195], v[34:37], v[66:69]
	v_mfma_f32_16x16x32_bf16 v[66:69], v[2:5], v[22:25], v[118:121]
	v_mfma_f32_16x16x32_bf16 v[102:105], v[6:9], v[38:41], v[66:69]
	v_mfma_f32_16x16x32_bf16 v[66:69], v[158:161], v[22:25], v[134:137]
	v_mfma_f32_16x16x32_bf16 v[98:101], v[192:195], v[38:41], v[66:69]
	v_mfma_f32_16x16x32_bf16 v[66:69], v[2:5], v[50:53], v[110:113]
	v_mfma_f32_16x16x32_bf16 v[86:89], v[6:9], v[196:199], v[66:69]
	v_mfma_f32_16x16x32_bf16 v[66:69], v[158:161], v[50:53], v[106:109]
	v_mfma_f32_16x16x32_bf16 v[82:85], v[192:195], v[196:199], v[66:69]
	v_mfma_f32_16x16x32_bf16 v[66:69], v[2:5], v[54:57], v[218:221]
	v_mfma_f32_16x16x32_bf16 v[70:73], v[6:9], v[200:203], v[66:69]
	v_mfma_f32_16x16x32_bf16 v[66:69], v[158:161], v[54:57], v[222:225]
	v_mfma_f32_16x16x32_bf16 v[66:69], v[192:195], v[200:203], v[66:69]
	s_setprio 0
	s_barrier
	ds_read_b128 v[134:137], v163
	ds_read_b128 v[218:221], v164
	ds_read_b128 v[162:165], v165
	ds_read_b128 v[222:225], v166
	s_waitcnt vmcnt(0)
	s_barrier
	s_waitcnt lgkmcnt(0)
	s_setprio 1
	s_waitcnt lgkmcnt(0)
	v_mfma_f32_16x16x32_bf16 v[94:97], v[134:137], v[18:21], v[94:97]
	v_mfma_f32_16x16x32_bf16 v[18:21], v[162:165], v[18:21], v[90:93]
	v_mfma_f32_16x16x32_bf16 v[118:121], v[222:225], v[34:37], v[18:21]
	v_mfma_f32_16x16x32_bf16 v[18:21], v[134:137], v[22:25], v[172:175]
	v_mfma_f32_16x16x32_bf16 v[110:113], v[218:221], v[38:41], v[18:21]
	v_mfma_f32_16x16x32_bf16 v[18:21], v[162:165], v[22:25], v[176:179]
	v_mfma_f32_16x16x32_bf16 v[106:109], v[222:225], v[38:41], v[18:21]
	v_mfma_f32_16x16x32_bf16 v[18:21], v[134:137], v[50:53], v[78:81]
	v_mfma_f32_16x16x32_bf16 v[122:125], v[218:221], v[34:37], v[94:97]
	v_mfma_f32_16x16x32_bf16 v[94:97], v[218:221], v[196:199], v[18:21]
	v_mfma_f32_16x16x32_bf16 v[18:21], v[162:165], v[50:53], v[74:77]
	v_mfma_f32_16x16x32_bf16 v[90:93], v[222:225], v[196:199], v[18:21]
	v_mfma_f32_16x16x32_bf16 v[18:21], v[134:137], v[54:57], v[180:183]
	v_mfma_f32_16x16x32_bf16 v[78:81], v[218:221], v[200:203], v[18:21]
	v_mfma_f32_16x16x32_bf16 v[18:21], v[162:165], v[54:57], v[184:187]
	v_mfma_f32_16x16x32_bf16 v[74:77], v[222:225], v[200:203], v[18:21]
	s_setprio 0
	s_barrier
	ds_read_b128 v[172:175], v148 offset:49152
	ds_read_b128 v[176:179], v148 offset:51200
	ds_read_b128 v[180:183], v149 offset:49152
	ds_read_b128 v[184:187], v149 offset:51200
	ds_read_b128 v[196:199], v148 offset:53248
	ds_read_b128 v[200:203], v148 offset:55296
	ds_read_b128 v[234:237], v149 offset:53248
	ds_read_b128 v[146:149], v149 offset:55296
	s_barrier
	s_waitcnt lgkmcnt(0)
	s_setprio 1
	s_waitcnt lgkmcnt(0)
	v_mfma_f32_16x16x32_bf16 v[18:21], v[2:5], v[172:175], v[62:65]
	v_mfma_f32_16x16x32_bf16 v[54:57], v[6:9], v[180:183], v[18:21]
	v_mfma_f32_16x16x32_bf16 v[18:21], v[158:161], v[172:175], v[58:61]
	v_mfma_f32_16x16x32_bf16 v[50:53], v[192:195], v[180:183], v[18:21]
	v_mfma_f32_16x16x32_bf16 v[18:21], v[2:5], v[176:179], v[226:229]
	v_mfma_f32_16x16x32_bf16 v[38:41], v[6:9], v[184:187], v[18:21]
	v_mfma_f32_16x16x32_bf16 v[18:21], v[158:161], v[176:179], v[230:233]
	v_mfma_f32_16x16x32_bf16 v[34:37], v[192:195], v[184:187], v[18:21]
	v_mfma_f32_16x16x32_bf16 v[18:21], v[2:5], v[196:199], v[46:49]
	v_mfma_f32_16x16x32_bf16 v[2:5], v[2:5], v[200:203], v[138:141]
	v_mfma_f32_16x16x32_bf16 v[22:25], v[6:9], v[234:237], v[18:21]
	v_mfma_f32_16x16x32_bf16 v[18:21], v[158:161], v[196:199], v[42:45]
	v_mfma_f32_16x16x32_bf16 v[6:9], v[6:9], v[146:149], v[2:5]
	v_mfma_f32_16x16x32_bf16 v[2:5], v[158:161], v[200:203], v[142:145]
	v_mfma_f32_16x16x32_bf16 v[18:21], v[192:195], v[234:237], v[18:21]
	v_mfma_f32_16x16x32_bf16 v[2:5], v[192:195], v[146:149], v[2:5]
	s_setprio 0
	s_setprio 1
	v_mfma_f32_16x16x32_bf16 v[26:29], v[162:165], v[172:175], v[26:29]
	v_mfma_f32_16x16x32_bf16 v[58:61], v[222:225], v[180:183], v[26:29]
	v_mfma_f32_16x16x32_bf16 v[26:29], v[134:137], v[176:179], v[150:153]
	v_mfma_f32_16x16x32_bf16 v[46:49], v[218:221], v[184:187], v[26:29]
	v_mfma_f32_16x16x32_bf16 v[26:29], v[162:165], v[176:179], v[168:171]
	v_mfma_f32_16x16x32_bf16 v[10:13], v[162:165], v[196:199], v[10:13]
	v_mfma_f32_16x16x32_bf16 v[30:33], v[134:137], v[172:175], v[30:33]
	v_mfma_f32_16x16x32_bf16 v[42:45], v[222:225], v[184:187], v[26:29]
	v_mfma_f32_16x16x32_bf16 v[14:17], v[134:137], v[196:199], v[14:17]
	v_mfma_f32_16x16x32_bf16 v[26:29], v[222:225], v[234:237], v[10:13]
	v_mfma_f32_16x16x32_bf16 v[10:13], v[134:137], v[200:203], v[188:191]
	v_mfma_f32_16x16x32_bf16 v[62:65], v[218:221], v[180:183], v[30:33]
	v_mfma_f32_16x16x32_bf16 v[30:33], v[218:221], v[234:237], v[14:17]
	v_mfma_f32_16x16x32_bf16 v[14:17], v[218:221], v[146:149], v[10:13]
	v_mfma_f32_16x16x32_bf16 v[10:13], v[162:165], v[200:203], v[154:157]
	v_mfma_f32_16x16x32_bf16 v[10:13], v[222:225], v[146:149], v[10:13]
	s_setprio 0
	s_cmpk_gt_u32 s0, 0xff
	s_barrier
	s_cbranch_scc1 .LBB0_329
	s_barrier
	s_branch .LBB0_329

.LBB0_596:
	s_lshl_b32 s19, s19, 5
	v_and_b32_e32 v0, 15, v17
	s_and_b32 s19, s19, 0x60
	v_lshlrev_b32_e32 v19, 7, v0
	v_or_b32_e32 v0, s19, v0
	s_add_i32 s19, s1, 0x18000
	s_mov_b64 s[24:25], 0x80
	v_lshl_or_b32 v19, s20, 13, v19
	v_lshl_add_u64 v[2:3], v[2:3], 0, s[24:25]
	s_mov_b32 m0, s19
	s_add_i32 s20, s1, 0x1a000
	s_waitcnt vmcnt(4)
	s_barrier
	global_load_lds_dwordx4 v[2:3], off
	v_lshl_add_u64 v[2:3], v[4:5], 0, s[24:25]
	s_mov_b32 m0, s20
	s_add_i32 s21, s1, 0x8000
	global_load_lds_dwordx4 v[2:3], off
	v_lshl_add_u64 v[2:3], v[8:9], 0, s[24:25]
	s_mov_b32 m0, s21
	s_add_i32 s22, s1, 0xa000
	global_load_lds_dwordx4 v[2:3], off nt
	v_lshl_add_u64 v[2:3], v[6:7], 0, s[24:25]
	s_mov_b32 m0, s22
	s_add_i32 s23, s1, 0x1c000
	global_load_lds_dwordx4 v[2:3], off nt
	v_lshl_add_u64 v[2:3], v[12:13], 0, s[24:25]
	s_mov_b32 m0, s23
	v_and_b32_e32 v20, 3, v18
	global_load_lds_dwordx4 v[2:3], off
	v_lshl_add_u64 v[2:3], v[10:11], 0, s[24:25]
	s_add_i32 s24, s1, 0x1e000
	s_mov_b32 m0, s24
	v_bfe_u32 v17, v17, 1, 3
	global_load_lds_dwordx4 v[2:3], off
	v_bitop3_b32 v18, v18, v17, 3 bitop3:0x6c
	v_bitop3_b32 v17, v20, v17, 4 bitop3:0x36
	v_lshlrev_b32_e32 v18, 4, v18
	v_lshlrev_b32_e32 v17, 4, v17
	v_lshlrev_b32_e32 v0, 7, v0
	v_or_b32_e32 v154, v0, v18
	v_or_b32_e32 v155, v0, v17
	v_add_u32_e32 v0, v16, v14
	s_waitcnt vmcnt(6)
	v_lshlrev_b64 v[2:3], 1, v[0:1]
	v_add_u32_e32 v0, v15, v14
	v_lshl_add_u64 v[142:143], s[8:9], 0, v[2:3]
	v_lshlrev_b64 v[4:5], 1, v[0:1]
	v_lshl_add_u64 v[146:147], s[10:11], 0, v[2:3]
	v_mov_b32_e32 v2, 0
	v_or_b32_e32 v152, v18, v19
	v_or_b32_e32 v153, v17, v19
	v_lshl_add_u64 v[144:145], s[8:9], 0, v[4:5]
	v_lshl_add_u64 v[148:149], s[10:11], 0, v[4:5]
	s_mov_b32 s10, -2
	v_mov_b64_e32 v[150:151], v[130:131]
	v_mov_b32_e32 v3, v2
	v_mov_b32_e32 v4, v2
	v_mov_b32_e32 v5, v2
	v_mov_b32_e32 v6, v2
	v_mov_b32_e32 v7, v2
	v_mov_b32_e32 v8, v2
	v_mov_b32_e32 v9, v2
	v_mov_b32_e32 v10, v2
	v_mov_b32_e32 v11, v2
	v_mov_b32_e32 v12, v2
	v_mov_b32_e32 v13, v2
	v_mov_b32_e32 v14, v2
	v_mov_b32_e32 v15, v2
	v_mov_b32_e32 v16, v2
	v_mov_b32_e32 v17, v2
	v_mov_b32_e32 v18, v2
	v_mov_b32_e32 v19, v2
	v_mov_b32_e32 v20, v2
	v_mov_b32_e32 v21, v2
	v_mov_b32_e32 v22, v2
	v_mov_b32_e32 v23, v2
	v_mov_b32_e32 v24, v2
	v_mov_b32_e32 v25, v2
	v_mov_b32_e32 v26, v2
	v_mov_b32_e32 v27, v2
	v_mov_b32_e32 v28, v2
	v_mov_b32_e32 v29, v2
	v_mov_b32_e32 v30, v2
	v_mov_b32_e32 v31, v2
	v_mov_b32_e32 v32, v2
	v_mov_b32_e32 v33, v2
	v_mov_b32_e32 v34, v2
	v_mov_b32_e32 v35, v2
	v_mov_b32_e32 v36, v2
	v_mov_b32_e32 v37, v2
	v_mov_b32_e32 v38, v2
	v_mov_b32_e32 v39, v2
	v_mov_b32_e32 v40, v2
	v_mov_b32_e32 v41, v2
	v_mov_b32_e32 v42, v2
	v_mov_b32_e32 v43, v2
	v_mov_b32_e32 v44, v2
	v_mov_b32_e32 v45, v2
	v_mov_b32_e32 v46, v2
	v_mov_b32_e32 v47, v2
	v_mov_b32_e32 v48, v2
	v_mov_b32_e32 v49, v2
	v_mov_b32_e32 v50, v2
	v_mov_b32_e32 v51, v2
	v_mov_b32_e32 v52, v2
	v_mov_b32_e32 v53, v2
	v_mov_b32_e32 v54, v2
	v_mov_b32_e32 v55, v2
	v_mov_b32_e32 v56, v2
	v_mov_b32_e32 v57, v2
	v_mov_b32_e32 v58, v2
	v_mov_b32_e32 v59, v2
	v_mov_b32_e32 v60, v2
	v_mov_b32_e32 v61, v2
	v_mov_b32_e32 v62, v2
	v_mov_b32_e32 v63, v2
	v_mov_b32_e32 v64, v2
	v_mov_b32_e32 v65, v2
	v_mov_b32_e32 v66, v2
	v_mov_b32_e32 v67, v2
	v_mov_b32_e32 v68, v2
	v_mov_b32_e32 v69, v2
	v_mov_b32_e32 v70, v2
	v_mov_b32_e32 v71, v2
	v_mov_b32_e32 v72, v2
	v_mov_b32_e32 v73, v2
	v_mov_b32_e32 v74, v2
	v_mov_b32_e32 v75, v2
	v_mov_b32_e32 v76, v2
	v_mov_b32_e32 v77, v2
	v_mov_b32_e32 v78, v2
	v_mov_b32_e32 v79, v2
	v_mov_b32_e32 v80, v2
	v_mov_b32_e32 v81, v2
	v_mov_b32_e32 v82, v2
	v_mov_b32_e32 v83, v2
	v_mov_b32_e32 v84, v2
	v_mov_b32_e32 v85, v2
	v_mov_b32_e32 v86, v2
	v_mov_b32_e32 v87, v2
	v_mov_b32_e32 v88, v2
	v_mov_b32_e32 v89, v2
	v_mov_b32_e32 v90, v2
	v_mov_b32_e32 v91, v2
	v_mov_b32_e32 v92, v2
	v_mov_b32_e32 v93, v2
	v_mov_b32_e32 v94, v2
	v_mov_b32_e32 v95, v2
	v_mov_b32_e32 v96, v2
	v_mov_b32_e32 v97, v2
	v_mov_b32_e32 v98, v2
	v_mov_b32_e32 v99, v2
	v_mov_b32_e32 v100, v2
	v_mov_b32_e32 v101, v2
	v_mov_b32_e32 v102, v2
	v_mov_b32_e32 v103, v2
	v_mov_b32_e32 v104, v2
	v_mov_b32_e32 v105, v2
	v_mov_b32_e32 v106, v2
	v_mov_b32_e32 v107, v2
	v_mov_b32_e32 v108, v2
	v_mov_b32_e32 v109, v2
	v_mov_b32_e32 v110, v2
	v_mov_b32_e32 v111, v2
	v_mov_b32_e32 v112, v2
	v_mov_b32_e32 v113, v2
	v_mov_b32_e32 v114, v2
	v_mov_b32_e32 v115, v2
	v_mov_b32_e32 v116, v2
	v_mov_b32_e32 v117, v2
	v_mov_b32_e32 v118, v2
	v_mov_b32_e32 v119, v2
	v_mov_b32_e32 v120, v2
	v_mov_b32_e32 v121, v2
	v_mov_b32_e32 v122, v2
	v_mov_b32_e32 v123, v2
	v_mov_b32_e32 v124, v2
	v_mov_b32_e32 v125, v2
	v_mov_b32_e32 v126, v2
	v_mov_b32_e32 v127, v2
	v_mov_b32_e32 v128, v2
	v_mov_b32_e32 v129, v2
	s_mov_b64 s[26:27], 0x263f4880
	s_mov_b64 s[30:31], 0x9a54900
	s_mov_b64 s[34:35], 0x26374900
	s_mov_b64 s[36:37], 0x9ad4900
	s_mov_b64 s[38:39], 0x263f4900
	s_mov_b64 s[40:41], 0x9a54980
	s_mov_b64 s[44:45], 0x26374980
	s_mov_b64 s[48:49], 0x9ad4980
	v_readfirstlane_b32 s100, v130
	v_readfirstlane_b32 s101, v131
	s_sub_u32 s100, s100, 0x40000000
	s_subb_u32 s101, s101, 0
	s_mov_b64 vcc, s[100:101]
	v_lshl_add_u64 v[210:211], v[150:151], 0, v[144:145]
	v_subrev_u32_e32 v210, vcc_lo, v210
	v_lshl_add_u64 v[214:215], v[150:151], 0, v[142:143]
	v_subrev_u32_e32 v214, vcc_lo, v214
	v_lshl_add_u64 v[246:247], v[150:151], 0, v[148:149]
	v_subrev_u32_e32 v246, vcc_lo, v246
	v_lshl_add_u64 v[248:249], v[150:151], 0, v[146:147]
	v_subrev_u32_e32 v248, vcc_lo, v248
	v_add_u32_e32 v211, 0x10000, v154
	v_add_u32_e32 v215, 0x10000, v155
	v_add_u32_e32 v0, s26, v210
	v_add_u32_e32 v156, s34, v210
	v_add_u32_e32 v157, s38, v210
	v_add_u32_e32 v210, s44, v210
	v_add_u32_e32 v158, s26, v214
	v_add_u32_e32 v159, s34, v214
	v_add_u32_e32 v160, s38, v214
	v_add_u32_e32 v214, s44, v214
	v_add_u32_e32 v161, s30, v246
	v_add_u32_e32 v162, s36, v246
	v_add_u32_e32 v163, s40, v246
	v_add_u32_e32 v246, s48, v246
	v_add_u32_e32 v247, s30, v248
	v_add_u32_e32 v249, s36, v248
	v_add_u32_e32 v250, s40, v248
	v_add_u32_e32 v248, s48, v248
	s_add_i32 s25, s1, 0xc000
	s_add_i32 s11, s1, 0xe000
	s_barrier
.LBB0_597:
	ds_read_b128 v[164:167], v211
	ds_read_b128 v[168:171], v215
	ds_read_b128 v[172:175], v211 offset:2048
	ds_read_b128 v[176:179], v215 offset:2048
	ds_read_b128 v[180:183], v152
	ds_read_b128 v[184:187], v152 offset:2048
	ds_read_b128 v[188:191], v153
	ds_read_b128 v[192:195], v153 offset:2048
	ds_read_b128 v[196:199], v152 offset:4096
	ds_read_b128 v[200:203], v152 offset:6144
	s_mov_b32 m0, s25
	ds_read_b128 v[206:209], v153 offset:4096
	global_load_lds_dwordx4 v0, vcc nt
	s_mov_b32 m0, s11
	ds_read_b128 v[218:221], v153 offset:6144
	global_load_lds_dwordx4 v158, vcc nt
	s_waitcnt vmcnt(10) lgkmcnt(8)
	s_barrier
	s_waitcnt lgkmcnt(0)
	v_mfma_f32_16x16x32_bf16 v[126:129], v[164:167], v[180:183], v[126:129]
	v_mfma_f32_16x16x32_bf16 v[122:125], v[172:175], v[180:183], v[122:125]
	v_mfma_f32_16x16x32_bf16 v[118:121], v[164:167], v[184:187], v[118:121]
	v_mfma_f32_16x16x32_bf16 v[114:117], v[172:175], v[184:187], v[114:117]
	v_mfma_f32_16x16x32_bf16 v[110:113], v[164:167], v[196:199], v[110:113]
	v_mfma_f32_16x16x32_bf16 v[106:109], v[172:175], v[196:199], v[106:109]
	v_mfma_f32_16x16x32_bf16 v[102:105], v[164:167], v[200:203], v[102:105]
	v_mfma_f32_16x16x32_bf16 v[98:101], v[172:175], v[200:203], v[98:101]
	v_mfma_f32_16x16x32_bf16 v[126:129], v[168:171], v[188:191], v[126:129]
	v_mfma_f32_16x16x32_bf16 v[122:125], v[176:179], v[188:191], v[122:125]
	v_mfma_f32_16x16x32_bf16 v[118:121], v[168:171], v[192:195], v[118:121]
	v_mfma_f32_16x16x32_bf16 v[114:117], v[176:179], v[192:195], v[114:117]
	v_mfma_f32_16x16x32_bf16 v[110:113], v[168:171], v[206:209], v[110:113]
	v_mfma_f32_16x16x32_bf16 v[106:109], v[176:179], v[206:209], v[106:109]
	v_mfma_f32_16x16x32_bf16 v[102:105], v[168:171], v[218:221], v[102:105]
	v_mfma_f32_16x16x32_bf16 v[98:101], v[176:179], v[218:221], v[98:101]
	s_barrier
	ds_read_b128 v[222:225], v211 offset:16384
	ds_read_b128 v[226:229], v215 offset:16384
	s_mov_b32 m0, s2
	ds_read_b128 v[230:233], v211 offset:18432
	global_load_lds_dwordx4 v161, vcc
	s_mov_b32 m0, s3
	ds_read_b128 v[234:237], v215 offset:18432
	global_load_lds_dwordx4 v247, vcc
	s_waitcnt vmcnt(10) lgkmcnt(0)
	s_barrier
	v_mfma_f32_16x16x32_bf16 v[94:97], v[222:225], v[180:183], v[94:97]
	v_mfma_f32_16x16x32_bf16 v[90:93], v[230:233], v[180:183], v[90:93]
	v_mfma_f32_16x16x32_bf16 v[86:89], v[222:225], v[184:187], v[86:89]
	v_mfma_f32_16x16x32_bf16 v[82:85], v[230:233], v[184:187], v[82:85]
	v_mfma_f32_16x16x32_bf16 v[78:81], v[222:225], v[196:199], v[78:81]
	v_mfma_f32_16x16x32_bf16 v[74:77], v[230:233], v[196:199], v[74:77]
	v_mfma_f32_16x16x32_bf16 v[70:73], v[222:225], v[200:203], v[70:73]
	v_mfma_f32_16x16x32_bf16 v[66:69], v[230:233], v[200:203], v[66:69]
	v_mfma_f32_16x16x32_bf16 v[94:97], v[226:229], v[188:191], v[94:97]
	v_mfma_f32_16x16x32_bf16 v[90:93], v[234:237], v[188:191], v[90:93]
	v_mfma_f32_16x16x32_bf16 v[86:89], v[226:229], v[192:195], v[86:89]
	v_mfma_f32_16x16x32_bf16 v[82:85], v[234:237], v[192:195], v[82:85]
	v_mfma_f32_16x16x32_bf16 v[78:81], v[226:229], v[206:209], v[78:81]
	v_mfma_f32_16x16x32_bf16 v[74:77], v[234:237], v[206:209], v[74:77]
	v_mfma_f32_16x16x32_bf16 v[70:73], v[226:229], v[218:221], v[70:73]
	v_mfma_f32_16x16x32_bf16 v[66:69], v[234:237], v[218:221], v[66:69]
	s_barrier
	ds_read_b128 v[180:183], v152 offset:16384
	ds_read_b128 v[184:187], v152 offset:18432
	ds_read_b128 v[188:191], v153 offset:16384
	ds_read_b128 v[192:195], v153 offset:18432
	s_mov_b32 m0, s1
	ds_read_b128 v[196:199], v152 offset:20480
	global_load_lds_dwordx4 v156, vcc nt
	s_mov_b32 m0, s13
	ds_read_b128 v[200:203], v152 offset:22528
	global_load_lds_dwordx4 v159, vcc nt
	s_mov_b32 m0, s15
	ds_read_b128 v[206:209], v153 offset:20480
	global_load_lds_dwordx4 v162, vcc
	s_mov_b32 m0, s16
	ds_read_b128 v[218:221], v153 offset:22528
	global_load_lds_dwordx4 v249, vcc
	s_waitcnt vmcnt(10) lgkmcnt(0)
	s_barrier
	v_mfma_f32_16x16x32_bf16 v[62:65], v[164:167], v[180:183], v[62:65]
	v_mfma_f32_16x16x32_bf16 v[58:61], v[172:175], v[180:183], v[58:61]
	v_mfma_f32_16x16x32_bf16 v[54:57], v[164:167], v[184:187], v[54:57]
	v_mfma_f32_16x16x32_bf16 v[50:53], v[172:175], v[184:187], v[50:53]
	v_mfma_f32_16x16x32_bf16 v[46:49], v[164:167], v[196:199], v[46:49]
	v_mfma_f32_16x16x32_bf16 v[42:45], v[172:175], v[196:199], v[42:45]
	v_mfma_f32_16x16x32_bf16 v[38:41], v[164:167], v[200:203], v[38:41]
	v_mfma_f32_16x16x32_bf16 v[34:37], v[172:175], v[200:203], v[34:37]
	v_mfma_f32_16x16x32_bf16 v[62:65], v[168:171], v[188:191], v[62:65]
	v_mfma_f32_16x16x32_bf16 v[58:61], v[176:179], v[188:191], v[58:61]
	v_mfma_f32_16x16x32_bf16 v[54:57], v[168:171], v[192:195], v[54:57]
	v_mfma_f32_16x16x32_bf16 v[50:53], v[176:179], v[192:195], v[50:53]
	v_mfma_f32_16x16x32_bf16 v[46:49], v[168:171], v[206:209], v[46:49]
	v_mfma_f32_16x16x32_bf16 v[42:45], v[176:179], v[206:209], v[42:45]
	v_mfma_f32_16x16x32_bf16 v[38:41], v[168:171], v[218:221], v[38:41]
	v_mfma_f32_16x16x32_bf16 v[34:37], v[176:179], v[218:221], v[34:37]
	v_mfma_f32_16x16x32_bf16 v[30:33], v[222:225], v[180:183], v[30:33]
	v_mfma_f32_16x16x32_bf16 v[26:29], v[230:233], v[180:183], v[26:29]
	v_mfma_f32_16x16x32_bf16 v[22:25], v[222:225], v[184:187], v[22:25]
	v_mfma_f32_16x16x32_bf16 v[18:21], v[230:233], v[184:187], v[18:21]
	v_mfma_f32_16x16x32_bf16 v[14:17], v[222:225], v[196:199], v[14:17]
	v_mfma_f32_16x16x32_bf16 v[10:13], v[230:233], v[196:199], v[10:13]
	v_mfma_f32_16x16x32_bf16 v[6:9], v[222:225], v[200:203], v[6:9]
	v_mfma_f32_16x16x32_bf16 v[2:5], v[230:233], v[200:203], v[2:5]
	v_mfma_f32_16x16x32_bf16 v[30:33], v[226:229], v[188:191], v[30:33]
	v_mfma_f32_16x16x32_bf16 v[26:29], v[234:237], v[188:191], v[26:29]
	v_mfma_f32_16x16x32_bf16 v[22:25], v[226:229], v[192:195], v[22:25]
	v_mfma_f32_16x16x32_bf16 v[18:21], v[234:237], v[192:195], v[18:21]
	v_mfma_f32_16x16x32_bf16 v[14:17], v[226:229], v[206:209], v[14:17]
	v_mfma_f32_16x16x32_bf16 v[10:13], v[234:237], v[206:209], v[10:13]
	v_mfma_f32_16x16x32_bf16 v[6:9], v[226:229], v[218:221], v[6:9]
	v_mfma_f32_16x16x32_bf16 v[2:5], v[234:237], v[218:221], v[2:5]
	s_barrier
	ds_read_b128 v[172:175], v211 offset:32768
	ds_read_b128 v[176:179], v215 offset:32768
	ds_read_b128 v[180:183], v211 offset:34816
	ds_read_b128 v[184:187], v215 offset:34816
	ds_read_b128 v[188:191], v152 offset:32768
	ds_read_b128 v[192:195], v152 offset:34816
	ds_read_b128 v[196:199], v153 offset:32768
	ds_read_b128 v[200:203], v153 offset:34816
	ds_read_b128 v[206:209], v152 offset:36864
	ds_read_b128 v[218:221], v152 offset:38912
	s_mov_b32 m0, s17
	ds_read_b128 v[222:225], v153 offset:36864
	global_load_lds_dwordx4 v157, vcc nt
	s_mov_b32 m0, s18
	ds_read_b128 v[226:229], v153 offset:38912
	global_load_lds_dwordx4 v160, vcc nt
	s_waitcnt vmcnt(10) lgkmcnt(8)
	s_barrier
	s_waitcnt lgkmcnt(0)
	v_mfma_f32_16x16x32_bf16 v[126:129], v[172:175], v[188:191], v[126:129]
	v_mfma_f32_16x16x32_bf16 v[122:125], v[180:183], v[188:191], v[122:125]
	v_mfma_f32_16x16x32_bf16 v[118:121], v[172:175], v[192:195], v[118:121]
	v_mfma_f32_16x16x32_bf16 v[114:117], v[180:183], v[192:195], v[114:117]
	v_mfma_f32_16x16x32_bf16 v[110:113], v[172:175], v[206:209], v[110:113]
	v_mfma_f32_16x16x32_bf16 v[106:109], v[180:183], v[206:209], v[106:109]
	v_mfma_f32_16x16x32_bf16 v[102:105], v[172:175], v[218:221], v[102:105]
	v_mfma_f32_16x16x32_bf16 v[98:101], v[180:183], v[218:221], v[98:101]
	v_mfma_f32_16x16x32_bf16 v[126:129], v[176:179], v[196:199], v[126:129]
	v_mfma_f32_16x16x32_bf16 v[122:125], v[184:187], v[196:199], v[122:125]
	v_mfma_f32_16x16x32_bf16 v[118:121], v[176:179], v[200:203], v[118:121]
	v_mfma_f32_16x16x32_bf16 v[114:117], v[184:187], v[200:203], v[114:117]
	v_mfma_f32_16x16x32_bf16 v[110:113], v[176:179], v[222:225], v[110:113]
	v_mfma_f32_16x16x32_bf16 v[106:109], v[184:187], v[222:225], v[106:109]
	v_mfma_f32_16x16x32_bf16 v[102:105], v[176:179], v[226:229], v[102:105]
	v_mfma_f32_16x16x32_bf16 v[98:101], v[184:187], v[226:229], v[98:101]
	s_barrier
	ds_read_b128 v[230:233], v211 offset:49152
	ds_read_b128 v[234:237], v215 offset:49152
	s_mov_b32 m0, s19
	ds_read_b128 v[238:241], v211 offset:51200
	global_load_lds_dwordx4 v163, vcc
	s_mov_b32 m0, s20
	ds_read_b128 v[242:245], v215 offset:51200
	global_load_lds_dwordx4 v250, vcc
	s_waitcnt vmcnt(10) lgkmcnt(0)
	s_barrier
	v_mfma_f32_16x16x32_bf16 v[94:97], v[230:233], v[188:191], v[94:97]
	v_mfma_f32_16x16x32_bf16 v[90:93], v[238:241], v[188:191], v[90:93]
	v_mfma_f32_16x16x32_bf16 v[86:89], v[230:233], v[192:195], v[86:89]
	v_mfma_f32_16x16x32_bf16 v[82:85], v[238:241], v[192:195], v[82:85]
	v_mfma_f32_16x16x32_bf16 v[78:81], v[230:233], v[206:209], v[78:81]
	v_mfma_f32_16x16x32_bf16 v[74:77], v[238:241], v[206:209], v[74:77]
	v_mfma_f32_16x16x32_bf16 v[70:73], v[230:233], v[218:221], v[70:73]
	v_mfma_f32_16x16x32_bf16 v[66:69], v[238:241], v[218:221], v[66:69]
	v_mfma_f32_16x16x32_bf16 v[94:97], v[234:237], v[196:199], v[94:97]
	v_mfma_f32_16x16x32_bf16 v[90:93], v[242:245], v[196:199], v[90:93]
	v_mfma_f32_16x16x32_bf16 v[86:89], v[234:237], v[200:203], v[86:89]
	v_mfma_f32_16x16x32_bf16 v[82:85], v[242:245], v[200:203], v[82:85]
	v_mfma_f32_16x16x32_bf16 v[78:81], v[234:237], v[222:225], v[78:81]
	v_mfma_f32_16x16x32_bf16 v[74:77], v[242:245], v[222:225], v[74:77]
	v_mfma_f32_16x16x32_bf16 v[70:73], v[234:237], v[226:229], v[70:73]
	v_mfma_f32_16x16x32_bf16 v[66:69], v[242:245], v[226:229], v[66:69]
	s_barrier
	ds_read_b128 v[188:191], v152 offset:49152
	ds_read_b128 v[192:195], v152 offset:51200
	ds_read_b128 v[196:199], v153 offset:49152
	ds_read_b128 v[200:203], v153 offset:51200
	s_mov_b32 m0, s21
	ds_read_b128 v[206:209], v152 offset:53248
	global_load_lds_dwordx4 v210, vcc nt
	s_mov_b32 m0, s22
	ds_read_b128 v[218:221], v152 offset:55296
	global_load_lds_dwordx4 v214, vcc nt
	s_mov_b32 m0, s23
	ds_read_b128 v[222:225], v153 offset:53248
	global_load_lds_dwordx4 v246, vcc
	s_mov_b32 m0, s24
	ds_read_b128 v[226:229], v153 offset:55296
	global_load_lds_dwordx4 v248, vcc
	s_waitcnt vmcnt(10) lgkmcnt(0)
	s_barrier
	v_mfma_f32_16x16x32_bf16 v[62:65], v[172:175], v[188:191], v[62:65]
	v_mfma_f32_16x16x32_bf16 v[58:61], v[180:183], v[188:191], v[58:61]
	v_mfma_f32_16x16x32_bf16 v[54:57], v[172:175], v[192:195], v[54:57]
	v_mfma_f32_16x16x32_bf16 v[50:53], v[180:183], v[192:195], v[50:53]
	v_mfma_f32_16x16x32_bf16 v[46:49], v[172:175], v[206:209], v[46:49]
	v_mfma_f32_16x16x32_bf16 v[42:45], v[180:183], v[206:209], v[42:45]
	v_mfma_f32_16x16x32_bf16 v[38:41], v[172:175], v[218:221], v[38:41]
	v_mfma_f32_16x16x32_bf16 v[34:37], v[180:183], v[218:221], v[34:37]
	v_mfma_f32_16x16x32_bf16 v[62:65], v[176:179], v[196:199], v[62:65]
	v_mfma_f32_16x16x32_bf16 v[58:61], v[184:187], v[196:199], v[58:61]
	v_mfma_f32_16x16x32_bf16 v[54:57], v[176:179], v[200:203], v[54:57]
	v_mfma_f32_16x16x32_bf16 v[50:53], v[184:187], v[200:203], v[50:53]
	v_mfma_f32_16x16x32_bf16 v[46:49], v[176:179], v[222:225], v[46:49]
	v_mfma_f32_16x16x32_bf16 v[42:45], v[184:187], v[222:225], v[42:45]
	v_mfma_f32_16x16x32_bf16 v[38:41], v[176:179], v[226:229], v[38:41]
	v_mfma_f32_16x16x32_bf16 v[34:37], v[184:187], v[226:229], v[34:37]
	v_mfma_f32_16x16x32_bf16 v[30:33], v[230:233], v[188:191], v[30:33]
	v_mfma_f32_16x16x32_bf16 v[26:29], v[238:241], v[188:191], v[26:29]
	v_mfma_f32_16x16x32_bf16 v[22:25], v[230:233], v[192:195], v[22:25]
	v_mfma_f32_16x16x32_bf16 v[18:21], v[238:241], v[192:195], v[18:21]
	v_mfma_f32_16x16x32_bf16 v[14:17], v[230:233], v[206:209], v[14:17]
	v_mfma_f32_16x16x32_bf16 v[10:13], v[238:241], v[206:209], v[10:13]
	v_mfma_f32_16x16x32_bf16 v[6:9], v[230:233], v[218:221], v[6:9]
	v_mfma_f32_16x16x32_bf16 v[2:5], v[238:241], v[218:221], v[2:5]
	v_mfma_f32_16x16x32_bf16 v[30:33], v[234:237], v[196:199], v[30:33]
	v_mfma_f32_16x16x32_bf16 v[26:29], v[242:245], v[196:199], v[26:29]
	v_mfma_f32_16x16x32_bf16 v[22:25], v[234:237], v[200:203], v[22:25]
	v_mfma_f32_16x16x32_bf16 v[18:21], v[242:245], v[200:203], v[18:21]
	v_mfma_f32_16x16x32_bf16 v[14:17], v[234:237], v[222:225], v[14:17]
	v_mfma_f32_16x16x32_bf16 v[10:13], v[242:245], v[222:225], v[10:13]
	v_mfma_f32_16x16x32_bf16 v[6:9], v[234:237], v[226:229], v[6:9]
	v_mfma_f32_16x16x32_bf16 v[2:5], v[242:245], v[226:229], v[2:5]
	s_add_u32 vcc_lo, vcc_lo, s54
	s_addc_u32 vcc_hi, vcc_hi, s55
	s_add_i32 s10, s10, 2
	s_cmp_lt_u32 s10, 28
	v_lshl_add_u64 v[150:151], v[150:151], 0, s[54:55]
	s_barrier
	s_cbranch_scc1 .LBB0_597
	s_waitcnt vmcnt(6)
	v_or_b32_e32 v0, 0x10000, v154
	v_add_u32_e32 v157, 0x10800, v154
	v_or_b32_e32 v156, 0x10000, v155
	v_add_u32_e32 v158, 0x10800, v155
	v_or_b32_e32 v159, 0x14000, v154
	v_add_u32_e32 v161, 0x14800, v154
	v_or_b32_e32 v160, 0x14000, v155
	v_add_u32_e32 v162, 0x14800, v155
	v_or_b32_e32 v163, 0x18000, v154
	v_add_u32_e32 v165, 0x18800, v154
	v_or_b32_e32 v164, 0x18000, v155
	v_add_u32_e32 v166, 0x18800, v155
	v_or_b32_e32 v167, 0x1c000, v154
	v_add_u32_e32 v169, 0x1c800, v154
	v_or_b32_e32 v168, 0x1c000, v155
	v_add_u32_e32 v170, 0x1c800, v155
	s_mov_b64 s[2:3], 0xf80
	s_mov_b32 m0, s25
	v_lshl_add_u64 v[140:141], v[140:141], 0, s[2:3]
	ds_read_b128 v[142:145], v0
	ds_read_b128 v[146:149], v156
	ds_read_b128 v[154:157], v157
	ds_read_b128 v[172:175], v158
	ds_read_b128 v[176:179], v152
	ds_read_b128 v[180:183], v152 offset:2048
	ds_read_b128 v[184:187], v153
	ds_read_b128 v[188:191], v153 offset:2048
	ds_read_b128 v[192:195], v152 offset:4096
	ds_read_b128 v[196:199], v152 offset:6144
	ds_read_b128 v[200:203], v153 offset:4096
	ds_read_b128 v[206:209], v153 offset:6144
	global_load_lds_dwordx4 v[140:141], off nt
	v_lshl_add_u64 v[138:139], v[138:139], 0, s[2:3]
	s_mov_b32 m0, s11
	s_nop 0
	global_load_lds_dwordx4 v[138:139], off nt
	s_barrier
	s_waitcnt lgkmcnt(0)
	s_setprio 1
	s_waitcnt lgkmcnt(0)
	v_mfma_f32_16x16x32_bf16 v[126:129], v[142:145], v[176:179], v[126:129]
	v_mfma_f32_16x16x32_bf16 v[122:125], v[154:157], v[176:179], v[122:125]
	v_mfma_f32_16x16x32_bf16 v[118:121], v[142:145], v[180:183], v[118:121]
	v_mfma_f32_16x16x32_bf16 v[114:117], v[154:157], v[180:183], v[114:117]
	v_mfma_f32_16x16x32_bf16 v[102:105], v[142:145], v[196:199], v[102:105]
	v_mfma_f32_16x16x32_bf16 v[98:101], v[154:157], v[196:199], v[98:101]
	v_mfma_f32_16x16x32_bf16 v[126:129], v[146:149], v[184:187], v[126:129]
	v_mfma_f32_16x16x32_bf16 v[122:125], v[172:175], v[184:187], v[122:125]
	v_mfma_f32_16x16x32_bf16 v[118:121], v[146:149], v[188:191], v[118:121]
	v_mfma_f32_16x16x32_bf16 v[114:117], v[172:175], v[188:191], v[114:117]
	v_mfma_f32_16x16x32_bf16 v[110:113], v[142:145], v[192:195], v[110:113]
	v_mfma_f32_16x16x32_bf16 v[106:109], v[154:157], v[192:195], v[106:109]
	v_mfma_f32_16x16x32_bf16 v[102:105], v[146:149], v[206:209], v[102:105]
	v_mfma_f32_16x16x32_bf16 v[98:101], v[172:175], v[206:209], v[98:101]
	v_mfma_f32_16x16x32_bf16 v[138:141], v[146:149], v[200:203], v[110:113]
	v_mfma_f32_16x16x32_bf16 v[218:221], v[172:175], v[200:203], v[106:109]
	s_setprio 0
	s_barrier
	s_nop 1
	ds_read_b128 v[106:109], v159
	ds_read_b128 v[110:113], v160
	ds_read_b128 v[158:161], v161
	ds_read_b128 v[222:225], v162
	s_barrier
	s_waitcnt lgkmcnt(0)
	s_setprio 1
	s_waitcnt lgkmcnt(0)
	v_mfma_f32_16x16x32_bf16 v[86:89], v[106:109], v[180:183], v[86:89]
	v_mfma_f32_16x16x32_bf16 v[82:85], v[158:161], v[180:183], v[82:85]
	v_mfma_f32_16x16x32_bf16 v[70:73], v[106:109], v[196:199], v[70:73]
	v_mfma_f32_16x16x32_bf16 v[66:69], v[158:161], v[196:199], v[66:69]
	v_mfma_f32_16x16x32_bf16 v[94:97], v[106:109], v[176:179], v[94:97]
	v_mfma_f32_16x16x32_bf16 v[90:93], v[158:161], v[176:179], v[90:93]
	v_mfma_f32_16x16x32_bf16 v[86:89], v[110:113], v[188:191], v[86:89]
	v_mfma_f32_16x16x32_bf16 v[82:85], v[222:225], v[188:191], v[82:85]
	v_mfma_f32_16x16x32_bf16 v[78:81], v[106:109], v[192:195], v[78:81]
	v_mfma_f32_16x16x32_bf16 v[74:77], v[158:161], v[192:195], v[74:77]
	v_mfma_f32_16x16x32_bf16 v[70:73], v[110:113], v[206:209], v[70:73]
	v_mfma_f32_16x16x32_bf16 v[66:69], v[222:225], v[206:209], v[66:69]
	v_mfma_f32_16x16x32_bf16 v[226:229], v[110:113], v[184:187], v[94:97]
	v_mfma_f32_16x16x32_bf16 v[176:179], v[222:225], v[184:187], v[90:93]
	v_mfma_f32_16x16x32_bf16 v[180:183], v[110:113], v[200:203], v[78:81]
	v_mfma_f32_16x16x32_bf16 v[184:187], v[222:225], v[200:203], v[74:77]
	s_setprio 0
	s_barrier
	s_nop 0
	ds_read_b128 v[74:77], v152 offset:16384
	ds_read_b128 v[78:81], v152 offset:18432
	ds_read_b128 v[90:93], v153 offset:16384
	ds_read_b128 v[94:97], v153 offset:18432
	ds_read_b128 v[188:191], v152 offset:20480
	ds_read_b128 v[192:195], v152 offset:22528
	ds_read_b128 v[196:199], v153 offset:20480
	ds_read_b128 v[200:203], v153 offset:22528
	s_waitcnt vmcnt(4)
	s_barrier
	s_waitcnt lgkmcnt(0)
	s_setprio 1
	s_waitcnt lgkmcnt(0)
	v_mfma_f32_16x16x32_bf16 v[62:65], v[142:145], v[74:77], v[62:65]
	v_mfma_f32_16x16x32_bf16 v[58:61], v[154:157], v[74:77], v[58:61]
	v_mfma_f32_16x16x32_bf16 v[54:57], v[142:145], v[78:81], v[54:57]
	v_mfma_f32_16x16x32_bf16 v[50:53], v[154:157], v[78:81], v[50:53]
	v_mfma_f32_16x16x32_bf16 v[38:41], v[142:145], v[192:195], v[38:41]
	v_mfma_f32_16x16x32_bf16 v[34:37], v[154:157], v[192:195], v[34:37]
	v_mfma_f32_16x16x32_bf16 v[62:65], v[146:149], v[90:93], v[62:65]
	v_mfma_f32_16x16x32_bf16 v[58:61], v[172:175], v[90:93], v[58:61]
	v_mfma_f32_16x16x32_bf16 v[54:57], v[146:149], v[94:97], v[54:57]
	v_mfma_f32_16x16x32_bf16 v[50:53], v[172:175], v[94:97], v[50:53]
	v_mfma_f32_16x16x32_bf16 v[46:49], v[142:145], v[188:191], v[46:49]
	v_mfma_f32_16x16x32_bf16 v[42:45], v[154:157], v[188:191], v[42:45]
	v_mfma_f32_16x16x32_bf16 v[38:41], v[146:149], v[200:203], v[38:41]
	v_mfma_f32_16x16x32_bf16 v[34:37], v[172:175], v[200:203], v[34:37]
	v_mfma_f32_16x16x32_bf16 v[206:209], v[146:149], v[196:199], v[46:49]
	v_mfma_f32_16x16x32_bf16 v[230:233], v[172:175], v[196:199], v[42:45]
	s_setprio 0
	s_setprio 1
	v_mfma_f32_16x16x32_bf16 v[22:25], v[106:109], v[78:81], v[22:25]
	v_mfma_f32_16x16x32_bf16 v[18:21], v[158:161], v[78:81], v[18:21]
	v_mfma_f32_16x16x32_bf16 v[6:9], v[106:109], v[192:195], v[6:9]
	v_mfma_f32_16x16x32_bf16 v[2:5], v[158:161], v[192:195], v[2:5]
	v_mfma_f32_16x16x32_bf16 v[30:33], v[106:109], v[74:77], v[30:33]
	v_mfma_f32_16x16x32_bf16 v[26:29], v[158:161], v[74:77], v[26:29]
	v_mfma_f32_16x16x32_bf16 v[22:25], v[110:113], v[94:97], v[22:25]
	v_mfma_f32_16x16x32_bf16 v[18:21], v[222:225], v[94:97], v[18:21]
	v_mfma_f32_16x16x32_bf16 v[14:17], v[106:109], v[188:191], v[14:17]
	v_mfma_f32_16x16x32_bf16 v[10:13], v[158:161], v[188:191], v[10:13]
	v_mfma_f32_16x16x32_bf16 v[6:9], v[110:113], v[200:203], v[6:9]
	v_mfma_f32_16x16x32_bf16 v[2:5], v[222:225], v[200:203], v[2:5]
	v_mfma_f32_16x16x32_bf16 v[142:145], v[110:113], v[90:93], v[30:33]
	v_mfma_f32_16x16x32_bf16 v[146:149], v[222:225], v[90:93], v[26:29]
	v_mfma_f32_16x16x32_bf16 v[154:157], v[110:113], v[196:199], v[14:17]
	v_mfma_f32_16x16x32_bf16 v[172:175], v[222:225], v[196:199], v[10:13]
	s_setprio 0
	s_barrier
	s_nop 0
	ds_read_b128 v[10:13], v163
	ds_read_b128 v[14:17], v164
	ds_read_b128 v[158:161], v165
	ds_read_b128 v[162:165], v166
	ds_read_b128 v[26:29], v152 offset:32768
	ds_read_b128 v[30:33], v152 offset:34816
	ds_read_b128 v[42:45], v153 offset:32768
	ds_read_b128 v[46:49], v153 offset:34816
	ds_read_b128 v[188:191], v152 offset:36864
	ds_read_b128 v[192:195], v152 offset:38912
	ds_read_b128 v[196:199], v153 offset:36864
	ds_read_b128 v[200:203], v153 offset:38912
	s_waitcnt vmcnt(2)
	s_barrier
	s_waitcnt lgkmcnt(0)
	s_setprio 1
	s_waitcnt lgkmcnt(0)
	v_mfma_f32_16x16x32_bf16 v[74:77], v[10:13], v[26:29], v[126:129]
	v_mfma_f32_16x16x32_bf16 v[126:129], v[14:17], v[42:45], v[74:77]
	v_mfma_f32_16x16x32_bf16 v[74:77], v[158:161], v[26:29], v[122:125]
	v_mfma_f32_16x16x32_bf16 v[122:125], v[162:165], v[42:45], v[74:77]
	v_mfma_f32_16x16x32_bf16 v[74:77], v[10:13], v[30:33], v[118:121]
	v_mfma_f32_16x16x32_bf16 v[110:113], v[14:17], v[46:49], v[74:77]
	v_mfma_f32_16x16x32_bf16 v[74:77], v[158:161], v[30:33], v[114:117]
	v_mfma_f32_16x16x32_bf16 v[106:109], v[162:165], v[46:49], v[74:77]
	v_mfma_f32_16x16x32_bf16 v[74:77], v[10:13], v[188:191], v[138:141]
	v_mfma_f32_16x16x32_bf16 v[94:97], v[14:17], v[196:199], v[74:77]
	v_mfma_f32_16x16x32_bf16 v[74:77], v[158:161], v[188:191], v[218:221]
	v_mfma_f32_16x16x32_bf16 v[90:93], v[162:165], v[196:199], v[74:77]
	v_mfma_f32_16x16x32_bf16 v[74:77], v[10:13], v[192:195], v[102:105]
	v_mfma_f32_16x16x32_bf16 v[78:81], v[14:17], v[200:203], v[74:77]
	v_mfma_f32_16x16x32_bf16 v[74:77], v[158:161], v[192:195], v[98:101]
	v_mfma_f32_16x16x32_bf16 v[74:77], v[162:165], v[200:203], v[74:77]
	s_setprio 0
	s_barrier
	ds_read_b128 v[138:141], v167
	ds_read_b128 v[218:221], v168
	ds_read_b128 v[166:169], v169
	ds_read_b128 v[222:225], v170
	s_waitcnt vmcnt(0)
	s_barrier
	s_waitcnt lgkmcnt(0)
	s_setprio 1
	s_waitcnt lgkmcnt(0)
	v_mfma_f32_16x16x32_bf16 v[98:101], v[138:141], v[26:29], v[226:229]
	v_mfma_f32_16x16x32_bf16 v[26:29], v[166:169], v[26:29], v[176:179]
	v_mfma_f32_16x16x32_bf16 v[114:117], v[222:225], v[42:45], v[26:29]
	v_mfma_f32_16x16x32_bf16 v[26:29], v[138:141], v[30:33], v[86:89]
	v_mfma_f32_16x16x32_bf16 v[102:105], v[218:221], v[46:49], v[26:29]
	v_mfma_f32_16x16x32_bf16 v[26:29], v[166:169], v[30:33], v[82:85]
	v_mfma_f32_16x16x32_bf16 v[118:121], v[218:221], v[42:45], v[98:101]
	v_mfma_f32_16x16x32_bf16 v[98:101], v[222:225], v[46:49], v[26:29]
	v_mfma_f32_16x16x32_bf16 v[26:29], v[138:141], v[188:191], v[180:183]
	v_mfma_f32_16x16x32_bf16 v[86:89], v[218:221], v[196:199], v[26:29]
	v_mfma_f32_16x16x32_bf16 v[26:29], v[166:169], v[188:191], v[184:187]
	v_mfma_f32_16x16x32_bf16 v[82:85], v[222:225], v[196:199], v[26:29]
	v_mfma_f32_16x16x32_bf16 v[26:29], v[138:141], v[192:195], v[70:73]
	v_mfma_f32_16x16x32_bf16 v[70:73], v[218:221], v[200:203], v[26:29]
	v_mfma_f32_16x16x32_bf16 v[26:29], v[166:169], v[192:195], v[66:69]
	v_mfma_f32_16x16x32_bf16 v[66:69], v[222:225], v[200:203], v[26:29]
	s_setprio 0
	s_barrier
	ds_read_b128 v[176:179], v152 offset:49152
	ds_read_b128 v[180:183], v152 offset:51200
	ds_read_b128 v[184:187], v153 offset:49152
	ds_read_b128 v[188:191], v153 offset:51200
	ds_read_b128 v[192:195], v152 offset:53248
	ds_read_b128 v[196:199], v152 offset:55296
	ds_read_b128 v[200:203], v153 offset:53248
	ds_read_b128 v[150:153], v153 offset:55296
	s_barrier
	s_waitcnt lgkmcnt(0)
	s_setprio 1
	s_waitcnt lgkmcnt(0)
	v_mfma_f32_16x16x32_bf16 v[26:29], v[10:13], v[176:179], v[62:65]
	v_mfma_f32_16x16x32_bf16 v[62:65], v[14:17], v[184:187], v[26:29]
	v_mfma_f32_16x16x32_bf16 v[26:29], v[158:161], v[176:179], v[58:61]
	v_mfma_f32_16x16x32_bf16 v[58:61], v[162:165], v[184:187], v[26:29]
	v_mfma_f32_16x16x32_bf16 v[26:29], v[10:13], v[180:183], v[54:57]
	v_mfma_f32_16x16x32_bf16 v[46:49], v[14:17], v[188:191], v[26:29]
	v_mfma_f32_16x16x32_bf16 v[26:29], v[158:161], v[180:183], v[50:53]
	v_mfma_f32_16x16x32_bf16 v[42:45], v[162:165], v[188:191], v[26:29]
	v_mfma_f32_16x16x32_bf16 v[26:29], v[10:13], v[192:195], v[206:209]
	v_mfma_f32_16x16x32_bf16 v[10:13], v[10:13], v[196:199], v[38:41]
	v_mfma_f32_16x16x32_bf16 v[30:33], v[14:17], v[200:203], v[26:29]
	v_mfma_f32_16x16x32_bf16 v[26:29], v[158:161], v[192:195], v[230:233]
	v_mfma_f32_16x16x32_bf16 v[14:17], v[14:17], v[150:153], v[10:13]
	v_mfma_f32_16x16x32_bf16 v[10:13], v[158:161], v[196:199], v[34:37]
	v_mfma_f32_16x16x32_bf16 v[26:29], v[162:165], v[200:203], v[26:29]
	v_mfma_f32_16x16x32_bf16 v[10:13], v[162:165], v[150:153], v[10:13]
	s_setprio 0
	s_setprio 1
	v_mfma_f32_16x16x32_bf16 v[34:37], v[138:141], v[176:179], v[142:145]
	v_mfma_f32_16x16x32_bf16 v[54:57], v[218:221], v[184:187], v[34:37]
	v_mfma_f32_16x16x32_bf16 v[34:37], v[166:169], v[176:179], v[146:149]
	v_mfma_f32_16x16x32_bf16 v[18:21], v[166:169], v[180:183], v[18:21]
	v_mfma_f32_16x16x32_bf16 v[50:53], v[222:225], v[184:187], v[34:37]
	v_mfma_f32_16x16x32_bf16 v[22:25], v[138:141], v[180:183], v[22:25]
	v_mfma_f32_16x16x32_bf16 v[34:37], v[222:225], v[188:191], v[18:21]
	v_mfma_f32_16x16x32_bf16 v[18:21], v[138:141], v[192:195], v[154:157]
	v_mfma_f32_16x16x32_bf16 v[38:41], v[218:221], v[188:191], v[22:25]
	v_mfma_f32_16x16x32_bf16 v[22:25], v[218:221], v[200:203], v[18:21]
	v_mfma_f32_16x16x32_bf16 v[18:21], v[166:169], v[192:195], v[172:175]
	v_mfma_f32_16x16x32_bf16 v[6:9], v[138:141], v[196:199], v[6:9]
	v_mfma_f32_16x16x32_bf16 v[2:5], v[166:169], v[196:199], v[2:5]
	v_mfma_f32_16x16x32_bf16 v[18:21], v[222:225], v[200:203], v[18:21]
	v_mfma_f32_16x16x32_bf16 v[6:9], v[218:221], v[150:153], v[6:9]
	v_mfma_f32_16x16x32_bf16 v[2:5], v[222:225], v[150:153], v[2:5]
	s_setprio 0
	s_cmpk_gt_u32 s0, 0xff
	s_barrier
	s_cbranch_scc1 .LBB0_600
	s_barrier

.LBB0_641:
	s_lshl_b32 s22, s22, 5
	v_and_b32_e32 v0, 15, v16
	s_and_b32 s22, s22, 0x60
	v_lshlrev_b32_e32 v21, 7, v0
	v_or_b32_e32 v0, s22, v0
	s_add_i32 s22, s1, 0x18000
	s_mov_b64 s[30:31], 0x80
	v_lshl_or_b32 v21, s23, 13, v21
	v_lshl_add_u64 v[10:11], v[10:11], 0, s[30:31]
	s_mov_b32 m0, s22
	s_add_i32 s23, s1, 0x1a000
	s_waitcnt vmcnt(4)
	s_barrier
	global_load_lds_dwordx4 v[10:11], off
	v_lshl_add_u64 v[8:9], v[8:9], 0, s[30:31]
	s_mov_b32 m0, s23
	s_add_i32 s24, s1, 0x8000
	global_load_lds_dwordx4 v[8:9], off
	v_lshl_add_u64 v[8:9], v[14:15], 0, s[30:31]
	s_mov_b32 m0, s24
	s_add_i32 s25, s1, 0xa000
	global_load_lds_dwordx4 v[8:9], off
	v_lshl_add_u64 v[8:9], v[12:13], 0, s[30:31]
	s_mov_b32 m0, s25
	s_add_i32 s26, s1, 0x1c000
	global_load_lds_dwordx4 v[8:9], off
	v_lshl_add_u64 v[6:7], v[6:7], 0, s[30:31]
	s_mov_b32 m0, s26
	s_add_i32 s27, s1, 0x1e000
	global_load_lds_dwordx4 v[6:7], off
	v_lshl_add_u64 v[4:5], v[4:5], 0, s[30:31]
	s_mov_b32 m0, s27
	v_and_b32_e32 v22, 3, v20
	global_load_lds_dwordx4 v[4:5], off
	v_bfe_u32 v16, v16, 1, 3
	v_bitop3_b32 v20, v20, v16, 3 bitop3:0x6c
	v_bitop3_b32 v16, v22, v16, 4 bitop3:0x36
	v_lshlrev_b32_e32 v20, 4, v20
	v_lshlrev_b32_e32 v16, 4, v16
	v_lshlrev_b32_e32 v0, 7, v0
	v_or_b32_e32 v152, v0, v20
	v_or_b32_e32 v153, v0, v16
	v_add_u32_e32 v0, v19, v18
	v_lshlrev_b64 v[4:5], 1, v[0:1]
	v_lshl_add_u64 v[6:7], s[12:13], 0, v[4:5]
	v_add_u32_e32 v0, v17, v18
	v_lshl_add_u64 v[142:143], v[2:3], 0, v[6:7]
	v_lshlrev_b64 v[6:7], 1, v[0:1]
	v_lshl_add_u64 v[8:9], s[12:13], 0, v[6:7]
	v_lshl_add_u64 v[144:145], v[2:3], 0, v[8:9]
	v_lshl_add_u64 v[2:3], s[10:11], 0, v[4:5]
	s_waitcnt vmcnt(6)
	v_lshl_add_u64 v[146:147], v[136:137], 0, v[2:3]
	v_lshl_add_u64 v[2:3], s[10:11], 0, v[6:7]
	v_lshl_add_u64 v[148:149], v[136:137], 0, v[2:3]
	v_mov_b32_e32 v2, 0
	v_or_b32_e32 v150, v20, v21
	v_or_b32_e32 v151, v16, v21
	s_mov_b32 s12, -2
	s_mov_b64 s[10:11], 0
	v_mov_b32_e32 v3, v2
	v_mov_b32_e32 v4, v2
	v_mov_b32_e32 v5, v2
	v_mov_b32_e32 v6, v2
	v_mov_b32_e32 v7, v2
	v_mov_b32_e32 v8, v2
	v_mov_b32_e32 v9, v2
	v_mov_b32_e32 v10, v2
	v_mov_b32_e32 v11, v2
	v_mov_b32_e32 v12, v2
	v_mov_b32_e32 v13, v2
	v_mov_b32_e32 v14, v2
	v_mov_b32_e32 v15, v2
	v_mov_b32_e32 v16, v2
	v_mov_b32_e32 v17, v2
	v_mov_b32_e32 v18, v2
	v_mov_b32_e32 v19, v2
	v_mov_b32_e32 v20, v2
	v_mov_b32_e32 v21, v2
	v_mov_b32_e32 v22, v2
	v_mov_b32_e32 v23, v2
	v_mov_b32_e32 v24, v2
	v_mov_b32_e32 v25, v2
	v_mov_b32_e32 v26, v2
	v_mov_b32_e32 v27, v2
	v_mov_b32_e32 v28, v2
	v_mov_b32_e32 v29, v2
	v_mov_b32_e32 v30, v2
	v_mov_b32_e32 v31, v2
	v_mov_b32_e32 v32, v2
	v_mov_b32_e32 v33, v2
	v_mov_b32_e32 v34, v2
	v_mov_b32_e32 v35, v2
	v_mov_b32_e32 v36, v2
	v_mov_b32_e32 v37, v2
	v_mov_b32_e32 v38, v2
	v_mov_b32_e32 v39, v2
	v_mov_b32_e32 v40, v2
	v_mov_b32_e32 v41, v2
	v_mov_b32_e32 v42, v2
	v_mov_b32_e32 v43, v2
	v_mov_b32_e32 v44, v2
	v_mov_b32_e32 v45, v2
	v_mov_b32_e32 v46, v2
	v_mov_b32_e32 v47, v2
	v_mov_b32_e32 v48, v2
	v_mov_b32_e32 v49, v2
	v_mov_b32_e32 v50, v2
	v_mov_b32_e32 v51, v2
	v_mov_b32_e32 v52, v2
	v_mov_b32_e32 v53, v2
	v_mov_b32_e32 v54, v2
	v_mov_b32_e32 v55, v2
	v_mov_b32_e32 v56, v2
	v_mov_b32_e32 v57, v2
	v_mov_b32_e32 v58, v2
	v_mov_b32_e32 v59, v2
	v_mov_b32_e32 v60, v2
	v_mov_b32_e32 v61, v2
	v_mov_b32_e32 v62, v2
	v_mov_b32_e32 v63, v2
	v_mov_b32_e32 v64, v2
	v_mov_b32_e32 v65, v2
	v_mov_b32_e32 v66, v2
	v_mov_b32_e32 v67, v2
	v_mov_b32_e32 v68, v2
	v_mov_b32_e32 v69, v2
	v_mov_b32_e32 v70, v2
	v_mov_b32_e32 v71, v2
	v_mov_b32_e32 v72, v2
	v_mov_b32_e32 v73, v2
	v_mov_b32_e32 v74, v2
	v_mov_b32_e32 v75, v2
	v_mov_b32_e32 v76, v2
	v_mov_b32_e32 v77, v2
	v_mov_b32_e32 v78, v2
	v_mov_b32_e32 v79, v2
	v_mov_b32_e32 v80, v2
	v_mov_b32_e32 v81, v2
	v_mov_b32_e32 v82, v2
	v_mov_b32_e32 v83, v2
	v_mov_b32_e32 v84, v2
	v_mov_b32_e32 v85, v2
	v_mov_b32_e32 v86, v2
	v_mov_b32_e32 v87, v2
	v_mov_b32_e32 v88, v2
	v_mov_b32_e32 v89, v2
	v_mov_b32_e32 v90, v2
	v_mov_b32_e32 v91, v2
	v_mov_b32_e32 v92, v2
	v_mov_b32_e32 v93, v2
	v_mov_b32_e32 v94, v2
	v_mov_b32_e32 v95, v2
	v_mov_b32_e32 v96, v2
	v_mov_b32_e32 v97, v2
	v_mov_b32_e32 v98, v2
	v_mov_b32_e32 v99, v2
	v_mov_b32_e32 v100, v2
	v_mov_b32_e32 v101, v2
	v_mov_b32_e32 v102, v2
	v_mov_b32_e32 v103, v2
	v_mov_b32_e32 v104, v2
	v_mov_b32_e32 v105, v2
	v_mov_b32_e32 v106, v2
	v_mov_b32_e32 v107, v2
	v_mov_b32_e32 v108, v2
	v_mov_b32_e32 v109, v2
	v_mov_b32_e32 v110, v2
	v_mov_b32_e32 v111, v2
	v_mov_b32_e32 v112, v2
	v_mov_b32_e32 v113, v2
	v_mov_b32_e32 v114, v2
	v_mov_b32_e32 v115, v2
	v_mov_b32_e32 v116, v2
	v_mov_b32_e32 v117, v2
	v_mov_b32_e32 v118, v2
	v_mov_b32_e32 v119, v2
	v_mov_b32_e32 v120, v2
	v_mov_b32_e32 v121, v2
	v_mov_b32_e32 v122, v2
	v_mov_b32_e32 v123, v2
	v_mov_b32_e32 v124, v2
	v_mov_b32_e32 v125, v2
	v_mov_b32_e32 v126, v2
	v_mov_b32_e32 v127, v2
	v_mov_b32_e32 v128, v2
	v_mov_b32_e32 v129, v2
	s_mov_b64 s[30:31], 0xa254900
	s_mov_b64 s[34:35], 0xa2d4900
	s_mov_b64 s[36:37], 0xa254980
	s_mov_b64 s[38:39], 0xa2d4980
	v_readfirstlane_b32 s100, v136
	v_readfirstlane_b32 s101, v137
	s_mov_b64 vcc, s[100:101]
	s_add_u32 s10, s10, vcc_lo
	s_addc_u32 s11, s11, vcc_hi
	v_subrev_u32_e32 v202, vcc_lo, v144
	v_subrev_u32_e32 v210, vcc_lo, v142
	v_subrev_u32_e32 v214, vcc_lo, v148
	v_subrev_u32_e32 v246, vcc_lo, v146
	v_add_u32_e32 v248, 0x10000, v152
	v_add_u32_e32 v249, 0x10000, v153
	v_add_u32_e32 v0, s50, v202
	v_add_u32_e32 v154, s54, v202
	v_add_u32_e32 v155, s58, v202
	v_add_u32_e32 v202, s62, v202
	v_add_u32_e32 v156, s50, v210
	v_add_u32_e32 v157, s54, v210
	v_add_u32_e32 v158, s58, v210
	v_add_u32_e32 v210, s62, v210
	v_add_u32_e32 v159, s30, v214
	v_add_u32_e32 v160, s34, v214
	v_add_u32_e32 v161, s36, v214
	v_add_u32_e32 v214, s38, v214
	v_add_u32_e32 v203, s30, v246
	v_add_u32_e32 v211, s34, v246
	v_add_u32_e32 v215, s36, v246
	v_add_u32_e32 v246, s38, v246
	s_add_i32 s28, s1, 0xc000
	s_add_i32 s13, s1, 0xe000
	s_barrier
.LBB0_642:
	ds_read_b128 v[162:165], v248
	ds_read_b128 v[166:169], v249
	ds_read_b128 v[170:173], v248 offset:2048
	ds_read_b128 v[174:177], v249 offset:2048
	ds_read_b128 v[178:181], v150
	ds_read_b128 v[182:185], v150 offset:2048
	ds_read_b128 v[186:189], v151
	ds_read_b128 v[190:193], v151 offset:2048
	ds_read_b128 v[194:197], v150 offset:4096
	ds_read_b128 v[198:201], v150 offset:6144
	s_mov_b32 m0, s28
	ds_read_b128 v[206:209], v151 offset:4096
	global_load_lds_dwordx4 v0, s[10:11]
	s_mov_b32 m0, s13
	ds_read_b128 v[218:221], v151 offset:6144
	global_load_lds_dwordx4 v156, s[10:11]
	s_waitcnt vmcnt(10) lgkmcnt(8)
	s_barrier
	s_waitcnt lgkmcnt(0)
	v_mfma_f32_16x16x32_bf16 v[126:129], v[162:165], v[178:181], v[126:129]
	v_mfma_f32_16x16x32_bf16 v[122:125], v[170:173], v[178:181], v[122:125]
	v_mfma_f32_16x16x32_bf16 v[118:121], v[162:165], v[182:185], v[118:121]
	v_mfma_f32_16x16x32_bf16 v[114:117], v[170:173], v[182:185], v[114:117]
	v_mfma_f32_16x16x32_bf16 v[110:113], v[162:165], v[194:197], v[110:113]
	v_mfma_f32_16x16x32_bf16 v[106:109], v[170:173], v[194:197], v[106:109]
	v_mfma_f32_16x16x32_bf16 v[102:105], v[162:165], v[198:201], v[102:105]
	v_mfma_f32_16x16x32_bf16 v[98:101], v[170:173], v[198:201], v[98:101]
	v_mfma_f32_16x16x32_bf16 v[126:129], v[166:169], v[186:189], v[126:129]
	v_mfma_f32_16x16x32_bf16 v[122:125], v[174:177], v[186:189], v[122:125]
	v_mfma_f32_16x16x32_bf16 v[118:121], v[166:169], v[190:193], v[118:121]
	v_mfma_f32_16x16x32_bf16 v[114:117], v[174:177], v[190:193], v[114:117]
	v_mfma_f32_16x16x32_bf16 v[110:113], v[166:169], v[206:209], v[110:113]
	v_mfma_f32_16x16x32_bf16 v[106:109], v[174:177], v[206:209], v[106:109]
	v_mfma_f32_16x16x32_bf16 v[102:105], v[166:169], v[218:221], v[102:105]
	v_mfma_f32_16x16x32_bf16 v[98:101], v[174:177], v[218:221], v[98:101]
	s_barrier
	ds_read_b128 v[222:225], v248 offset:16384
	ds_read_b128 v[226:229], v249 offset:16384
	s_mov_b32 m0, s2
	ds_read_b128 v[230:233], v248 offset:18432
	global_load_lds_dwordx4 v159, s[10:11]
	s_mov_b32 m0, s3
	ds_read_b128 v[234:237], v249 offset:18432
	global_load_lds_dwordx4 v203, s[10:11]
	s_waitcnt vmcnt(10) lgkmcnt(0)
	s_barrier
	v_mfma_f32_16x16x32_bf16 v[94:97], v[222:225], v[178:181], v[94:97]
	v_mfma_f32_16x16x32_bf16 v[90:93], v[230:233], v[178:181], v[90:93]
	v_mfma_f32_16x16x32_bf16 v[86:89], v[222:225], v[182:185], v[86:89]
	v_mfma_f32_16x16x32_bf16 v[82:85], v[230:233], v[182:185], v[82:85]
	v_mfma_f32_16x16x32_bf16 v[78:81], v[222:225], v[194:197], v[78:81]
	v_mfma_f32_16x16x32_bf16 v[74:77], v[230:233], v[194:197], v[74:77]
	v_mfma_f32_16x16x32_bf16 v[70:73], v[222:225], v[198:201], v[70:73]
	v_mfma_f32_16x16x32_bf16 v[66:69], v[230:233], v[198:201], v[66:69]
	v_mfma_f32_16x16x32_bf16 v[94:97], v[226:229], v[186:189], v[94:97]
	v_mfma_f32_16x16x32_bf16 v[90:93], v[234:237], v[186:189], v[90:93]
	v_mfma_f32_16x16x32_bf16 v[86:89], v[226:229], v[190:193], v[86:89]
	v_mfma_f32_16x16x32_bf16 v[82:85], v[234:237], v[190:193], v[82:85]
	v_mfma_f32_16x16x32_bf16 v[78:81], v[226:229], v[206:209], v[78:81]
	v_mfma_f32_16x16x32_bf16 v[74:77], v[234:237], v[206:209], v[74:77]
	v_mfma_f32_16x16x32_bf16 v[70:73], v[226:229], v[218:221], v[70:73]
	v_mfma_f32_16x16x32_bf16 v[66:69], v[234:237], v[218:221], v[66:69]
	s_barrier
	ds_read_b128 v[178:181], v150 offset:16384
	ds_read_b128 v[182:185], v150 offset:18432
	ds_read_b128 v[186:189], v151 offset:16384
	ds_read_b128 v[190:193], v151 offset:18432
	s_mov_b32 m0, s1
	ds_read_b128 v[194:197], v150 offset:20480
	global_load_lds_dwordx4 v154, s[10:11]
	s_mov_b32 m0, s17
	ds_read_b128 v[198:201], v150 offset:22528
	global_load_lds_dwordx4 v157, s[10:11]
	s_mov_b32 m0, s18
	ds_read_b128 v[206:209], v151 offset:20480
	global_load_lds_dwordx4 v160, s[10:11]
	s_mov_b32 m0, s19
	ds_read_b128 v[218:221], v151 offset:22528
	global_load_lds_dwordx4 v211, s[10:11]
	s_waitcnt vmcnt(10) lgkmcnt(0)
	s_barrier
	v_mfma_f32_16x16x32_bf16 v[62:65], v[162:165], v[178:181], v[62:65]
	v_mfma_f32_16x16x32_bf16 v[58:61], v[170:173], v[178:181], v[58:61]
	v_mfma_f32_16x16x32_bf16 v[54:57], v[162:165], v[182:185], v[54:57]
	v_mfma_f32_16x16x32_bf16 v[50:53], v[170:173], v[182:185], v[50:53]
	v_mfma_f32_16x16x32_bf16 v[46:49], v[162:165], v[194:197], v[46:49]
	v_mfma_f32_16x16x32_bf16 v[42:45], v[170:173], v[194:197], v[42:45]
	v_mfma_f32_16x16x32_bf16 v[38:41], v[162:165], v[198:201], v[38:41]
	v_mfma_f32_16x16x32_bf16 v[34:37], v[170:173], v[198:201], v[34:37]
	v_mfma_f32_16x16x32_bf16 v[62:65], v[166:169], v[186:189], v[62:65]
	v_mfma_f32_16x16x32_bf16 v[58:61], v[174:177], v[186:189], v[58:61]
	v_mfma_f32_16x16x32_bf16 v[54:57], v[166:169], v[190:193], v[54:57]
	v_mfma_f32_16x16x32_bf16 v[50:53], v[174:177], v[190:193], v[50:53]
	v_mfma_f32_16x16x32_bf16 v[46:49], v[166:169], v[206:209], v[46:49]
	v_mfma_f32_16x16x32_bf16 v[42:45], v[174:177], v[206:209], v[42:45]
	v_mfma_f32_16x16x32_bf16 v[38:41], v[166:169], v[218:221], v[38:41]
	v_mfma_f32_16x16x32_bf16 v[34:37], v[174:177], v[218:221], v[34:37]
	v_mfma_f32_16x16x32_bf16 v[30:33], v[222:225], v[178:181], v[30:33]
	v_mfma_f32_16x16x32_bf16 v[26:29], v[230:233], v[178:181], v[26:29]
	v_mfma_f32_16x16x32_bf16 v[22:25], v[222:225], v[182:185], v[22:25]
	v_mfma_f32_16x16x32_bf16 v[18:21], v[230:233], v[182:185], v[18:21]
	v_mfma_f32_16x16x32_bf16 v[14:17], v[222:225], v[194:197], v[14:17]
	v_mfma_f32_16x16x32_bf16 v[10:13], v[230:233], v[194:197], v[10:13]
	v_mfma_f32_16x16x32_bf16 v[6:9], v[222:225], v[198:201], v[6:9]
	v_mfma_f32_16x16x32_bf16 v[2:5], v[230:233], v[198:201], v[2:5]
	v_mfma_f32_16x16x32_bf16 v[30:33], v[226:229], v[186:189], v[30:33]
	v_mfma_f32_16x16x32_bf16 v[26:29], v[234:237], v[186:189], v[26:29]
	v_mfma_f32_16x16x32_bf16 v[22:25], v[226:229], v[190:193], v[22:25]
	v_mfma_f32_16x16x32_bf16 v[18:21], v[234:237], v[190:193], v[18:21]
	v_mfma_f32_16x16x32_bf16 v[14:17], v[226:229], v[206:209], v[14:17]
	v_mfma_f32_16x16x32_bf16 v[10:13], v[234:237], v[206:209], v[10:13]
	v_mfma_f32_16x16x32_bf16 v[6:9], v[226:229], v[218:221], v[6:9]
	v_mfma_f32_16x16x32_bf16 v[2:5], v[234:237], v[218:221], v[2:5]
	s_barrier
	ds_read_b128 v[170:173], v248 offset:32768
	ds_read_b128 v[174:177], v249 offset:32768
	ds_read_b128 v[178:181], v248 offset:34816
	ds_read_b128 v[182:185], v249 offset:34816
	ds_read_b128 v[186:189], v150 offset:32768
	ds_read_b128 v[190:193], v150 offset:34816
	ds_read_b128 v[194:197], v151 offset:32768
	ds_read_b128 v[198:201], v151 offset:34816
	ds_read_b128 v[206:209], v150 offset:36864
	ds_read_b128 v[218:221], v150 offset:38912
	s_mov_b32 m0, s20
	ds_read_b128 v[222:225], v151 offset:36864
	global_load_lds_dwordx4 v155, s[10:11]
	s_mov_b32 m0, s21
	ds_read_b128 v[226:229], v151 offset:38912
	global_load_lds_dwordx4 v158, s[10:11]
	s_waitcnt vmcnt(10) lgkmcnt(8)
	s_barrier
	s_waitcnt lgkmcnt(0)
	v_mfma_f32_16x16x32_bf16 v[126:129], v[170:173], v[186:189], v[126:129]
	v_mfma_f32_16x16x32_bf16 v[122:125], v[178:181], v[186:189], v[122:125]
	v_mfma_f32_16x16x32_bf16 v[118:121], v[170:173], v[190:193], v[118:121]
	v_mfma_f32_16x16x32_bf16 v[114:117], v[178:181], v[190:193], v[114:117]
	v_mfma_f32_16x16x32_bf16 v[110:113], v[170:173], v[206:209], v[110:113]
	v_mfma_f32_16x16x32_bf16 v[106:109], v[178:181], v[206:209], v[106:109]
	v_mfma_f32_16x16x32_bf16 v[102:105], v[170:173], v[218:221], v[102:105]
	v_mfma_f32_16x16x32_bf16 v[98:101], v[178:181], v[218:221], v[98:101]
	v_mfma_f32_16x16x32_bf16 v[126:129], v[174:177], v[194:197], v[126:129]
	v_mfma_f32_16x16x32_bf16 v[122:125], v[182:185], v[194:197], v[122:125]
	v_mfma_f32_16x16x32_bf16 v[118:121], v[174:177], v[198:201], v[118:121]
	v_mfma_f32_16x16x32_bf16 v[114:117], v[182:185], v[198:201], v[114:117]
	v_mfma_f32_16x16x32_bf16 v[110:113], v[174:177], v[222:225], v[110:113]
	v_mfma_f32_16x16x32_bf16 v[106:109], v[182:185], v[222:225], v[106:109]
	v_mfma_f32_16x16x32_bf16 v[102:105], v[174:177], v[226:229], v[102:105]
	v_mfma_f32_16x16x32_bf16 v[98:101], v[182:185], v[226:229], v[98:101]
	s_barrier
	ds_read_b128 v[230:233], v248 offset:49152
	ds_read_b128 v[234:237], v249 offset:49152
	s_mov_b32 m0, s22
	ds_read_b128 v[238:241], v248 offset:51200
	global_load_lds_dwordx4 v161, s[10:11]
	s_mov_b32 m0, s23
	ds_read_b128 v[242:245], v249 offset:51200
	global_load_lds_dwordx4 v215, s[10:11]
	s_waitcnt vmcnt(10) lgkmcnt(0)
	s_barrier
	v_mfma_f32_16x16x32_bf16 v[94:97], v[230:233], v[186:189], v[94:97]
	v_mfma_f32_16x16x32_bf16 v[90:93], v[238:241], v[186:189], v[90:93]
	v_mfma_f32_16x16x32_bf16 v[86:89], v[230:233], v[190:193], v[86:89]
	v_mfma_f32_16x16x32_bf16 v[82:85], v[238:241], v[190:193], v[82:85]
	v_mfma_f32_16x16x32_bf16 v[78:81], v[230:233], v[206:209], v[78:81]
	v_mfma_f32_16x16x32_bf16 v[74:77], v[238:241], v[206:209], v[74:77]
	v_mfma_f32_16x16x32_bf16 v[70:73], v[230:233], v[218:221], v[70:73]
	v_mfma_f32_16x16x32_bf16 v[66:69], v[238:241], v[218:221], v[66:69]
	v_mfma_f32_16x16x32_bf16 v[94:97], v[234:237], v[194:197], v[94:97]
	v_mfma_f32_16x16x32_bf16 v[90:93], v[242:245], v[194:197], v[90:93]
	v_mfma_f32_16x16x32_bf16 v[86:89], v[234:237], v[198:201], v[86:89]
	v_mfma_f32_16x16x32_bf16 v[82:85], v[242:245], v[198:201], v[82:85]
	v_mfma_f32_16x16x32_bf16 v[78:81], v[234:237], v[222:225], v[78:81]
	v_mfma_f32_16x16x32_bf16 v[74:77], v[242:245], v[222:225], v[74:77]
	v_mfma_f32_16x16x32_bf16 v[70:73], v[234:237], v[226:229], v[70:73]
	v_mfma_f32_16x16x32_bf16 v[66:69], v[242:245], v[226:229], v[66:69]
	s_barrier
	ds_read_b128 v[186:189], v150 offset:49152
	ds_read_b128 v[190:193], v150 offset:51200
	ds_read_b128 v[194:197], v151 offset:49152
	ds_read_b128 v[198:201], v151 offset:51200
	s_mov_b32 m0, s24
	ds_read_b128 v[206:209], v150 offset:53248
	global_load_lds_dwordx4 v202, s[10:11]
	s_mov_b32 m0, s25
	ds_read_b128 v[218:221], v150 offset:55296
	global_load_lds_dwordx4 v210, s[10:11]
	s_mov_b32 m0, s26
	ds_read_b128 v[222:225], v151 offset:53248
	global_load_lds_dwordx4 v214, s[10:11]
	s_mov_b32 m0, s27
	ds_read_b128 v[226:229], v151 offset:55296
	global_load_lds_dwordx4 v246, s[10:11]
	s_waitcnt vmcnt(10) lgkmcnt(0)
	s_barrier
	v_mfma_f32_16x16x32_bf16 v[62:65], v[170:173], v[186:189], v[62:65]
	v_mfma_f32_16x16x32_bf16 v[58:61], v[178:181], v[186:189], v[58:61]
	v_mfma_f32_16x16x32_bf16 v[54:57], v[170:173], v[190:193], v[54:57]
	v_mfma_f32_16x16x32_bf16 v[50:53], v[178:181], v[190:193], v[50:53]
	v_mfma_f32_16x16x32_bf16 v[46:49], v[170:173], v[206:209], v[46:49]
	v_mfma_f32_16x16x32_bf16 v[42:45], v[178:181], v[206:209], v[42:45]
	v_mfma_f32_16x16x32_bf16 v[38:41], v[170:173], v[218:221], v[38:41]
	v_mfma_f32_16x16x32_bf16 v[34:37], v[178:181], v[218:221], v[34:37]
	v_mfma_f32_16x16x32_bf16 v[62:65], v[174:177], v[194:197], v[62:65]
	v_mfma_f32_16x16x32_bf16 v[58:61], v[182:185], v[194:197], v[58:61]
	v_mfma_f32_16x16x32_bf16 v[54:57], v[174:177], v[198:201], v[54:57]
	v_mfma_f32_16x16x32_bf16 v[50:53], v[182:185], v[198:201], v[50:53]
	v_mfma_f32_16x16x32_bf16 v[46:49], v[174:177], v[222:225], v[46:49]
	v_mfma_f32_16x16x32_bf16 v[42:45], v[182:185], v[222:225], v[42:45]
	v_mfma_f32_16x16x32_bf16 v[38:41], v[174:177], v[226:229], v[38:41]
	v_mfma_f32_16x16x32_bf16 v[34:37], v[182:185], v[226:229], v[34:37]
	v_mfma_f32_16x16x32_bf16 v[30:33], v[230:233], v[186:189], v[30:33]
	v_mfma_f32_16x16x32_bf16 v[26:29], v[238:241], v[186:189], v[26:29]
	v_mfma_f32_16x16x32_bf16 v[22:25], v[230:233], v[190:193], v[22:25]
	v_mfma_f32_16x16x32_bf16 v[18:21], v[238:241], v[190:193], v[18:21]
	v_mfma_f32_16x16x32_bf16 v[14:17], v[230:233], v[206:209], v[14:17]
	v_mfma_f32_16x16x32_bf16 v[10:13], v[238:241], v[206:209], v[10:13]
	v_mfma_f32_16x16x32_bf16 v[6:9], v[230:233], v[218:221], v[6:9]
	v_mfma_f32_16x16x32_bf16 v[2:5], v[238:241], v[218:221], v[2:5]
	v_mfma_f32_16x16x32_bf16 v[30:33], v[234:237], v[194:197], v[30:33]
	v_mfma_f32_16x16x32_bf16 v[26:29], v[242:245], v[194:197], v[26:29]
	v_mfma_f32_16x16x32_bf16 v[22:25], v[234:237], v[198:201], v[22:25]
	v_mfma_f32_16x16x32_bf16 v[18:21], v[242:245], v[198:201], v[18:21]
	v_mfma_f32_16x16x32_bf16 v[14:17], v[234:237], v[222:225], v[14:17]
	v_mfma_f32_16x16x32_bf16 v[10:13], v[242:245], v[222:225], v[10:13]
	v_mfma_f32_16x16x32_bf16 v[6:9], v[234:237], v[226:229], v[6:9]
	v_mfma_f32_16x16x32_bf16 v[2:5], v[242:245], v[226:229], v[2:5]
	s_add_i32 s12, s12, 2
	s_add_u32 s10, s10, 0x100
	s_addc_u32 s11, s11, 0
	s_cmp_lt_u32 s12, 28
	s_barrier
	s_cbranch_scc1 .LBB0_642
	s_waitcnt vmcnt(6)
	v_or_b32_e32 v0, 0x10000, v152
	v_add_u32_e32 v155, 0x10800, v152
	v_or_b32_e32 v154, 0x10000, v153
	v_add_u32_e32 v156, 0x10800, v153
	v_or_b32_e32 v157, 0x14000, v152
	v_add_u32_e32 v159, 0x14800, v152
	v_or_b32_e32 v158, 0x14000, v153
	v_add_u32_e32 v160, 0x14800, v153
	v_or_b32_e32 v161, 0x18000, v152
	v_add_u32_e32 v163, 0x18800, v152
	v_or_b32_e32 v162, 0x18000, v153
	v_add_u32_e32 v164, 0x18800, v153
	v_or_b32_e32 v165, 0x1c000, v152
	v_add_u32_e32 v167, 0x1c800, v152
	v_or_b32_e32 v166, 0x1c000, v153
	v_add_u32_e32 v168, 0x1c800, v153
	s_mov_b64 s[2:3], 0xf80
	s_mov_b32 m0, s28
	v_lshl_add_u64 v[140:141], v[140:141], 0, s[2:3]
	ds_read_b128 v[142:145], v0
	ds_read_b128 v[146:149], v154
	ds_read_b128 v[152:155], v155
	ds_read_b128 v[170:173], v156
	ds_read_b128 v[174:177], v150
	ds_read_b128 v[178:181], v150 offset:2048
	ds_read_b128 v[182:185], v151
	ds_read_b128 v[186:189], v151 offset:2048
	ds_read_b128 v[190:193], v150 offset:4096
	ds_read_b128 v[194:197], v150 offset:6144
	ds_read_b128 v[198:201], v151 offset:4096
	ds_read_b128 v[206:209], v151 offset:6144
	global_load_lds_dwordx4 v[140:141], off
	v_lshl_add_u64 v[138:139], v[138:139], 0, s[2:3]
	s_mov_b32 m0, s13
	s_nop 0
	global_load_lds_dwordx4 v[138:139], off
	s_barrier
	s_waitcnt lgkmcnt(0)
	s_setprio 1
	s_waitcnt lgkmcnt(0)
	v_mfma_f32_16x16x32_bf16 v[126:129], v[142:145], v[174:177], v[126:129]
	v_mfma_f32_16x16x32_bf16 v[122:125], v[152:155], v[174:177], v[122:125]
	v_mfma_f32_16x16x32_bf16 v[114:117], v[152:155], v[178:181], v[114:117]
	v_mfma_f32_16x16x32_bf16 v[106:109], v[152:155], v[190:193], v[106:109]
	v_mfma_f32_16x16x32_bf16 v[98:101], v[152:155], v[194:197], v[98:101]
	v_mfma_f32_16x16x32_bf16 v[126:129], v[146:149], v[182:185], v[126:129]
	v_mfma_f32_16x16x32_bf16 v[122:125], v[170:173], v[182:185], v[122:125]
	v_mfma_f32_16x16x32_bf16 v[118:121], v[142:145], v[178:181], v[118:121]
	v_mfma_f32_16x16x32_bf16 v[114:117], v[170:173], v[186:189], v[114:117]
	v_mfma_f32_16x16x32_bf16 v[110:113], v[142:145], v[190:193], v[110:113]
	v_mfma_f32_16x16x32_bf16 v[106:109], v[170:173], v[198:201], v[106:109]
	v_mfma_f32_16x16x32_bf16 v[102:105], v[142:145], v[194:197], v[102:105]
	v_mfma_f32_16x16x32_bf16 v[98:101], v[170:173], v[206:209], v[98:101]
	v_mfma_f32_16x16x32_bf16 v[138:141], v[146:149], v[186:189], v[118:121]
	v_mfma_f32_16x16x32_bf16 v[218:221], v[146:149], v[198:201], v[110:113]
	v_mfma_f32_16x16x32_bf16 v[222:225], v[146:149], v[206:209], v[102:105]
	s_setprio 0
	s_barrier
	s_nop 1
	ds_read_b128 v[102:105], v157
	ds_read_b128 v[110:113], v158
	ds_read_b128 v[118:121], v159
	ds_read_b128 v[156:159], v160
	s_barrier
	s_waitcnt lgkmcnt(0)
	s_setprio 1
	s_waitcnt lgkmcnt(0)
	v_mfma_f32_16x16x32_bf16 v[90:93], v[118:121], v[174:177], v[90:93]
	v_mfma_f32_16x16x32_bf16 v[82:85], v[118:121], v[178:181], v[82:85]
	v_mfma_f32_16x16x32_bf16 v[74:77], v[118:121], v[190:193], v[74:77]
	v_mfma_f32_16x16x32_bf16 v[66:69], v[118:121], v[194:197], v[66:69]
	v_mfma_f32_16x16x32_bf16 v[94:97], v[102:105], v[174:177], v[94:97]
	v_mfma_f32_16x16x32_bf16 v[90:93], v[156:159], v[182:185], v[90:93]
	v_mfma_f32_16x16x32_bf16 v[86:89], v[102:105], v[178:181], v[86:89]
	v_mfma_f32_16x16x32_bf16 v[82:85], v[156:159], v[186:189], v[82:85]
	v_mfma_f32_16x16x32_bf16 v[78:81], v[102:105], v[190:193], v[78:81]
	v_mfma_f32_16x16x32_bf16 v[74:77], v[156:159], v[198:201], v[74:77]
	v_mfma_f32_16x16x32_bf16 v[70:73], v[102:105], v[194:197], v[70:73]
	v_mfma_f32_16x16x32_bf16 v[66:69], v[156:159], v[206:209], v[66:69]
	v_mfma_f32_16x16x32_bf16 v[226:229], v[110:113], v[182:185], v[94:97]
	v_mfma_f32_16x16x32_bf16 v[174:177], v[110:113], v[186:189], v[86:89]
	v_mfma_f32_16x16x32_bf16 v[178:181], v[110:113], v[198:201], v[78:81]
	v_mfma_f32_16x16x32_bf16 v[182:185], v[110:113], v[206:209], v[70:73]
	s_setprio 0
	s_barrier
	s_nop 0
	ds_read_b128 v[70:73], v150 offset:16384
	ds_read_b128 v[78:81], v150 offset:18432
	ds_read_b128 v[86:89], v151 offset:16384
	ds_read_b128 v[94:97], v151 offset:18432
	ds_read_b128 v[186:189], v150 offset:20480
	ds_read_b128 v[190:193], v150 offset:22528
	ds_read_b128 v[194:197], v151 offset:20480
	ds_read_b128 v[198:201], v151 offset:22528
	s_waitcnt vmcnt(4)
	s_barrier
	s_waitcnt lgkmcnt(0)
	s_setprio 1
	s_waitcnt lgkmcnt(0)
	v_mfma_f32_16x16x32_bf16 v[62:65], v[142:145], v[70:73], v[62:65]
	v_mfma_f32_16x16x32_bf16 v[58:61], v[152:155], v[70:73], v[58:61]
	v_mfma_f32_16x16x32_bf16 v[50:53], v[152:155], v[78:81], v[50:53]
	v_mfma_f32_16x16x32_bf16 v[42:45], v[152:155], v[186:189], v[42:45]
	v_mfma_f32_16x16x32_bf16 v[34:37], v[152:155], v[190:193], v[34:37]
	v_mfma_f32_16x16x32_bf16 v[62:65], v[146:149], v[86:89], v[62:65]
	v_mfma_f32_16x16x32_bf16 v[58:61], v[170:173], v[86:89], v[58:61]
	v_mfma_f32_16x16x32_bf16 v[54:57], v[142:145], v[78:81], v[54:57]
	v_mfma_f32_16x16x32_bf16 v[50:53], v[170:173], v[94:97], v[50:53]
	v_mfma_f32_16x16x32_bf16 v[46:49], v[142:145], v[186:189], v[46:49]
	v_mfma_f32_16x16x32_bf16 v[42:45], v[170:173], v[194:197], v[42:45]
	v_mfma_f32_16x16x32_bf16 v[38:41], v[142:145], v[190:193], v[38:41]
	v_mfma_f32_16x16x32_bf16 v[34:37], v[170:173], v[198:201], v[34:37]
	v_mfma_f32_16x16x32_bf16 v[206:209], v[146:149], v[94:97], v[54:57]
	v_mfma_f32_16x16x32_bf16 v[230:233], v[146:149], v[194:197], v[46:49]
	v_mfma_f32_16x16x32_bf16 v[142:145], v[146:149], v[198:201], v[38:41]
	s_setprio 0
	s_setprio 1
	v_mfma_f32_16x16x32_bf16 v[26:29], v[118:121], v[70:73], v[26:29]
	v_mfma_f32_16x16x32_bf16 v[18:21], v[118:121], v[78:81], v[18:21]
	v_mfma_f32_16x16x32_bf16 v[10:13], v[118:121], v[186:189], v[10:13]
	v_mfma_f32_16x16x32_bf16 v[2:5], v[118:121], v[190:193], v[2:5]
	v_mfma_f32_16x16x32_bf16 v[30:33], v[102:105], v[70:73], v[30:33]
	v_mfma_f32_16x16x32_bf16 v[26:29], v[156:159], v[86:89], v[26:29]
	v_mfma_f32_16x16x32_bf16 v[22:25], v[102:105], v[78:81], v[22:25]
	v_mfma_f32_16x16x32_bf16 v[18:21], v[156:159], v[94:97], v[18:21]
	v_mfma_f32_16x16x32_bf16 v[14:17], v[102:105], v[186:189], v[14:17]
	v_mfma_f32_16x16x32_bf16 v[10:13], v[156:159], v[194:197], v[10:13]
	v_mfma_f32_16x16x32_bf16 v[6:9], v[102:105], v[190:193], v[6:9]
	v_mfma_f32_16x16x32_bf16 v[2:5], v[156:159], v[198:201], v[2:5]
	v_mfma_f32_16x16x32_bf16 v[146:149], v[110:113], v[86:89], v[30:33]
	v_mfma_f32_16x16x32_bf16 v[152:155], v[110:113], v[94:97], v[22:25]
	v_mfma_f32_16x16x32_bf16 v[170:173], v[110:113], v[194:197], v[14:17]
	v_mfma_f32_16x16x32_bf16 v[186:189], v[110:113], v[198:201], v[6:9]
	s_setprio 0
	s_barrier
	s_nop 0
	ds_read_b128 v[6:9], v161
	ds_read_b128 v[14:17], v162
	ds_read_b128 v[156:159], v163
	ds_read_b128 v[160:163], v164
	ds_read_b128 v[22:25], v150 offset:32768
	ds_read_b128 v[30:33], v150 offset:34816
	ds_read_b128 v[38:41], v151 offset:32768
	ds_read_b128 v[46:49], v151 offset:34816
	ds_read_b128 v[54:57], v150 offset:36864
	ds_read_b128 v[190:193], v150 offset:38912
	ds_read_b128 v[194:197], v151 offset:36864
	ds_read_b128 v[198:201], v151 offset:38912
	s_waitcnt vmcnt(2)
	s_barrier
	s_waitcnt lgkmcnt(0)
	s_setprio 1
	s_waitcnt lgkmcnt(0)
	v_mfma_f32_16x16x32_bf16 v[70:73], v[6:9], v[22:25], v[126:129]
	v_mfma_f32_16x16x32_bf16 v[126:129], v[14:17], v[38:41], v[70:73]
	v_mfma_f32_16x16x32_bf16 v[70:73], v[156:159], v[22:25], v[122:125]
	v_mfma_f32_16x16x32_bf16 v[118:121], v[160:163], v[38:41], v[70:73]
	v_mfma_f32_16x16x32_bf16 v[70:73], v[6:9], v[30:33], v[138:141]
	v_mfma_f32_16x16x32_bf16 v[110:113], v[14:17], v[46:49], v[70:73]
	v_mfma_f32_16x16x32_bf16 v[70:73], v[156:159], v[30:33], v[114:117]
	v_mfma_f32_16x16x32_bf16 v[102:105], v[160:163], v[46:49], v[70:73]
	v_mfma_f32_16x16x32_bf16 v[70:73], v[6:9], v[54:57], v[218:221]
	v_mfma_f32_16x16x32_bf16 v[94:97], v[14:17], v[194:197], v[70:73]
	v_mfma_f32_16x16x32_bf16 v[70:73], v[156:159], v[54:57], v[106:109]
	v_mfma_f32_16x16x32_bf16 v[86:89], v[160:163], v[194:197], v[70:73]
	v_mfma_f32_16x16x32_bf16 v[70:73], v[6:9], v[190:193], v[222:225]
	v_mfma_f32_16x16x32_bf16 v[78:81], v[14:17], v[198:201], v[70:73]
	v_mfma_f32_16x16x32_bf16 v[70:73], v[156:159], v[190:193], v[98:101]
	v_mfma_f32_16x16x32_bf16 v[70:73], v[160:163], v[198:201], v[70:73]
	s_setprio 0
	s_barrier
	ds_read_b128 v[138:141], v165
	ds_read_b128 v[218:221], v166
	ds_read_b128 v[164:167], v167
	ds_read_b128 v[222:225], v168
	s_waitcnt vmcnt(0)
	s_barrier
	s_waitcnt lgkmcnt(0)
	s_setprio 1
	s_waitcnt lgkmcnt(0)
	v_mfma_f32_16x16x32_bf16 v[98:101], v[138:141], v[22:25], v[226:229]
	v_mfma_f32_16x16x32_bf16 v[22:25], v[164:167], v[22:25], v[90:93]
	v_mfma_f32_16x16x32_bf16 v[114:117], v[222:225], v[38:41], v[22:25]
	v_mfma_f32_16x16x32_bf16 v[22:25], v[138:141], v[30:33], v[174:177]
	v_mfma_f32_16x16x32_bf16 v[106:109], v[218:221], v[46:49], v[22:25]
	v_mfma_f32_16x16x32_bf16 v[22:25], v[164:167], v[30:33], v[82:85]
	v_mfma_f32_16x16x32_bf16 v[122:125], v[218:221], v[38:41], v[98:101]
	v_mfma_f32_16x16x32_bf16 v[98:101], v[222:225], v[46:49], v[22:25]
	v_mfma_f32_16x16x32_bf16 v[22:25], v[138:141], v[54:57], v[178:181]
	v_mfma_f32_16x16x32_bf16 v[90:93], v[218:221], v[194:197], v[22:25]
	v_mfma_f32_16x16x32_bf16 v[22:25], v[164:167], v[54:57], v[74:77]
	v_mfma_f32_16x16x32_bf16 v[82:85], v[222:225], v[194:197], v[22:25]
	v_mfma_f32_16x16x32_bf16 v[22:25], v[138:141], v[190:193], v[182:185]
	v_mfma_f32_16x16x32_bf16 v[74:77], v[218:221], v[198:201], v[22:25]
	v_mfma_f32_16x16x32_bf16 v[22:25], v[164:167], v[190:193], v[66:69]
	v_mfma_f32_16x16x32_bf16 v[66:69], v[222:225], v[198:201], v[22:25]
	s_setprio 0
	s_barrier
	ds_read_b128 v[174:177], v150 offset:49152
	ds_read_b128 v[178:181], v150 offset:51200
	ds_read_b128 v[182:185], v151 offset:49152
	ds_read_b128 v[190:193], v151 offset:51200
	ds_read_b128 v[194:197], v150 offset:53248
	ds_read_b128 v[198:201], v150 offset:55296
	ds_read_b128 v[226:229], v151 offset:53248
	ds_read_b128 v[234:237], v151 offset:55296
	s_barrier
	s_waitcnt lgkmcnt(0)
	s_setprio 1
	s_waitcnt lgkmcnt(0)
	v_mfma_f32_16x16x32_bf16 v[22:25], v[6:9], v[174:177], v[62:65]
	v_mfma_f32_16x16x32_bf16 v[62:65], v[14:17], v[182:185], v[22:25]
	v_mfma_f32_16x16x32_bf16 v[22:25], v[156:159], v[174:177], v[58:61]
	v_mfma_f32_16x16x32_bf16 v[54:57], v[160:163], v[182:185], v[22:25]
	v_mfma_f32_16x16x32_bf16 v[22:25], v[6:9], v[178:181], v[206:209]
	v_mfma_f32_16x16x32_bf16 v[46:49], v[14:17], v[190:193], v[22:25]
	v_mfma_f32_16x16x32_bf16 v[22:25], v[156:159], v[178:181], v[50:53]
	v_mfma_f32_16x16x32_bf16 v[38:41], v[160:163], v[190:193], v[22:25]
	v_mfma_f32_16x16x32_bf16 v[22:25], v[6:9], v[194:197], v[230:233]
	v_mfma_f32_16x16x32_bf16 v[6:9], v[6:9], v[198:201], v[142:145]
	v_mfma_f32_16x16x32_bf16 v[30:33], v[14:17], v[226:229], v[22:25]
	v_mfma_f32_16x16x32_bf16 v[22:25], v[156:159], v[194:197], v[42:45]
	v_mfma_f32_16x16x32_bf16 v[14:17], v[14:17], v[234:237], v[6:9]
	v_mfma_f32_16x16x32_bf16 v[6:9], v[156:159], v[198:201], v[34:37]
	v_mfma_f32_16x16x32_bf16 v[22:25], v[160:163], v[226:229], v[22:25]
	v_mfma_f32_16x16x32_bf16 v[6:9], v[160:163], v[234:237], v[6:9]
	s_setprio 0
	s_setprio 1
	v_mfma_f32_16x16x32_bf16 v[34:37], v[138:141], v[174:177], v[146:149]
	v_mfma_f32_16x16x32_bf16 v[26:29], v[164:167], v[174:177], v[26:29]
	v_mfma_f32_16x16x32_bf16 v[18:21], v[164:167], v[178:181], v[18:21]
	v_mfma_f32_16x16x32_bf16 v[58:61], v[218:221], v[182:185], v[34:37]
	v_mfma_f32_16x16x32_bf16 v[50:53], v[222:225], v[182:185], v[26:29]
	v_mfma_f32_16x16x32_bf16 v[26:29], v[138:141], v[178:181], v[152:155]
	v_mfma_f32_16x16x32_bf16 v[34:37], v[222:225], v[190:193], v[18:21]
	v_mfma_f32_16x16x32_bf16 v[18:21], v[138:141], v[194:197], v[170:173]
	v_mfma_f32_16x16x32_bf16 v[10:13], v[164:167], v[194:197], v[10:13]
	v_mfma_f32_16x16x32_bf16 v[42:45], v[218:221], v[190:193], v[26:29]
	v_mfma_f32_16x16x32_bf16 v[26:29], v[218:221], v[226:229], v[18:21]
	v_mfma_f32_16x16x32_bf16 v[18:21], v[222:225], v[226:229], v[10:13]
	v_mfma_f32_16x16x32_bf16 v[10:13], v[138:141], v[198:201], v[186:189]
	v_mfma_f32_16x16x32_bf16 v[2:5], v[164:167], v[198:201], v[2:5]
	v_mfma_f32_16x16x32_bf16 v[10:13], v[218:221], v[234:237], v[10:13]
	v_mfma_f32_16x16x32_bf16 v[2:5], v[222:225], v[234:237], v[2:5]
	s_setprio 0
	s_cmpk_gt_u32 s0, 0xff
	s_barrier
	s_cbranch_scc1 .LBB0_633
	s_barrier
	s_branch .LBB0_633

.LBB0_664:
	s_lshl_b32 s20, s20, 5
	v_and_b32_e32 v19, 15, v17
	s_and_b32 s20, s20, 0x60
	v_lshlrev_b32_e32 v20, 7, v19
	v_or_b32_e32 v19, s20, v19
	s_add_i32 s20, s1, 0x18000
	s_mov_b64 s[26:27], 0x80
	v_lshl_or_b32 v20, s21, 13, v20
	v_lshl_add_u64 v[2:3], v[2:3], 0, s[26:27]
	s_mov_b32 m0, s20
	s_add_i32 s21, s1, 0x1a000
	s_waitcnt vmcnt(4)
	s_barrier
	global_load_lds_dwordx4 v[2:3], off
	v_lshl_add_u64 v[2:3], v[4:5], 0, s[26:27]
	s_mov_b32 m0, s21
	s_mov_b64 s[22:23], 0x400800
	global_load_lds_dwordx4 v[2:3], off
	v_lshl_add_u64 v[2:3], v[6:7], 0, s[22:23]
	s_add_i32 s22, s1, 0x8000
	v_lshl_add_u64 v[4:5], v[0:1], 1, v[2:3]
	s_mov_b32 m0, s22
	s_add_i32 s23, s1, 0xa000
	global_load_lds_dwordx4 v[4:5], off nt
	v_lshl_add_u64 v[2:3], v[138:139], 1, v[2:3]
	s_mov_b32 m0, s23
	s_add_i32 s24, s1, 0x1c000
	global_load_lds_dwordx4 v[2:3], off nt
	v_lshl_add_u64 v[2:3], v[10:11], 0, s[26:27]
	s_mov_b32 m0, s24
	s_add_i32 s25, s1, 0x1e000
	global_load_lds_dwordx4 v[2:3], off
	v_lshl_add_u64 v[2:3], v[8:9], 0, s[26:27]
	s_mov_b32 m0, s25
	s_add_u32 s12, s4, s12
	global_load_lds_dwordx4 v[2:3], off
	s_addc_u32 s13, 0, s13
	v_add_u32_e32 v2, v16, v12
	v_mov_b32_e32 v3, v1
	v_lshl_add_u64 v[142:143], v[2:3], 1, s[12:13]
	v_add_u32_e32 v2, v14, v12
	v_bfe_u32 v21, v17, 4, 2
	v_bfe_u32 v17, v17, 1, 3
	v_lshl_add_u64 v[144:145], v[2:3], 1, s[12:13]
	v_add_u32_e32 v2, v15, v12
	v_bitop3_b32 v18, v18, v17, 3 bitop3:0x6c
	v_bitop3_b32 v17, v21, v17, 4 bitop3:0x36
	s_waitcnt vmcnt(6)
	v_lshl_add_u64 v[146:147], v[2:3], 1, s[10:11]
	v_add_u32_e32 v2, v13, v12
	v_lshlrev_b32_e32 v18, 4, v18
	v_lshlrev_b32_e32 v17, 4, v17
	v_lshlrev_b32_e32 v19, 7, v19
	v_lshl_add_u64 v[148:149], v[2:3], 1, s[10:11]
	v_mov_b32_e32 v2, 0
	v_or_b32_e32 v150, v18, v20
	v_or_b32_e32 v152, v19, v18
	v_or_b32_e32 v153, v19, v17
	v_or_b32_e32 v151, v17, v20
	s_mov_b32 s10, -2
	v_mov_b32_e32 v3, v2
	v_mov_b32_e32 v4, v2
	v_mov_b32_e32 v5, v2
	v_mov_b32_e32 v6, v2
	v_mov_b32_e32 v7, v2
	v_mov_b32_e32 v8, v2
	v_mov_b32_e32 v9, v2
	v_mov_b32_e32 v10, v2
	v_mov_b32_e32 v11, v2
	v_mov_b32_e32 v12, v2
	v_mov_b32_e32 v13, v2
	v_mov_b32_e32 v14, v2
	v_mov_b32_e32 v15, v2
	v_mov_b32_e32 v16, v2
	v_mov_b32_e32 v17, v2
	v_mov_b32_e32 v18, v2
	v_mov_b32_e32 v19, v2
	v_mov_b32_e32 v20, v2
	v_mov_b32_e32 v21, v2
	v_mov_b32_e32 v22, v2
	v_mov_b32_e32 v23, v2
	v_mov_b32_e32 v24, v2
	v_mov_b32_e32 v25, v2
	v_mov_b32_e32 v26, v2
	v_mov_b32_e32 v27, v2
	v_mov_b32_e32 v28, v2
	v_mov_b32_e32 v29, v2
	v_mov_b32_e32 v30, v2
	v_mov_b32_e32 v31, v2
	v_mov_b32_e32 v32, v2
	v_mov_b32_e32 v33, v2
	v_mov_b32_e32 v34, v2
	v_mov_b32_e32 v35, v2
	v_mov_b32_e32 v36, v2
	v_mov_b32_e32 v37, v2
	v_mov_b32_e32 v38, v2
	v_mov_b32_e32 v39, v2
	v_mov_b32_e32 v40, v2
	v_mov_b32_e32 v41, v2
	v_mov_b32_e32 v42, v2
	v_mov_b32_e32 v43, v2
	v_mov_b32_e32 v44, v2
	v_mov_b32_e32 v45, v2
	v_mov_b32_e32 v46, v2
	v_mov_b32_e32 v47, v2
	v_mov_b32_e32 v48, v2
	v_mov_b32_e32 v49, v2
	v_mov_b32_e32 v50, v2
	v_mov_b32_e32 v51, v2
	v_mov_b32_e32 v52, v2
	v_mov_b32_e32 v53, v2
	v_mov_b32_e32 v54, v2
	v_mov_b32_e32 v55, v2
	v_mov_b32_e32 v56, v2
	v_mov_b32_e32 v57, v2
	v_mov_b32_e32 v58, v2
	v_mov_b32_e32 v59, v2
	v_mov_b32_e32 v60, v2
	v_mov_b32_e32 v61, v2
	v_mov_b32_e32 v62, v2
	v_mov_b32_e32 v63, v2
	v_mov_b32_e32 v64, v2
	v_mov_b32_e32 v65, v2
	v_mov_b32_e32 v66, v2
	v_mov_b32_e32 v67, v2
	v_mov_b32_e32 v68, v2
	v_mov_b32_e32 v69, v2
	v_mov_b32_e32 v70, v2
	v_mov_b32_e32 v71, v2
	v_mov_b32_e32 v72, v2
	v_mov_b32_e32 v73, v2
	v_mov_b32_e32 v74, v2
	v_mov_b32_e32 v75, v2
	v_mov_b32_e32 v76, v2
	v_mov_b32_e32 v77, v2
	v_mov_b32_e32 v78, v2
	v_mov_b32_e32 v79, v2
	v_mov_b32_e32 v80, v2
	v_mov_b32_e32 v81, v2
	v_mov_b32_e32 v82, v2
	v_mov_b32_e32 v83, v2
	v_mov_b32_e32 v84, v2
	v_mov_b32_e32 v85, v2
	v_mov_b32_e32 v86, v2
	v_mov_b32_e32 v87, v2
	v_mov_b32_e32 v88, v2
	v_mov_b32_e32 v89, v2
	v_mov_b32_e32 v90, v2
	v_mov_b32_e32 v91, v2
	v_mov_b32_e32 v92, v2
	v_mov_b32_e32 v93, v2
	v_mov_b32_e32 v94, v2
	v_mov_b32_e32 v95, v2
	v_mov_b32_e32 v96, v2
	v_mov_b32_e32 v97, v2
	v_mov_b32_e32 v98, v2
	v_mov_b32_e32 v99, v2
	v_mov_b32_e32 v100, v2
	v_mov_b32_e32 v101, v2
	v_mov_b32_e32 v102, v2
	v_mov_b32_e32 v103, v2
	v_mov_b32_e32 v104, v2
	v_mov_b32_e32 v105, v2
	v_mov_b32_e32 v106, v2
	v_mov_b32_e32 v107, v2
	v_mov_b32_e32 v108, v2
	v_mov_b32_e32 v109, v2
	v_mov_b32_e32 v110, v2
	v_mov_b32_e32 v111, v2
	v_mov_b32_e32 v112, v2
	v_mov_b32_e32 v113, v2
	v_mov_b32_e32 v114, v2
	v_mov_b32_e32 v115, v2
	v_mov_b32_e32 v116, v2
	v_mov_b32_e32 v117, v2
	v_mov_b32_e32 v118, v2
	v_mov_b32_e32 v119, v2
	v_mov_b32_e32 v120, v2
	v_mov_b32_e32 v121, v2
	v_mov_b32_e32 v122, v2
	v_mov_b32_e32 v123, v2
	v_mov_b32_e32 v124, v2
	v_mov_b32_e32 v125, v2
	v_mov_b32_e32 v126, v2
	v_mov_b32_e32 v127, v2
	v_mov_b32_e32 v128, v2
	v_mov_b32_e32 v129, v2
	s_mov_b64 s[26:27], 0x404800
	s_mov_b64 s[30:31], 0xc254900
	s_mov_b64 s[34:35], 0xc454900
	s_mov_b64 s[36:37], 0x805000
	v_readfirstlane_b32 s100, v130
	v_readfirstlane_b32 s101, v131
	s_mov_b64 vcc, s[100:101]
	v_add_u32_e32 v202, 0x10000, v152
	v_add_u32_e32 v203, 0x10000, v153
	v_add_u32_e32 v143, s26, v144
	v_add_u32_e32 v145, s42, v144
	v_add_u32_e32 v147, s36, v144
	v_add_u32_e32 v144, s96, v144
	v_add_u32_e32 v149, s26, v142
	v_add_u32_e32 v154, s42, v142
	v_add_u32_e32 v155, s36, v142
	v_add_u32_e32 v142, s96, v142
	v_add_u32_e32 v156, s30, v148
	v_add_u32_e32 v157, s34, v148
	v_add_u32_e32 v158, s46, v148
	v_add_u32_e32 v148, s68, v148
	v_add_u32_e32 v159, s30, v146
	v_add_u32_e32 v160, s34, v146
	v_add_u32_e32 v161, s46, v146
	v_add_u32_e32 v146, s68, v146
	s_barrier
.LBB0_665:
	ds_read_b128 v[162:165], v202
	ds_read_b128 v[166:169], v203
	ds_read_b128 v[170:173], v202 offset:2048
	ds_read_b128 v[174:177], v203 offset:2048
	ds_read_b128 v[178:181], v150
	ds_read_b128 v[182:185], v150 offset:2048
	ds_read_b128 v[186:189], v151
	ds_read_b128 v[190:193], v151 offset:2048
	ds_read_b128 v[194:197], v150 offset:4096
	ds_read_b128 v[198:201], v150 offset:6144
	s_add_i32 m0, s1, 0xc000
	ds_read_b128 v[206:209], v151 offset:4096
	global_load_lds_dwordx4 v143, vcc nt
	s_add_i32 m0, s1, 0xe000
	ds_read_b128 v[218:221], v151 offset:6144
	global_load_lds_dwordx4 v149, vcc nt
	s_waitcnt vmcnt(10) lgkmcnt(8)
	s_barrier
	s_waitcnt lgkmcnt(0)
	v_mfma_f32_16x16x32_bf16 v[126:129], v[162:165], v[178:181], v[126:129]
	v_mfma_f32_16x16x32_bf16 v[122:125], v[170:173], v[178:181], v[122:125]
	v_mfma_f32_16x16x32_bf16 v[118:121], v[162:165], v[182:185], v[118:121]
	v_mfma_f32_16x16x32_bf16 v[114:117], v[170:173], v[182:185], v[114:117]
	v_mfma_f32_16x16x32_bf16 v[110:113], v[162:165], v[194:197], v[110:113]
	v_mfma_f32_16x16x32_bf16 v[106:109], v[170:173], v[194:197], v[106:109]
	v_mfma_f32_16x16x32_bf16 v[102:105], v[162:165], v[198:201], v[102:105]
	v_mfma_f32_16x16x32_bf16 v[98:101], v[170:173], v[198:201], v[98:101]
	v_mfma_f32_16x16x32_bf16 v[126:129], v[166:169], v[186:189], v[126:129]
	v_mfma_f32_16x16x32_bf16 v[122:125], v[174:177], v[186:189], v[122:125]
	v_mfma_f32_16x16x32_bf16 v[118:121], v[166:169], v[190:193], v[118:121]
	v_mfma_f32_16x16x32_bf16 v[114:117], v[174:177], v[190:193], v[114:117]
	v_mfma_f32_16x16x32_bf16 v[110:113], v[166:169], v[206:209], v[110:113]
	v_mfma_f32_16x16x32_bf16 v[106:109], v[174:177], v[206:209], v[106:109]
	v_mfma_f32_16x16x32_bf16 v[102:105], v[166:169], v[218:221], v[102:105]
	v_mfma_f32_16x16x32_bf16 v[98:101], v[174:177], v[218:221], v[98:101]
	s_barrier
	ds_read_b128 v[222:225], v202 offset:16384
	ds_read_b128 v[226:229], v203 offset:16384
	s_mov_b32 m0, s2
	ds_read_b128 v[230:233], v202 offset:18432
	global_load_lds_dwordx4 v156, s[100:101]
	s_mov_b32 m0, s3
	ds_read_b128 v[234:237], v203 offset:18432
	global_load_lds_dwordx4 v159, s[100:101]
	s_waitcnt vmcnt(10) lgkmcnt(0)
	s_barrier
	v_mfma_f32_16x16x32_bf16 v[94:97], v[222:225], v[178:181], v[94:97]
	v_mfma_f32_16x16x32_bf16 v[90:93], v[230:233], v[178:181], v[90:93]
	v_mfma_f32_16x16x32_bf16 v[86:89], v[222:225], v[182:185], v[86:89]
	v_mfma_f32_16x16x32_bf16 v[82:85], v[230:233], v[182:185], v[82:85]
	v_mfma_f32_16x16x32_bf16 v[78:81], v[222:225], v[194:197], v[78:81]
	v_mfma_f32_16x16x32_bf16 v[74:77], v[230:233], v[194:197], v[74:77]
	v_mfma_f32_16x16x32_bf16 v[70:73], v[222:225], v[198:201], v[70:73]
	v_mfma_f32_16x16x32_bf16 v[66:69], v[230:233], v[198:201], v[66:69]
	v_mfma_f32_16x16x32_bf16 v[94:97], v[226:229], v[186:189], v[94:97]
	v_mfma_f32_16x16x32_bf16 v[90:93], v[234:237], v[186:189], v[90:93]
	v_mfma_f32_16x16x32_bf16 v[86:89], v[226:229], v[190:193], v[86:89]
	v_mfma_f32_16x16x32_bf16 v[82:85], v[234:237], v[190:193], v[82:85]
	v_mfma_f32_16x16x32_bf16 v[78:81], v[226:229], v[206:209], v[78:81]
	v_mfma_f32_16x16x32_bf16 v[74:77], v[234:237], v[206:209], v[74:77]
	v_mfma_f32_16x16x32_bf16 v[70:73], v[226:229], v[218:221], v[70:73]
	v_mfma_f32_16x16x32_bf16 v[66:69], v[234:237], v[218:221], v[66:69]
	s_barrier
	ds_read_b128 v[178:181], v150 offset:16384
	ds_read_b128 v[182:185], v150 offset:18432
	ds_read_b128 v[186:189], v151 offset:16384
	ds_read_b128 v[190:193], v151 offset:18432
	s_mov_b32 m0, s1
	ds_read_b128 v[194:197], v150 offset:20480
	global_load_lds_dwordx4 v145, vcc nt
	s_mov_b32 m0, s5
	ds_read_b128 v[198:201], v150 offset:22528
	global_load_lds_dwordx4 v154, vcc nt
	s_mov_b32 m0, s15
	ds_read_b128 v[206:209], v151 offset:20480
	global_load_lds_dwordx4 v157, s[100:101]
	s_mov_b32 m0, s17
	ds_read_b128 v[218:221], v151 offset:22528
	global_load_lds_dwordx4 v160, s[100:101]
	s_waitcnt vmcnt(10) lgkmcnt(0)
	s_barrier
	v_mfma_f32_16x16x32_bf16 v[62:65], v[162:165], v[178:181], v[62:65]
	v_mfma_f32_16x16x32_bf16 v[58:61], v[170:173], v[178:181], v[58:61]
	v_mfma_f32_16x16x32_bf16 v[54:57], v[162:165], v[182:185], v[54:57]
	v_mfma_f32_16x16x32_bf16 v[50:53], v[170:173], v[182:185], v[50:53]
	v_mfma_f32_16x16x32_bf16 v[46:49], v[162:165], v[194:197], v[46:49]
	v_mfma_f32_16x16x32_bf16 v[42:45], v[170:173], v[194:197], v[42:45]
	v_mfma_f32_16x16x32_bf16 v[38:41], v[162:165], v[198:201], v[38:41]
	v_mfma_f32_16x16x32_bf16 v[34:37], v[170:173], v[198:201], v[34:37]
	v_mfma_f32_16x16x32_bf16 v[62:65], v[166:169], v[186:189], v[62:65]
	v_mfma_f32_16x16x32_bf16 v[58:61], v[174:177], v[186:189], v[58:61]
	v_mfma_f32_16x16x32_bf16 v[54:57], v[166:169], v[190:193], v[54:57]
	v_mfma_f32_16x16x32_bf16 v[50:53], v[174:177], v[190:193], v[50:53]
	v_mfma_f32_16x16x32_bf16 v[46:49], v[166:169], v[206:209], v[46:49]
	v_mfma_f32_16x16x32_bf16 v[42:45], v[174:177], v[206:209], v[42:45]
	v_mfma_f32_16x16x32_bf16 v[38:41], v[166:169], v[218:221], v[38:41]
	v_mfma_f32_16x16x32_bf16 v[34:37], v[174:177], v[218:221], v[34:37]
	v_mfma_f32_16x16x32_bf16 v[30:33], v[222:225], v[178:181], v[30:33]
	v_mfma_f32_16x16x32_bf16 v[26:29], v[230:233], v[178:181], v[26:29]
	v_mfma_f32_16x16x32_bf16 v[22:25], v[222:225], v[182:185], v[22:25]
	v_mfma_f32_16x16x32_bf16 v[18:21], v[230:233], v[182:185], v[18:21]
	v_mfma_f32_16x16x32_bf16 v[14:17], v[222:225], v[194:197], v[14:17]
	v_mfma_f32_16x16x32_bf16 v[10:13], v[230:233], v[194:197], v[10:13]
	v_mfma_f32_16x16x32_bf16 v[6:9], v[222:225], v[198:201], v[6:9]
	v_mfma_f32_16x16x32_bf16 v[2:5], v[230:233], v[198:201], v[2:5]
	v_mfma_f32_16x16x32_bf16 v[30:33], v[226:229], v[186:189], v[30:33]
	v_mfma_f32_16x16x32_bf16 v[26:29], v[234:237], v[186:189], v[26:29]
	v_mfma_f32_16x16x32_bf16 v[22:25], v[226:229], v[190:193], v[22:25]
	v_mfma_f32_16x16x32_bf16 v[18:21], v[234:237], v[190:193], v[18:21]
	v_mfma_f32_16x16x32_bf16 v[14:17], v[226:229], v[206:209], v[14:17]
	v_mfma_f32_16x16x32_bf16 v[10:13], v[234:237], v[206:209], v[10:13]
	v_mfma_f32_16x16x32_bf16 v[6:9], v[226:229], v[218:221], v[6:9]
	v_mfma_f32_16x16x32_bf16 v[2:5], v[234:237], v[218:221], v[2:5]
	s_barrier
	ds_read_b128 v[170:173], v202 offset:32768
	ds_read_b128 v[174:177], v203 offset:32768
	ds_read_b128 v[178:181], v202 offset:34816
	ds_read_b128 v[182:185], v203 offset:34816
	ds_read_b128 v[186:189], v150 offset:32768
	ds_read_b128 v[190:193], v150 offset:34816
	ds_read_b128 v[194:197], v151 offset:32768
	ds_read_b128 v[198:201], v151 offset:34816
	ds_read_b128 v[206:209], v150 offset:36864
	ds_read_b128 v[218:221], v150 offset:38912
	s_mov_b32 m0, s18
	ds_read_b128 v[222:225], v151 offset:36864
	global_load_lds_dwordx4 v147, vcc nt
	s_mov_b32 m0, s19
	ds_read_b128 v[226:229], v151 offset:38912
	global_load_lds_dwordx4 v155, vcc nt
	s_waitcnt vmcnt(10) lgkmcnt(8)
	s_barrier
	s_waitcnt lgkmcnt(0)
	v_mfma_f32_16x16x32_bf16 v[126:129], v[170:173], v[186:189], v[126:129]
	v_mfma_f32_16x16x32_bf16 v[122:125], v[178:181], v[186:189], v[122:125]
	v_mfma_f32_16x16x32_bf16 v[118:121], v[170:173], v[190:193], v[118:121]
	v_mfma_f32_16x16x32_bf16 v[114:117], v[178:181], v[190:193], v[114:117]
	v_mfma_f32_16x16x32_bf16 v[110:113], v[170:173], v[206:209], v[110:113]
	v_mfma_f32_16x16x32_bf16 v[106:109], v[178:181], v[206:209], v[106:109]
	v_mfma_f32_16x16x32_bf16 v[102:105], v[170:173], v[218:221], v[102:105]
	v_mfma_f32_16x16x32_bf16 v[98:101], v[178:181], v[218:221], v[98:101]
	v_mfma_f32_16x16x32_bf16 v[126:129], v[174:177], v[194:197], v[126:129]
	v_mfma_f32_16x16x32_bf16 v[122:125], v[182:185], v[194:197], v[122:125]
	v_mfma_f32_16x16x32_bf16 v[118:121], v[174:177], v[198:201], v[118:121]
	v_mfma_f32_16x16x32_bf16 v[114:117], v[182:185], v[198:201], v[114:117]
	v_mfma_f32_16x16x32_bf16 v[110:113], v[174:177], v[222:225], v[110:113]
	v_mfma_f32_16x16x32_bf16 v[106:109], v[182:185], v[222:225], v[106:109]
	v_mfma_f32_16x16x32_bf16 v[102:105], v[174:177], v[226:229], v[102:105]
	v_mfma_f32_16x16x32_bf16 v[98:101], v[182:185], v[226:229], v[98:101]
	s_barrier
	ds_read_b128 v[230:233], v202 offset:49152
	ds_read_b128 v[234:237], v203 offset:49152
	s_mov_b32 m0, s20
	ds_read_b128 v[238:241], v202 offset:51200
	global_load_lds_dwordx4 v158, s[100:101]
	s_mov_b32 m0, s21
	ds_read_b128 v[242:245], v203 offset:51200
	global_load_lds_dwordx4 v161, s[100:101]
	s_waitcnt vmcnt(10) lgkmcnt(0)
	s_barrier
	v_mfma_f32_16x16x32_bf16 v[94:97], v[230:233], v[186:189], v[94:97]
	v_mfma_f32_16x16x32_bf16 v[90:93], v[238:241], v[186:189], v[90:93]
	v_mfma_f32_16x16x32_bf16 v[86:89], v[230:233], v[190:193], v[86:89]
	v_mfma_f32_16x16x32_bf16 v[82:85], v[238:241], v[190:193], v[82:85]
	v_mfma_f32_16x16x32_bf16 v[78:81], v[230:233], v[206:209], v[78:81]
	v_mfma_f32_16x16x32_bf16 v[74:77], v[238:241], v[206:209], v[74:77]
	v_mfma_f32_16x16x32_bf16 v[70:73], v[230:233], v[218:221], v[70:73]
	v_mfma_f32_16x16x32_bf16 v[66:69], v[238:241], v[218:221], v[66:69]
	v_mfma_f32_16x16x32_bf16 v[94:97], v[234:237], v[194:197], v[94:97]
	v_mfma_f32_16x16x32_bf16 v[90:93], v[242:245], v[194:197], v[90:93]
	v_mfma_f32_16x16x32_bf16 v[86:89], v[234:237], v[198:201], v[86:89]
	v_mfma_f32_16x16x32_bf16 v[82:85], v[242:245], v[198:201], v[82:85]
	v_mfma_f32_16x16x32_bf16 v[78:81], v[234:237], v[222:225], v[78:81]
	v_mfma_f32_16x16x32_bf16 v[74:77], v[242:245], v[222:225], v[74:77]
	v_mfma_f32_16x16x32_bf16 v[70:73], v[234:237], v[226:229], v[70:73]
	v_mfma_f32_16x16x32_bf16 v[66:69], v[242:245], v[226:229], v[66:69]
	s_barrier
	ds_read_b128 v[186:189], v150 offset:49152
	ds_read_b128 v[190:193], v150 offset:51200
	ds_read_b128 v[194:197], v151 offset:49152
	ds_read_b128 v[198:201], v151 offset:51200
	s_mov_b32 m0, s22
	ds_read_b128 v[206:209], v150 offset:53248
	global_load_lds_dwordx4 v144, vcc nt
	s_mov_b32 m0, s23
	ds_read_b128 v[218:221], v150 offset:55296
	global_load_lds_dwordx4 v142, vcc nt
	s_mov_b32 m0, s24
	ds_read_b128 v[222:225], v151 offset:53248
	global_load_lds_dwordx4 v148, s[100:101]
	s_mov_b32 m0, s25
	ds_read_b128 v[226:229], v151 offset:55296
	global_load_lds_dwordx4 v146, s[100:101]
	s_waitcnt vmcnt(10) lgkmcnt(0)
	s_barrier
	v_mfma_f32_16x16x32_bf16 v[62:65], v[170:173], v[186:189], v[62:65]
	v_mfma_f32_16x16x32_bf16 v[58:61], v[178:181], v[186:189], v[58:61]
	v_mfma_f32_16x16x32_bf16 v[54:57], v[170:173], v[190:193], v[54:57]
	v_mfma_f32_16x16x32_bf16 v[50:53], v[178:181], v[190:193], v[50:53]
	v_mfma_f32_16x16x32_bf16 v[46:49], v[170:173], v[206:209], v[46:49]
	v_mfma_f32_16x16x32_bf16 v[42:45], v[178:181], v[206:209], v[42:45]
	v_mfma_f32_16x16x32_bf16 v[38:41], v[170:173], v[218:221], v[38:41]
	v_mfma_f32_16x16x32_bf16 v[34:37], v[178:181], v[218:221], v[34:37]
	v_mfma_f32_16x16x32_bf16 v[62:65], v[174:177], v[194:197], v[62:65]
	v_mfma_f32_16x16x32_bf16 v[58:61], v[182:185], v[194:197], v[58:61]
	v_mfma_f32_16x16x32_bf16 v[54:57], v[174:177], v[198:201], v[54:57]
	v_mfma_f32_16x16x32_bf16 v[50:53], v[182:185], v[198:201], v[50:53]
	v_mfma_f32_16x16x32_bf16 v[46:49], v[174:177], v[222:225], v[46:49]
	v_mfma_f32_16x16x32_bf16 v[42:45], v[182:185], v[222:225], v[42:45]
	v_mfma_f32_16x16x32_bf16 v[38:41], v[174:177], v[226:229], v[38:41]
	v_mfma_f32_16x16x32_bf16 v[34:37], v[182:185], v[226:229], v[34:37]
	v_mfma_f32_16x16x32_bf16 v[30:33], v[230:233], v[186:189], v[30:33]
	v_mfma_f32_16x16x32_bf16 v[26:29], v[238:241], v[186:189], v[26:29]
	v_mfma_f32_16x16x32_bf16 v[22:25], v[230:233], v[190:193], v[22:25]
	v_mfma_f32_16x16x32_bf16 v[18:21], v[238:241], v[190:193], v[18:21]
	v_mfma_f32_16x16x32_bf16 v[14:17], v[230:233], v[206:209], v[14:17]
	v_mfma_f32_16x16x32_bf16 v[10:13], v[238:241], v[206:209], v[10:13]
	v_mfma_f32_16x16x32_bf16 v[6:9], v[230:233], v[218:221], v[6:9]
	v_mfma_f32_16x16x32_bf16 v[2:5], v[238:241], v[218:221], v[2:5]
	v_mfma_f32_16x16x32_bf16 v[30:33], v[234:237], v[194:197], v[30:33]
	v_mfma_f32_16x16x32_bf16 v[26:29], v[242:245], v[194:197], v[26:29]
	v_mfma_f32_16x16x32_bf16 v[22:25], v[234:237], v[198:201], v[22:25]
	v_mfma_f32_16x16x32_bf16 v[18:21], v[242:245], v[198:201], v[18:21]
	v_mfma_f32_16x16x32_bf16 v[14:17], v[234:237], v[222:225], v[14:17]
	v_mfma_f32_16x16x32_bf16 v[10:13], v[242:245], v[222:225], v[10:13]
	v_mfma_f32_16x16x32_bf16 v[6:9], v[234:237], v[226:229], v[6:9]
	v_mfma_f32_16x16x32_bf16 v[2:5], v[242:245], v[226:229], v[2:5]
	s_add_u32 vcc_lo, vcc_lo, s42
	s_addc_u32 vcc_hi, vcc_hi, s43
	s_add_u32 s100, s100, s54
	s_addc_u32 s101, s101, s55
	s_add_i32 s10, s10, 2
	s_cmpk_lt_u32 s10, 0x7c
	s_barrier
	s_cbranch_scc1 .LBB0_665
	s_waitcnt vmcnt(6)
	v_or_b32_e32 v154, 0x10000, v152
	v_add_u32_e32 v156, 0x10800, v152
	v_or_b32_e32 v155, 0x10000, v153
	v_add_u32_e32 v157, 0x10800, v153
	s_add_i32 s12, s1, 0xc000
	s_add_i32 s11, s1, 0xe000
	v_or_b32_e32 v158, 0x14000, v152
	v_add_u32_e32 v160, 0x14800, v152
	v_or_b32_e32 v159, 0x14000, v153
	v_add_u32_e32 v161, 0x14800, v153
	v_or_b32_e32 v162, 0x18000, v152
	v_add_u32_e32 v164, 0x18800, v152
	v_or_b32_e32 v163, 0x18000, v153
	v_add_u32_e32 v165, 0x18800, v153
	v_or_b32_e32 v166, 0x1c000, v152
	v_add_u32_e32 v168, 0x1c800, v152
	v_or_b32_e32 v167, 0x1c000, v153
	v_add_u32_e32 v169, 0x1c800, v153
	s_mov_b64 s[2:3], 0x1fc3f800
	v_lshl_add_u64 v[140:141], v[140:141], 0, s[2:3]
	s_mov_b32 m0, s12
	ds_read_b128 v[142:145], v154
	ds_read_b128 v[146:149], v155
	ds_read_b128 v[152:155], v156
	ds_read_b128 v[170:173], v157
	ds_read_b128 v[174:177], v150
	ds_read_b128 v[178:181], v150 offset:2048
	ds_read_b128 v[182:185], v151
	ds_read_b128 v[186:189], v151 offset:2048
	ds_read_b128 v[190:193], v150 offset:4096
	ds_read_b128 v[194:197], v150 offset:6144
	ds_read_b128 v[198:201], v151 offset:4096
	ds_read_b128 v[206:209], v151 offset:6144
	v_lshl_add_u64 v[156:157], v[0:1], 1, v[140:141]
	global_load_lds_dwordx4 v[156:157], off nt
	v_lshl_add_u64 v[138:139], v[138:139], 1, v[140:141]
	s_mov_b32 m0, s11
	s_nop 0
	global_load_lds_dwordx4 v[138:139], off nt
	s_barrier
	s_waitcnt lgkmcnt(0)
	s_setprio 1
	s_waitcnt lgkmcnt(0)
	v_mfma_f32_16x16x32_bf16 v[126:129], v[142:145], v[174:177], v[126:129]
	v_mfma_f32_16x16x32_bf16 v[122:125], v[152:155], v[174:177], v[122:125]
	v_mfma_f32_16x16x32_bf16 v[118:121], v[142:145], v[178:181], v[118:121]
	v_mfma_f32_16x16x32_bf16 v[114:117], v[152:155], v[178:181], v[114:117]
	v_mfma_f32_16x16x32_bf16 v[102:105], v[142:145], v[194:197], v[102:105]
	v_mfma_f32_16x16x32_bf16 v[98:101], v[152:155], v[194:197], v[98:101]
	v_mfma_f32_16x16x32_bf16 v[126:129], v[146:149], v[182:185], v[126:129]
	v_mfma_f32_16x16x32_bf16 v[122:125], v[170:173], v[182:185], v[122:125]
	v_mfma_f32_16x16x32_bf16 v[118:121], v[146:149], v[186:189], v[118:121]
	v_mfma_f32_16x16x32_bf16 v[114:117], v[170:173], v[186:189], v[114:117]
	v_mfma_f32_16x16x32_bf16 v[110:113], v[142:145], v[190:193], v[110:113]
	v_mfma_f32_16x16x32_bf16 v[106:109], v[152:155], v[190:193], v[106:109]
	v_mfma_f32_16x16x32_bf16 v[102:105], v[146:149], v[206:209], v[102:105]
	v_mfma_f32_16x16x32_bf16 v[98:101], v[170:173], v[206:209], v[98:101]
	v_mfma_f32_16x16x32_bf16 v[138:141], v[146:149], v[198:201], v[110:113]
	v_mfma_f32_16x16x32_bf16 v[218:221], v[170:173], v[198:201], v[106:109]
	s_setprio 0
	s_barrier
	s_nop 1
	ds_read_b128 v[106:109], v158
	ds_read_b128 v[110:113], v159
	ds_read_b128 v[156:159], v160
	ds_read_b128 v[222:225], v161
	s_barrier
	s_waitcnt lgkmcnt(0)
	s_setprio 1
	s_waitcnt lgkmcnt(0)
	v_mfma_f32_16x16x32_bf16 v[86:89], v[106:109], v[178:181], v[86:89]
	v_mfma_f32_16x16x32_bf16 v[82:85], v[156:159], v[178:181], v[82:85]
	v_mfma_f32_16x16x32_bf16 v[70:73], v[106:109], v[194:197], v[70:73]
	v_mfma_f32_16x16x32_bf16 v[66:69], v[156:159], v[194:197], v[66:69]
	v_mfma_f32_16x16x32_bf16 v[94:97], v[106:109], v[174:177], v[94:97]
	v_mfma_f32_16x16x32_bf16 v[90:93], v[156:159], v[174:177], v[90:93]
	v_mfma_f32_16x16x32_bf16 v[86:89], v[110:113], v[186:189], v[86:89]
	v_mfma_f32_16x16x32_bf16 v[82:85], v[222:225], v[186:189], v[82:85]
	v_mfma_f32_16x16x32_bf16 v[78:81], v[106:109], v[190:193], v[78:81]
	v_mfma_f32_16x16x32_bf16 v[74:77], v[156:159], v[190:193], v[74:77]
	v_mfma_f32_16x16x32_bf16 v[70:73], v[110:113], v[206:209], v[70:73]
	v_mfma_f32_16x16x32_bf16 v[66:69], v[222:225], v[206:209], v[66:69]
	v_mfma_f32_16x16x32_bf16 v[226:229], v[110:113], v[182:185], v[94:97]
	v_mfma_f32_16x16x32_bf16 v[174:177], v[222:225], v[182:185], v[90:93]
	v_mfma_f32_16x16x32_bf16 v[178:181], v[110:113], v[198:201], v[78:81]
	v_mfma_f32_16x16x32_bf16 v[182:185], v[222:225], v[198:201], v[74:77]
	s_setprio 0
	s_barrier
	s_nop 0
	ds_read_b128 v[74:77], v150 offset:16384
	ds_read_b128 v[78:81], v150 offset:18432
	ds_read_b128 v[90:93], v151 offset:16384
	ds_read_b128 v[94:97], v151 offset:18432
	ds_read_b128 v[186:189], v150 offset:20480
	ds_read_b128 v[190:193], v150 offset:22528
	ds_read_b128 v[194:197], v151 offset:20480
	ds_read_b128 v[198:201], v151 offset:22528
	s_waitcnt vmcnt(4)
	s_barrier
	s_waitcnt lgkmcnt(0)
	s_setprio 1
	s_waitcnt lgkmcnt(0)
	v_mfma_f32_16x16x32_bf16 v[62:65], v[142:145], v[74:77], v[62:65]
	v_mfma_f32_16x16x32_bf16 v[58:61], v[152:155], v[74:77], v[58:61]
	v_mfma_f32_16x16x32_bf16 v[54:57], v[142:145], v[78:81], v[54:57]
	v_mfma_f32_16x16x32_bf16 v[50:53], v[152:155], v[78:81], v[50:53]
	v_mfma_f32_16x16x32_bf16 v[38:41], v[142:145], v[190:193], v[38:41]
	v_mfma_f32_16x16x32_bf16 v[34:37], v[152:155], v[190:193], v[34:37]
	v_mfma_f32_16x16x32_bf16 v[62:65], v[146:149], v[90:93], v[62:65]
	v_mfma_f32_16x16x32_bf16 v[58:61], v[170:173], v[90:93], v[58:61]
	v_mfma_f32_16x16x32_bf16 v[54:57], v[146:149], v[94:97], v[54:57]
	v_mfma_f32_16x16x32_bf16 v[50:53], v[170:173], v[94:97], v[50:53]
	v_mfma_f32_16x16x32_bf16 v[46:49], v[142:145], v[186:189], v[46:49]
	v_mfma_f32_16x16x32_bf16 v[42:45], v[152:155], v[186:189], v[42:45]
	v_mfma_f32_16x16x32_bf16 v[38:41], v[146:149], v[198:201], v[38:41]
	v_mfma_f32_16x16x32_bf16 v[34:37], v[170:173], v[198:201], v[34:37]
	v_mfma_f32_16x16x32_bf16 v[206:209], v[146:149], v[194:197], v[46:49]
	v_mfma_f32_16x16x32_bf16 v[230:233], v[170:173], v[194:197], v[42:45]
	s_setprio 0
	s_setprio 1
	v_mfma_f32_16x16x32_bf16 v[22:25], v[106:109], v[78:81], v[22:25]
	v_mfma_f32_16x16x32_bf16 v[18:21], v[156:159], v[78:81], v[18:21]
	v_mfma_f32_16x16x32_bf16 v[6:9], v[106:109], v[190:193], v[6:9]
	v_mfma_f32_16x16x32_bf16 v[2:5], v[156:159], v[190:193], v[2:5]
	v_mfma_f32_16x16x32_bf16 v[30:33], v[106:109], v[74:77], v[30:33]
	v_mfma_f32_16x16x32_bf16 v[26:29], v[156:159], v[74:77], v[26:29]
	v_mfma_f32_16x16x32_bf16 v[22:25], v[110:113], v[94:97], v[22:25]
	v_mfma_f32_16x16x32_bf16 v[18:21], v[222:225], v[94:97], v[18:21]
	v_mfma_f32_16x16x32_bf16 v[14:17], v[106:109], v[186:189], v[14:17]
	v_mfma_f32_16x16x32_bf16 v[10:13], v[156:159], v[186:189], v[10:13]
	v_mfma_f32_16x16x32_bf16 v[6:9], v[110:113], v[198:201], v[6:9]
	v_mfma_f32_16x16x32_bf16 v[2:5], v[222:225], v[198:201], v[2:5]
	v_mfma_f32_16x16x32_bf16 v[142:145], v[110:113], v[90:93], v[30:33]
	v_mfma_f32_16x16x32_bf16 v[146:149], v[222:225], v[90:93], v[26:29]
	v_mfma_f32_16x16x32_bf16 v[152:155], v[110:113], v[194:197], v[14:17]
	v_mfma_f32_16x16x32_bf16 v[170:173], v[222:225], v[194:197], v[10:13]
	s_setprio 0
	s_barrier
	s_nop 0
	ds_read_b128 v[10:13], v162
	ds_read_b128 v[14:17], v163
	ds_read_b128 v[156:159], v164
	ds_read_b128 v[160:163], v165
	ds_read_b128 v[26:29], v150 offset:32768
	ds_read_b128 v[30:33], v150 offset:34816
	ds_read_b128 v[42:45], v151 offset:32768
	ds_read_b128 v[46:49], v151 offset:34816
	ds_read_b128 v[186:189], v150 offset:36864
	ds_read_b128 v[190:193], v150 offset:38912
	ds_read_b128 v[194:197], v151 offset:36864
	ds_read_b128 v[198:201], v151 offset:38912
	s_waitcnt vmcnt(2)
	s_barrier
	s_waitcnt lgkmcnt(0)
	s_setprio 1
	s_waitcnt lgkmcnt(0)
	v_mfma_f32_16x16x32_bf16 v[74:77], v[10:13], v[26:29], v[126:129]
	v_mfma_f32_16x16x32_bf16 v[126:129], v[14:17], v[42:45], v[74:77]
	v_mfma_f32_16x16x32_bf16 v[74:77], v[156:159], v[26:29], v[122:125]
	v_mfma_f32_16x16x32_bf16 v[122:125], v[160:163], v[42:45], v[74:77]
	v_mfma_f32_16x16x32_bf16 v[74:77], v[10:13], v[30:33], v[118:121]
	v_mfma_f32_16x16x32_bf16 v[110:113], v[14:17], v[46:49], v[74:77]
	v_mfma_f32_16x16x32_bf16 v[74:77], v[156:159], v[30:33], v[114:117]
	v_mfma_f32_16x16x32_bf16 v[106:109], v[160:163], v[46:49], v[74:77]
	v_mfma_f32_16x16x32_bf16 v[74:77], v[10:13], v[186:189], v[138:141]
	v_mfma_f32_16x16x32_bf16 v[94:97], v[14:17], v[194:197], v[74:77]
	v_mfma_f32_16x16x32_bf16 v[74:77], v[156:159], v[186:189], v[218:221]
	v_mfma_f32_16x16x32_bf16 v[90:93], v[160:163], v[194:197], v[74:77]
	v_mfma_f32_16x16x32_bf16 v[74:77], v[10:13], v[190:193], v[102:105]
	v_mfma_f32_16x16x32_bf16 v[78:81], v[14:17], v[198:201], v[74:77]
	v_mfma_f32_16x16x32_bf16 v[74:77], v[156:159], v[190:193], v[98:101]
	v_mfma_f32_16x16x32_bf16 v[74:77], v[160:163], v[198:201], v[74:77]
	s_setprio 0
	s_barrier
	ds_read_b128 v[138:141], v166
	ds_read_b128 v[164:167], v167
	ds_read_b128 v[218:221], v168
	ds_read_b128 v[222:225], v169
	s_waitcnt vmcnt(0)
	s_barrier
	s_waitcnt lgkmcnt(0)
	s_setprio 1
	s_waitcnt lgkmcnt(0)
	v_mfma_f32_16x16x32_bf16 v[98:101], v[138:141], v[26:29], v[226:229]
	v_mfma_f32_16x16x32_bf16 v[26:29], v[218:221], v[26:29], v[174:177]
	v_mfma_f32_16x16x32_bf16 v[114:117], v[222:225], v[42:45], v[26:29]
	v_mfma_f32_16x16x32_bf16 v[26:29], v[138:141], v[30:33], v[86:89]
	v_mfma_f32_16x16x32_bf16 v[102:105], v[164:167], v[46:49], v[26:29]
	v_mfma_f32_16x16x32_bf16 v[26:29], v[218:221], v[30:33], v[82:85]
	v_mfma_f32_16x16x32_bf16 v[118:121], v[164:167], v[42:45], v[98:101]
	v_mfma_f32_16x16x32_bf16 v[98:101], v[222:225], v[46:49], v[26:29]
	v_mfma_f32_16x16x32_bf16 v[26:29], v[138:141], v[186:189], v[178:181]
	v_mfma_f32_16x16x32_bf16 v[86:89], v[164:167], v[194:197], v[26:29]
	v_mfma_f32_16x16x32_bf16 v[26:29], v[218:221], v[186:189], v[182:185]
	v_mfma_f32_16x16x32_bf16 v[82:85], v[222:225], v[194:197], v[26:29]
	v_mfma_f32_16x16x32_bf16 v[26:29], v[138:141], v[190:193], v[70:73]
	v_mfma_f32_16x16x32_bf16 v[70:73], v[164:167], v[198:201], v[26:29]
	v_mfma_f32_16x16x32_bf16 v[26:29], v[218:221], v[190:193], v[66:69]
	v_mfma_f32_16x16x32_bf16 v[66:69], v[222:225], v[198:201], v[26:29]
	s_setprio 0
	s_barrier
	ds_read_b128 v[174:177], v150 offset:49152
	ds_read_b128 v[178:181], v150 offset:51200
	ds_read_b128 v[182:185], v151 offset:49152
	ds_read_b128 v[186:189], v151 offset:51200
	ds_read_b128 v[190:193], v150 offset:53248
	ds_read_b128 v[194:197], v150 offset:55296
	ds_read_b128 v[198:201], v151 offset:53248
	ds_read_b128 v[226:229], v151 offset:55296
	s_barrier
	s_waitcnt lgkmcnt(0)
	s_setprio 1
	s_waitcnt lgkmcnt(0)
	v_mfma_f32_16x16x32_bf16 v[26:29], v[10:13], v[174:177], v[62:65]
	v_mfma_f32_16x16x32_bf16 v[62:65], v[14:17], v[182:185], v[26:29]
	v_mfma_f32_16x16x32_bf16 v[26:29], v[156:159], v[174:177], v[58:61]
	v_mfma_f32_16x16x32_bf16 v[58:61], v[160:163], v[182:185], v[26:29]
	v_mfma_f32_16x16x32_bf16 v[26:29], v[10:13], v[178:181], v[54:57]
	v_mfma_f32_16x16x32_bf16 v[46:49], v[14:17], v[186:189], v[26:29]
	v_mfma_f32_16x16x32_bf16 v[26:29], v[156:159], v[178:181], v[50:53]
	v_mfma_f32_16x16x32_bf16 v[42:45], v[160:163], v[186:189], v[26:29]
	v_mfma_f32_16x16x32_bf16 v[26:29], v[10:13], v[190:193], v[206:209]
	v_mfma_f32_16x16x32_bf16 v[10:13], v[10:13], v[194:197], v[38:41]
	v_mfma_f32_16x16x32_bf16 v[30:33], v[14:17], v[198:201], v[26:29]
	v_mfma_f32_16x16x32_bf16 v[26:29], v[156:159], v[190:193], v[230:233]
	v_mfma_f32_16x16x32_bf16 v[14:17], v[14:17], v[226:229], v[10:13]
	v_mfma_f32_16x16x32_bf16 v[10:13], v[156:159], v[194:197], v[34:37]
	v_mfma_f32_16x16x32_bf16 v[26:29], v[160:163], v[198:201], v[26:29]
	v_mfma_f32_16x16x32_bf16 v[10:13], v[160:163], v[226:229], v[10:13]
	s_setprio 0
	s_setprio 1
	v_mfma_f32_16x16x32_bf16 v[34:37], v[138:141], v[174:177], v[142:145]
	v_mfma_f32_16x16x32_bf16 v[54:57], v[164:167], v[182:185], v[34:37]
	v_mfma_f32_16x16x32_bf16 v[34:37], v[218:221], v[174:177], v[146:149]
	v_mfma_f32_16x16x32_bf16 v[18:21], v[218:221], v[178:181], v[18:21]
	v_mfma_f32_16x16x32_bf16 v[50:53], v[222:225], v[182:185], v[34:37]
	v_mfma_f32_16x16x32_bf16 v[22:25], v[138:141], v[178:181], v[22:25]
	v_mfma_f32_16x16x32_bf16 v[34:37], v[222:225], v[186:189], v[18:21]
	v_mfma_f32_16x16x32_bf16 v[18:21], v[138:141], v[190:193], v[152:155]
	v_mfma_f32_16x16x32_bf16 v[38:41], v[164:167], v[186:189], v[22:25]
	v_mfma_f32_16x16x32_bf16 v[22:25], v[164:167], v[198:201], v[18:21]
	v_mfma_f32_16x16x32_bf16 v[18:21], v[218:221], v[190:193], v[170:173]
	v_mfma_f32_16x16x32_bf16 v[6:9], v[138:141], v[194:197], v[6:9]
	v_mfma_f32_16x16x32_bf16 v[2:5], v[218:221], v[194:197], v[2:5]
	v_mfma_f32_16x16x32_bf16 v[18:21], v[222:225], v[198:201], v[18:21]
	v_mfma_f32_16x16x32_bf16 v[6:9], v[164:167], v[226:229], v[6:9]
	v_mfma_f32_16x16x32_bf16 v[2:5], v[222:225], v[226:229], v[2:5]
	s_setprio 0
	s_cmpk_gt_u32 s0, 0xff
	s_barrier
	s_cbranch_scc1 .LBB0_668
	s_barrier
